# GEMM K loops: first load segment issues its two LDS-DMA loads before the next-tile pointer-select SALU chain
# baseline (speedup 1.0000x reference)
; #define PG8_STAGE(bufoff, gbase, voff) do { _Pragma("unroll") for (int _i = 0; _i < 2; ++_i) \
;         __builtin_amdgcn_global_load_lds((const unsigned*)((const char*)(gbase) + (voff)[_i]), (PG8_LAS unsigned*)(lds + (bufoff) + ldsw + _i * 8192), 16, 0, 0); } while (0)
; #define PG8_LDA(dst, b, h) do { _Pragma("unroll") for (int m = 0; m < 4; ++m) _Pragma("unroll") for (int k = 0; k < 2; ++k) dst[m][k] = *(const PG8_LAS bf16x8*)(lds + PG8_SA(b, h) + aoff + m * 2048 + k * 1024); } while (0)
; #define PG8_LDB(dst, b, h) do { _Pragma("unroll") for (int n = 0; n < 2; ++n) _Pragma("unroll") for (int k = 0; k < 2; ++k) dst[n][k] = *(const PG8_LAS bf16x8*)(lds + PG8_SB(b, h) + boff + n * 2048 + k * 1024); } while (0)
; #define PG8_MMA(ai, bj, At, Bt) do { __builtin_amdgcn_s_setprio(1); _Pragma("unroll") for (int m = 0; m < 4; ++m) _Pragma("unroll") for (int n = 0; n < 2; ++n) _Pragma("unroll") for (int k = 0; k < 2; ++k) \
;         acc[ai][bj][m][n] = __builtin_amdgcn_mfma_f32_16x16x32_bf16(Bt[n][k], At[m][k], acc[ai][bj][m][n], 0, 0, 0); __builtin_amdgcn_s_setprio(0); } while (0)
; #define PG8_WAIT_V(n) asm volatile("s_waitcnt vmcnt(" #n ")" ::: "memory")
; #define PG8_WAIT_L(n) asm volatile("s_waitcnt lgkmcnt(" #n ")" ::: "memory")
; template <class Epi, class Sched, bool ALIGN_EPI = false, bool SP2 = false>
; __device__ __forceinline__ void gemm_phase(PG8_LAS unsigned char* lds, const Gemm g, const Sched& S, const Epi& E) {
;     ...
;             const bool last = (t == nt - 2);
;             const char* a1 = cA + (size_t)(t + 1) * kstep;
;             const char* a2 = last ? nA : cA + (size_t)(t + 2) * kstep; const char* b2 = last ? nB : cB + (size_t)(t + 2) * kstep;
;             const char* a3 = a2 + kstep; const char* b3 = b2 + kstep;
;             if (last && has_next) S.a_ready(nxt);
;             if constexpr (SP2) {
;             PG8_LDB(B0, 0, 0); PG8_LDB(B1, 0, 1); PG8_SCHED; PG8_LDA(At, 0, 0); PG8_STAGE(PG8_SA(1, 1), a1 + hstep, voffA);
;             PG8_WAIT_V(8); PG8_WAIT_L(0); PG8_BAR; PG8_MMA(0, 0, At, B0); PG8_MMA(0, 1, At, B1); PG8_BAR; PG8_SCHED;
;             PG8_LDA(At, 0, 1); PG8_STAGE(PG8_SB(0, 0), b2, voffB); PG8_STAGE(PG8_SB(0, 1), b2 + hstep, voffB); PG8_STAGE(PG8_SA(0, 0), a2, voffA);
;             PG8_WAIT_V(8); PG8_WAIT_L(0); PG8_BAR; PG8_MMA(1, 0, At, B0); PG8_MMA(1, 1, At, B1); PG8_BAR; PG8_SCHED;
.LBB0_427:
	v_lshl_add_u64 v[160:161], s[8:9], 0, v[140:141]
	s_add_i32 m0, s63, 0xc000
	ds_read_b128 v[152:155], v162
	global_load_lds_dwordx4 v[160:161], off
	v_lshl_add_u64 v[160:161], s[8:9], 0, v[142:143]
	s_add_i32 m0, s63, 0xe000
	ds_read_b128 v[156:159], v162 offset:1024
	global_load_lds_dwordx4 v[160:161], off
	s_add_u32 s28, s8, 0xfffc0080
	s_addc_u32 s29, s9, -1
	s_cmp_eq_u32 s39, 12
	s_cselect_b32 s37, s5, s29
	s_cselect_b32 s36, s7, s28
	s_cselect_b32 s29, s12, s38
	s_cselect_b32 s28, s21, s23
	ds_read_b128 v[166:169], v162 offset:2048
	ds_read_b128 v[170:173], v162 offset:3072
	ds_read_b128 v[174:177], v163
	ds_read_b128 v[178:181], v163 offset:1024
	ds_read_b128 v[182:185], v163 offset:2048
	ds_read_b128 v[186:189], v163 offset:3072
	ds_read_b128 v[190:193], v164
	ds_read_b128 v[194:197], v164 offset:1024
	ds_read_b128 v[198:201], v164 offset:2048
	ds_read_b128 v[202:205], v164 offset:3072
	ds_read_b128 v[206:209], v164 offset:4096
	ds_read_b128 v[210:213], v164 offset:5120
	ds_read_b128 v[214:217], v164 offset:6144
	ds_read_b128 v[218:221], v164 offset:7168
	s_waitcnt vmcnt(8)
	s_waitcnt lgkmcnt(0)
	s_barrier
	s_setprio 1
	s_waitcnt lgkmcnt(0)
	v_mfma_f32_16x16x32_bf16 v[124:127], v[152:155], v[190:193], v[124:127]
	v_mfma_f32_16x16x32_bf16 v[120:123], v[166:169], v[190:193], v[120:123]
	v_mfma_f32_16x16x32_bf16 v[108:111], v[152:155], v[198:201], v[108:111]
	v_mfma_f32_16x16x32_bf16 v[104:107], v[166:169], v[198:201], v[104:107]
	v_mfma_f32_16x16x32_bf16 v[92:95], v[152:155], v[206:209], v[92:95]
	v_mfma_f32_16x16x32_bf16 v[88:91], v[166:169], v[206:209], v[88:91]
	v_mfma_f32_16x16x32_bf16 v[76:79], v[152:155], v[214:217], v[76:79]
	v_mfma_f32_16x16x32_bf16 v[72:75], v[166:169], v[214:217], v[72:75]
	v_mfma_f32_16x16x32_bf16 v[124:127], v[156:159], v[194:197], v[124:127]
	v_mfma_f32_16x16x32_bf16 v[120:123], v[170:173], v[194:197], v[120:123]
	v_mfma_f32_16x16x32_bf16 v[108:111], v[156:159], v[202:205], v[108:111]
	v_mfma_f32_16x16x32_bf16 v[104:107], v[170:173], v[202:205], v[104:107]
	v_mfma_f32_16x16x32_bf16 v[92:95], v[156:159], v[210:213], v[92:95]
	v_mfma_f32_16x16x32_bf16 v[88:91], v[170:173], v[210:213], v[88:91]
	v_mfma_f32_16x16x32_bf16 v[76:79], v[156:159], v[218:221], v[76:79]
	v_mfma_f32_16x16x32_bf16 v[72:75], v[170:173], v[218:221], v[72:75]
	s_setprio 0
	s_setprio 1
	v_mfma_f32_16x16x32_bf16 v[116:119], v[174:177], v[190:193], v[116:119]
	v_mfma_f32_16x16x32_bf16 v[112:115], v[182:185], v[190:193], v[112:115]
	v_mfma_f32_16x16x32_bf16 v[100:103], v[174:177], v[198:201], v[100:103]
	v_mfma_f32_16x16x32_bf16 v[96:99], v[182:185], v[198:201], v[96:99]
	v_mfma_f32_16x16x32_bf16 v[84:87], v[174:177], v[206:209], v[84:87]
	v_mfma_f32_16x16x32_bf16 v[80:83], v[182:185], v[206:209], v[80:83]
	v_mfma_f32_16x16x32_bf16 v[68:71], v[174:177], v[214:217], v[68:71]
	v_mfma_f32_16x16x32_bf16 v[64:67], v[182:185], v[214:217], v[64:67]
	v_mfma_f32_16x16x32_bf16 v[116:119], v[178:181], v[194:197], v[116:119]
	v_mfma_f32_16x16x32_bf16 v[112:115], v[186:189], v[194:197], v[112:115]
	v_mfma_f32_16x16x32_bf16 v[100:103], v[178:181], v[202:205], v[100:103]
	v_mfma_f32_16x16x32_bf16 v[96:99], v[186:189], v[202:205], v[96:99]
	v_mfma_f32_16x16x32_bf16 v[84:87], v[178:181], v[210:213], v[84:87]
	v_mfma_f32_16x16x32_bf16 v[80:83], v[186:189], v[210:213], v[80:83]
	v_mfma_f32_16x16x32_bf16 v[68:71], v[178:181], v[218:221], v[68:71]
	v_mfma_f32_16x16x32_bf16 v[64:67], v[186:189], v[218:221], v[64:67]
	s_setprio 0
	s_barrier
	s_add_i32 s42, s79, s62
	v_lshl_add_u64 v[160:161], s[28:29], 0, v[130:131]
	s_mov_b32 m0, s42
	v_lshl_add_u64 v[222:223], s[28:29], 0, v[134:135]
	global_load_lds_dwordx4 v[160:161], off
	s_add_i32 m0, s42, 0x2000
	s_add_u32 s42, s28, 0x40000
	s_addc_u32 s43, s29, 0
	s_add_i32 s44, s84, s62
	global_load_lds_dwordx4 v[222:223], off
	v_lshl_add_u64 v[224:225], s[42:43], 0, v[130:131]
	s_mov_b32 m0, s44
	v_lshl_add_u64 v[226:227], s[36:37], 0, v[132:133]
	global_load_lds_dwordx4 v[224:225], off
	v_lshl_add_u64 v[224:225], s[42:43], 0, v[134:135]
	s_add_i32 m0, s44, 0x2000
	ds_read_b128 v[190:193], v164 offset:16384
	global_load_lds_dwordx4 v[224:225], off
	v_lshl_add_u64 v[224:225], s[36:37], 0, v[128:129]
	s_mov_b32 m0, s63
	ds_read_b128 v[194:197], v164 offset:17408
	global_load_lds_dwordx4 v[224:225], off
	s_mov_b32 m0, s68
	ds_read_b128 v[198:201], v164 offset:18432
	global_load_lds_dwordx4 v[226:227], off
	ds_read_b128 v[202:205], v164 offset:19456
	ds_read_b128 v[206:209], v164 offset:20480
	ds_read_b128 v[210:213], v164 offset:21504
	ds_read_b128 v[214:217], v164 offset:22528
	ds_read_b128 v[218:221], v164 offset:23552
	s_waitcnt vmcnt(8)
	s_waitcnt lgkmcnt(0)
	s_barrier
; #define PG8_STAGE(bufoff, gbase, voff) do { _Pragma("unroll") for (int _i = 0; _i < 2; ++_i) \
;         __builtin_amdgcn_global_load_lds((const unsigned*)((const char*)(gbase) + (voff)[_i]), (PG8_LAS unsigned*)(lds + (bufoff) + ldsw + _i * 8192), 16, 0, 0); } while (0)
; #define PG8_LDA(dst, b, h) do { _Pragma("unroll") for (int m = 0; m < 4; ++m) _Pragma("unroll") for (int k = 0; k < 2; ++k) dst[m][k] = *(const PG8_LAS bf16x8*)(lds + PG8_SA(b, h) + aoff + m * 2048 + k * 1024); } while (0)
; #define PG8_LDB(dst, b, h) do { _Pragma("unroll") for (int n = 0; n < 2; ++n) _Pragma("unroll") for (int k = 0; k < 2; ++k) dst[n][k] = *(const PG8_LAS bf16x8*)(lds + PG8_SB(b, h) + boff + n * 2048 + k * 1024); } while (0)
; #define PG8_MMA(ai, bj, At, Bt) do { __builtin_amdgcn_s_setprio(1); _Pragma("unroll") for (int m = 0; m < 4; ++m) _Pragma("unroll") for (int n = 0; n < 2; ++n) _Pragma("unroll") for (int k = 0; k < 2; ++k) \
;         acc[ai][bj][m][n] = __builtin_amdgcn_mfma_f32_16x16x32_bf16(Bt[n][k], At[m][k], acc[ai][bj][m][n], 0, 0, 0); __builtin_amdgcn_s_setprio(0); } while (0)
; #define PG8_WAIT_V(n) asm volatile("s_waitcnt vmcnt(" #n ")" ::: "memory")
; #define PG8_WAIT_L(n) asm volatile("s_waitcnt lgkmcnt(" #n ")" ::: "memory")
; #define PG8_BAR __builtin_amdgcn_s_barrier()
; #define PG8_SCHED __builtin_amdgcn_sched_barrier(0)
; template <class Epi, class Sched, bool ALIGN_EPI = false, bool SP2 = false>
; __device__ __forceinline__ void gemm_phase(PG8_LAS unsigned char* lds, const Gemm g, const Sched& S, const Epi& E) {
;     ...
;             PG8_WAIT_V(8); PG8_WAIT_L(0); PG8_BAR; PG8_MMA(1, 0, At, B0); PG8_MMA(1, 1, At, B1); PG8_BAR; PG8_SCHED;
;             PG8_LDB(B0, 1, 0); PG8_LDB(B1, 1, 1); PG8_SCHED; PG8_LDA(At, 1, 0); PG8_STAGE(PG8_SA(0, 1), a2 + hstep, voffA);
;             PG8_WAIT_V(8); PG8_WAIT_L(0); PG8_BAR; PG8_MMA(0, 0, At, B0); PG8_MMA(0, 1, At, B1); PG8_BAR; PG8_SCHED;
	s_setprio 1
	s_waitcnt lgkmcnt(0)
	v_mfma_f32_16x16x32_bf16 v[60:63], v[152:155], v[190:193], v[60:63]
	v_mfma_f32_16x16x32_bf16 v[56:59], v[166:169], v[190:193], v[56:59]
	v_mfma_f32_16x16x32_bf16 v[44:47], v[152:155], v[198:201], v[44:47]
	v_mfma_f32_16x16x32_bf16 v[40:43], v[166:169], v[198:201], v[40:43]
	v_mfma_f32_16x16x32_bf16 v[28:31], v[152:155], v[206:209], v[28:31]
	v_mfma_f32_16x16x32_bf16 v[24:27], v[166:169], v[206:209], v[24:27]
	v_mfma_f32_16x16x32_bf16 v[12:15], v[152:155], v[214:217], v[12:15]
	v_mfma_f32_16x16x32_bf16 v[8:11], v[166:169], v[214:217], v[8:11]
	v_mfma_f32_16x16x32_bf16 v[60:63], v[156:159], v[194:197], v[60:63]
	v_mfma_f32_16x16x32_bf16 v[56:59], v[170:173], v[194:197], v[56:59]
	v_mfma_f32_16x16x32_bf16 v[44:47], v[156:159], v[202:205], v[44:47]
	v_mfma_f32_16x16x32_bf16 v[40:43], v[170:173], v[202:205], v[40:43]
	v_mfma_f32_16x16x32_bf16 v[28:31], v[156:159], v[210:213], v[28:31]
	v_mfma_f32_16x16x32_bf16 v[24:27], v[170:173], v[210:213], v[24:27]
	v_mfma_f32_16x16x32_bf16 v[12:15], v[156:159], v[218:221], v[12:15]
	v_mfma_f32_16x16x32_bf16 v[8:11], v[170:173], v[218:221], v[8:11]
	s_setprio 0
	s_setprio 1
	v_mfma_f32_16x16x32_bf16 v[52:55], v[174:177], v[190:193], v[52:55]
	v_mfma_f32_16x16x32_bf16 v[48:51], v[182:185], v[190:193], v[48:51]
	v_mfma_f32_16x16x32_bf16 v[36:39], v[174:177], v[198:201], v[36:39]
	v_mfma_f32_16x16x32_bf16 v[32:35], v[182:185], v[198:201], v[32:35]
	v_mfma_f32_16x16x32_bf16 v[20:23], v[174:177], v[206:209], v[20:23]
	v_mfma_f32_16x16x32_bf16 v[16:19], v[182:185], v[206:209], v[16:19]
	v_mfma_f32_16x16x32_bf16 v[4:7], v[174:177], v[214:217], v[4:7]
	v_mfma_f32_16x16x32_bf16 v[0:3], v[182:185], v[214:217], v[0:3]
	v_mfma_f32_16x16x32_bf16 v[52:55], v[178:181], v[194:197], v[52:55]
	v_mfma_f32_16x16x32_bf16 v[48:51], v[186:189], v[194:197], v[48:51]
	v_mfma_f32_16x16x32_bf16 v[36:39], v[178:181], v[202:205], v[36:39]
	v_mfma_f32_16x16x32_bf16 v[32:35], v[186:189], v[202:205], v[32:35]
	v_mfma_f32_16x16x32_bf16 v[20:23], v[178:181], v[210:213], v[20:23]
	v_mfma_f32_16x16x32_bf16 v[16:19], v[186:189], v[210:213], v[16:19]
	v_mfma_f32_16x16x32_bf16 v[4:7], v[178:181], v[218:221], v[4:7]
	v_mfma_f32_16x16x32_bf16 v[0:3], v[186:189], v[218:221], v[0:3]
	s_setprio 0
	s_barrier
	s_add_i32 s42, 0, 0x18000
	s_add_i32 s43, 0, 0x1c000
	s_add_u32 s36, s36, 0x40000
	s_addc_u32 s37, s37, 0
	s_mov_b32 m0, s50
	v_lshl_add_u64 v[228:229], s[36:37], 0, v[128:129]
	global_load_lds_dwordx4 v[228:229], off
	v_lshl_add_u64 v[228:229], s[36:37], 0, v[132:133]
	s_mov_b32 m0, s51
	v_add_u32_e32 v136, s42, v149
	global_load_lds_dwordx4 v[228:229], off
	ds_read_b128 v[152:155], v136
	ds_read_b128 v[156:159], v136 offset:1024
	ds_read_b128 v[166:169], v136 offset:2048
	ds_read_b128 v[170:173], v136 offset:3072
	v_add_u32_e32 v136, s43, v149
	ds_read_b128 v[174:177], v136
	ds_read_b128 v[178:181], v136 offset:1024
	ds_read_b128 v[182:185], v136 offset:2048
	ds_read_b128 v[186:189], v136 offset:3072
	ds_read_b128 v[190:193], v164 offset:32768
	ds_read_b128 v[194:197], v164 offset:33792
	ds_read_b128 v[198:201], v164 offset:34816
	ds_read_b128 v[202:205], v164 offset:35840
	ds_read_b128 v[206:209], v164 offset:36864
	ds_read_b128 v[210:213], v164 offset:37888
	ds_read_b128 v[214:217], v164 offset:38912
	ds_read_b128 v[218:221], v164 offset:39936
	s_waitcnt vmcnt(8)
	s_waitcnt lgkmcnt(0)
	s_barrier
	s_setprio 1
	s_waitcnt lgkmcnt(0)
	v_mfma_f32_16x16x32_bf16 v[124:127], v[152:155], v[190:193], v[124:127]
	v_mfma_f32_16x16x32_bf16 v[120:123], v[166:169], v[190:193], v[120:123]
	v_mfma_f32_16x16x32_bf16 v[108:111], v[152:155], v[198:201], v[108:111]
	v_mfma_f32_16x16x32_bf16 v[104:107], v[166:169], v[198:201], v[104:107]
	v_mfma_f32_16x16x32_bf16 v[92:95], v[152:155], v[206:209], v[92:95]
	v_mfma_f32_16x16x32_bf16 v[88:91], v[166:169], v[206:209], v[88:91]
	v_mfma_f32_16x16x32_bf16 v[76:79], v[152:155], v[214:217], v[76:79]
	v_mfma_f32_16x16x32_bf16 v[72:75], v[166:169], v[214:217], v[72:75]
	v_mfma_f32_16x16x32_bf16 v[124:127], v[156:159], v[194:197], v[124:127]
	v_mfma_f32_16x16x32_bf16 v[120:123], v[170:173], v[194:197], v[120:123]
	v_mfma_f32_16x16x32_bf16 v[108:111], v[156:159], v[202:205], v[108:111]
	v_mfma_f32_16x16x32_bf16 v[104:107], v[170:173], v[202:205], v[104:107]
	v_mfma_f32_16x16x32_bf16 v[92:95], v[156:159], v[210:213], v[92:95]
	v_mfma_f32_16x16x32_bf16 v[88:91], v[170:173], v[210:213], v[88:91]
	v_mfma_f32_16x16x32_bf16 v[76:79], v[156:159], v[218:221], v[76:79]
	v_mfma_f32_16x16x32_bf16 v[72:75], v[170:173], v[218:221], v[72:75]
	s_setprio 0
	s_setprio 1
	v_mfma_f32_16x16x32_bf16 v[116:119], v[174:177], v[190:193], v[116:119]
	v_mfma_f32_16x16x32_bf16 v[112:115], v[182:185], v[190:193], v[112:115]
	v_mfma_f32_16x16x32_bf16 v[100:103], v[174:177], v[198:201], v[100:103]
	v_mfma_f32_16x16x32_bf16 v[96:99], v[182:185], v[198:201], v[96:99]
	v_mfma_f32_16x16x32_bf16 v[84:87], v[174:177], v[206:209], v[84:87]
	v_mfma_f32_16x16x32_bf16 v[80:83], v[182:185], v[206:209], v[80:83]
	v_mfma_f32_16x16x32_bf16 v[68:71], v[174:177], v[214:217], v[68:71]
	v_mfma_f32_16x16x32_bf16 v[64:67], v[182:185], v[214:217], v[64:67]
	v_mfma_f32_16x16x32_bf16 v[116:119], v[178:181], v[194:197], v[116:119]
	v_mfma_f32_16x16x32_bf16 v[112:115], v[186:189], v[194:197], v[112:115]
	v_mfma_f32_16x16x32_bf16 v[100:103], v[178:181], v[202:205], v[100:103]
	v_mfma_f32_16x16x32_bf16 v[96:99], v[186:189], v[202:205], v[96:99]
	v_mfma_f32_16x16x32_bf16 v[84:87], v[178:181], v[210:213], v[84:87]
	v_mfma_f32_16x16x32_bf16 v[80:83], v[186:189], v[210:213], v[80:83]
	v_mfma_f32_16x16x32_bf16 v[68:71], v[178:181], v[218:221], v[68:71]
	v_mfma_f32_16x16x32_bf16 v[64:67], v[186:189], v[218:221], v[64:67]
	s_setprio 0
	s_barrier
; #define PG8_STAGE(bufoff, gbase, voff) do { _Pragma("unroll") for (int _i = 0; _i < 2; ++_i) \
;         __builtin_amdgcn_global_load_lds((const unsigned*)((const char*)(gbase) + (voff)[_i]), (PG8_LAS unsigned*)(lds + (bufoff) + ldsw + _i * 8192), 16, 0, 0); } while (0)
; #define PG8_LDA(dst, b, h) do { _Pragma("unroll") for (int m = 0; m < 4; ++m) _Pragma("unroll") for (int k = 0; k < 2; ++k) dst[m][k] = *(const PG8_LAS bf16x8*)(lds + PG8_SA(b, h) + aoff + m * 2048 + k * 1024); } while (0)
; #define PG8_MMA(ai, bj, At, Bt) do { __builtin_amdgcn_s_setprio(1); _Pragma("unroll") for (int m = 0; m < 4; ++m) _Pragma("unroll") for (int n = 0; n < 2; ++n) _Pragma("unroll") for (int k = 0; k < 2; ++k) \
;         acc[ai][bj][m][n] = __builtin_amdgcn_mfma_f32_16x16x32_bf16(Bt[n][k], At[m][k], acc[ai][bj][m][n], 0, 0, 0); __builtin_amdgcn_s_setprio(0); } while (0)
; #define PG8_WAIT_V(n) asm volatile("s_waitcnt vmcnt(" #n ")" ::: "memory")
; #define PG8_WAIT_L(n) asm volatile("s_waitcnt lgkmcnt(" #n ")" ::: "memory")
; #define PG8_BAR __builtin_amdgcn_s_barrier()
; #define PG8_SCHED __builtin_amdgcn_sched_barrier(0)
; template <class Epi, class Sched, bool ALIGN_EPI = false, bool SP2 = false>
; __device__ __forceinline__ void gemm_phase(PG8_LAS unsigned char* lds, const Gemm g, const Sched& S, const Epi& E) {
;     ...
;             PG8_LDA(At, 1, 1); PG8_STAGE(PG8_SB(1, 0), b3, voffB); PG8_STAGE(PG8_SB(1, 1), b3 + hstep, voffB); PG8_STAGE(PG8_SA(1, 0), a3, voffA);
;             PG8_WAIT_V(8); PG8_WAIT_L(0); PG8_BAR; PG8_MMA(1, 0, At, B0); PG8_MMA(1, 1, At, B1); PG8_BAR; PG8_SCHED;
;     ...
;         if constexpr (ALIGN_EPI) { if (wr == 0) PG8_BAR; }
	s_add_i32 s36, s42, s62
	v_lshl_add_u64 v[160:161], v[160:161], 0, s[16:17]
	s_mov_b32 m0, s36
	ds_read_b128 v[190:193], v164 offset:49152
	global_load_lds_dwordx4 v[160:161], off
	s_add_i32 m0, s36, 0x2000
	s_add_u32 s28, s28, 0x40080
	v_lshl_add_u64 v[160:161], v[222:223], 0, s[16:17]
	s_addc_u32 s29, s29, 0
	s_add_i32 s36, s43, s62
	global_load_lds_dwordx4 v[160:161], off
	v_lshl_add_u64 v[160:161], s[28:29], 0, v[130:131]
	s_mov_b32 m0, s36
	ds_read_b128 v[194:197], v164 offset:50176
	global_load_lds_dwordx4 v[160:161], off
	v_lshl_add_u64 v[160:161], s[28:29], 0, v[134:135]
	s_add_i32 m0, s36, 0x2000
	ds_read_b128 v[198:201], v164 offset:51200
	global_load_lds_dwordx4 v[160:161], off
	v_lshl_add_u64 v[160:161], v[224:225], 0, s[16:17]
	s_mov_b32 m0, s69
	ds_read_b128 v[202:205], v164 offset:52224
	global_load_lds_dwordx4 v[160:161], off
	v_lshl_add_u64 v[160:161], v[226:227], 0, s[16:17]
	s_mov_b32 m0, s70
	ds_read_b128 v[206:209], v164 offset:53248
	global_load_lds_dwordx4 v[160:161], off
	ds_read_b128 v[210:213], v164 offset:54272
	ds_read_b128 v[214:217], v164 offset:55296
	ds_read_b128 v[218:221], v164 offset:56320
	s_waitcnt vmcnt(8)
	s_waitcnt lgkmcnt(0)
	s_barrier
	s_setprio 1
	s_waitcnt lgkmcnt(0)
	v_mfma_f32_16x16x32_bf16 v[60:63], v[152:155], v[190:193], v[60:63]
	v_mfma_f32_16x16x32_bf16 v[56:59], v[166:169], v[190:193], v[56:59]
	v_mfma_f32_16x16x32_bf16 v[44:47], v[152:155], v[198:201], v[44:47]
	v_mfma_f32_16x16x32_bf16 v[40:43], v[166:169], v[198:201], v[40:43]
	v_mfma_f32_16x16x32_bf16 v[28:31], v[152:155], v[206:209], v[28:31]
	v_mfma_f32_16x16x32_bf16 v[24:27], v[166:169], v[206:209], v[24:27]
	v_mfma_f32_16x16x32_bf16 v[12:15], v[152:155], v[214:217], v[12:15]
	v_mfma_f32_16x16x32_bf16 v[8:11], v[166:169], v[214:217], v[8:11]
	v_mfma_f32_16x16x32_bf16 v[60:63], v[156:159], v[194:197], v[60:63]
	v_mfma_f32_16x16x32_bf16 v[56:59], v[170:173], v[194:197], v[56:59]
	v_mfma_f32_16x16x32_bf16 v[44:47], v[156:159], v[202:205], v[44:47]
	v_mfma_f32_16x16x32_bf16 v[40:43], v[170:173], v[202:205], v[40:43]
	v_mfma_f32_16x16x32_bf16 v[28:31], v[156:159], v[210:213], v[28:31]
	v_mfma_f32_16x16x32_bf16 v[24:27], v[170:173], v[210:213], v[24:27]
	v_mfma_f32_16x16x32_bf16 v[12:15], v[156:159], v[218:221], v[12:15]
	v_mfma_f32_16x16x32_bf16 v[8:11], v[170:173], v[218:221], v[8:11]
	s_setprio 0
	s_setprio 1
	v_mfma_f32_16x16x32_bf16 v[52:55], v[174:177], v[190:193], v[52:55]
	v_mfma_f32_16x16x32_bf16 v[48:51], v[182:185], v[190:193], v[48:51]
	v_mfma_f32_16x16x32_bf16 v[36:39], v[174:177], v[198:201], v[36:39]
	v_mfma_f32_16x16x32_bf16 v[32:35], v[182:185], v[198:201], v[32:35]
	v_mfma_f32_16x16x32_bf16 v[20:23], v[174:177], v[206:209], v[20:23]
	v_mfma_f32_16x16x32_bf16 v[16:19], v[182:185], v[206:209], v[16:19]
	v_mfma_f32_16x16x32_bf16 v[4:7], v[174:177], v[214:217], v[4:7]
	v_mfma_f32_16x16x32_bf16 v[0:3], v[182:185], v[214:217], v[0:3]
	v_mfma_f32_16x16x32_bf16 v[52:55], v[178:181], v[194:197], v[52:55]
	v_mfma_f32_16x16x32_bf16 v[48:51], v[186:189], v[194:197], v[48:51]
	v_mfma_f32_16x16x32_bf16 v[36:39], v[178:181], v[202:205], v[36:39]
	v_mfma_f32_16x16x32_bf16 v[32:35], v[186:189], v[202:205], v[32:35]
	v_mfma_f32_16x16x32_bf16 v[20:23], v[178:181], v[210:213], v[20:23]
	v_mfma_f32_16x16x32_bf16 v[16:19], v[186:189], v[210:213], v[16:19]
	v_mfma_f32_16x16x32_bf16 v[4:7], v[178:181], v[218:221], v[4:7]
	v_mfma_f32_16x16x32_bf16 v[0:3], v[186:189], v[218:221], v[0:3]
	s_setprio 0
	s_barrier
	s_add_i32 s39, s39, 2
	s_add_u32 s8, s8, 0x100
	s_addc_u32 s9, s9, 0
	s_add_u32 s23, s23, 0x100
	s_addc_u32 s38, s38, 0
	s_cmp_gt_u32 s39, 13
	s_cbranch_scc0 .LBB0_427
	s_nop 0
	s_nop 0
	s_nop 0
	s_nop 0
	s_nop 0
	s_nop 0
	s_nop 0
	s_nop 0
	s_nop 0
	s_and_b64 vcc, exec, s[18:19]
	s_cbranch_vccz .LBB0_430
	s_barrier

; #define PG8_STAGE(bufoff, gbase, voff) do { _Pragma("unroll") for (int _i = 0; _i < 2; ++_i) \
;         __builtin_amdgcn_global_load_lds((const unsigned*)((const char*)(gbase) + (voff)[_i]), (PG8_LAS unsigned*)(lds + (bufoff) + ldsw + _i * 8192), 16, 0, 0); } while (0)
; #define PG8_LDA(dst, b, h) do { _Pragma("unroll") for (int m = 0; m < 4; ++m) _Pragma("unroll") for (int k = 0; k < 2; ++k) dst[m][k] = *(const PG8_LAS bf16x8*)(lds + PG8_SA(b, h) + aoff + m * 2048 + k * 1024); } while (0)
; #define PG8_LDB(dst, b, h) do { _Pragma("unroll") for (int n = 0; n < 2; ++n) _Pragma("unroll") for (int k = 0; k < 2; ++k) dst[n][k] = *(const PG8_LAS bf16x8*)(lds + PG8_SB(b, h) + boff + n * 2048 + k * 1024); } while (0)
; #define PG8_MMA(ai, bj, At, Bt) do { __builtin_amdgcn_s_setprio(1); _Pragma("unroll") for (int m = 0; m < 4; ++m) _Pragma("unroll") for (int n = 0; n < 2; ++n) _Pragma("unroll") for (int k = 0; k < 2; ++k) \
;         acc[ai][bj][m][n] = __builtin_amdgcn_mfma_f32_16x16x32_bf16(Bt[n][k], At[m][k], acc[ai][bj][m][n], 0, 0, 0); __builtin_amdgcn_s_setprio(0); } while (0)
; #define PG8_WAIT_V(n) asm volatile("s_waitcnt vmcnt(" #n ")" ::: "memory")
; #define PG8_WAIT_L(n) asm volatile("s_waitcnt lgkmcnt(" #n ")" ::: "memory")
; template <class Epi, class Sched, bool ALIGN_EPI = false, bool SP2 = false>
; __device__ __forceinline__ void gemm_phase(PG8_LAS unsigned char* lds, const Gemm g, const Sched& S, const Epi& E) {
;     ...
;             const bool last = (t == nt - 2);
;             const char* a1 = cA + (size_t)(t + 1) * kstep;
;             const char* a2 = last ? nA : cA + (size_t)(t + 2) * kstep; const char* b2 = last ? nB : cB + (size_t)(t + 2) * kstep;
;             const char* a3 = a2 + kstep; const char* b3 = b2 + kstep;
;             if (last && has_next) S.a_ready(nxt);
;             if constexpr (SP2) {
;             PG8_LDB(B0, 0, 0); PG8_LDB(B1, 0, 1); PG8_SCHED; PG8_LDA(At, 0, 0); PG8_STAGE(PG8_SA(1, 1), a1 + hstep, voffA);
;             PG8_WAIT_V(8); PG8_WAIT_L(0); PG8_BAR; PG8_MMA(0, 0, At, B0); PG8_MMA(0, 1, At, B1); PG8_BAR; PG8_SCHED;
;             PG8_LDA(At, 0, 1); PG8_STAGE(PG8_SB(0, 0), b2, voffB); PG8_STAGE(PG8_SB(0, 1), b2 + hstep, voffB); PG8_STAGE(PG8_SA(0, 0), a2, voffA);
;             PG8_WAIT_V(8); PG8_WAIT_L(0); PG8_BAR; PG8_MMA(1, 0, At, B0); PG8_MMA(1, 1, At, B1); PG8_BAR; PG8_SCHED;
.LBB0_1247:
	v_lshl_add_u64 v[154:155], s[4:5], 0, v[136:137]
	s_add_i32 m0, s40, 0xc000
	ds_read_b128 v[144:147], v163
	global_load_lds_dwordx4 v[154:155], off
	v_lshl_add_u64 v[154:155], s[4:5], 0, v[138:139]
	s_add_i32 m0, s40, 0xe000
	ds_read_b128 v[174:177], v163 offset:1024
	global_load_lds_dwordx4 v[154:155], off
	s_add_u32 s6, s4, 0xfffc0080
	s_addc_u32 s7, s5, -1
	s_cmp_eq_u32 s56, 12
	s_cselect_b32 s9, s10, s7
	s_cselect_b32 s8, s11, s6
	s_cselect_b32 s7, s27, s53
	s_cselect_b32 s6, s29, s52
	ds_read_b128 v[178:181], v163 offset:2048
	ds_read_b128 v[182:185], v163 offset:3072
	ds_read_b128 v[186:189], v170
	ds_read_b128 v[190:193], v170 offset:1024
	ds_read_b128 v[194:197], v170 offset:2048
	ds_read_b128 v[198:201], v170 offset:3072
	ds_read_b128 v[202:205], v171
	ds_read_b128 v[206:209], v171 offset:1024
	ds_read_b128 v[210:213], v171 offset:2048
	ds_read_b128 v[214:217], v171 offset:3072
	ds_read_b128 v[218:221], v171 offset:4096
	ds_read_b128 v[222:225], v171 offset:5120
	ds_read_b128 v[226:229], v171 offset:6144
	ds_read_b128 v[230:233], v171 offset:7168
	s_waitcnt vmcnt(8)
	s_waitcnt lgkmcnt(0)
	s_barrier
	s_setprio 1
	s_waitcnt lgkmcnt(0)
	v_mfma_f32_16x16x32_bf16 v[124:127], v[144:147], v[202:205], v[124:127]
	v_mfma_f32_16x16x32_bf16 v[120:123], v[178:181], v[202:205], v[120:123]
	v_mfma_f32_16x16x32_bf16 v[108:111], v[144:147], v[210:213], v[108:111]
	v_mfma_f32_16x16x32_bf16 v[104:107], v[178:181], v[210:213], v[104:107]
	v_mfma_f32_16x16x32_bf16 v[92:95], v[144:147], v[218:221], v[92:95]
	v_mfma_f32_16x16x32_bf16 v[88:91], v[178:181], v[218:221], v[88:91]
	v_mfma_f32_16x16x32_bf16 v[76:79], v[144:147], v[226:229], v[76:79]
	v_mfma_f32_16x16x32_bf16 v[72:75], v[178:181], v[226:229], v[72:75]
	v_mfma_f32_16x16x32_bf16 v[124:127], v[174:177], v[206:209], v[124:127]
	v_mfma_f32_16x16x32_bf16 v[120:123], v[182:185], v[206:209], v[120:123]
	v_mfma_f32_16x16x32_bf16 v[108:111], v[174:177], v[214:217], v[108:111]
	v_mfma_f32_16x16x32_bf16 v[104:107], v[182:185], v[214:217], v[104:107]
	v_mfma_f32_16x16x32_bf16 v[92:95], v[174:177], v[222:225], v[92:95]
	v_mfma_f32_16x16x32_bf16 v[88:91], v[182:185], v[222:225], v[88:91]
	v_mfma_f32_16x16x32_bf16 v[76:79], v[174:177], v[230:233], v[76:79]
	v_mfma_f32_16x16x32_bf16 v[72:75], v[182:185], v[230:233], v[72:75]
	s_setprio 0
	s_setprio 1
	v_mfma_f32_16x16x32_bf16 v[116:119], v[186:189], v[202:205], v[116:119]
	v_mfma_f32_16x16x32_bf16 v[112:115], v[194:197], v[202:205], v[112:115]
	v_mfma_f32_16x16x32_bf16 v[100:103], v[186:189], v[210:213], v[100:103]
	v_mfma_f32_16x16x32_bf16 v[96:99], v[194:197], v[210:213], v[96:99]
	v_mfma_f32_16x16x32_bf16 v[84:87], v[186:189], v[218:221], v[84:87]
	v_mfma_f32_16x16x32_bf16 v[80:83], v[194:197], v[218:221], v[80:83]
	v_mfma_f32_16x16x32_bf16 v[68:71], v[186:189], v[226:229], v[68:71]
	v_mfma_f32_16x16x32_bf16 v[64:67], v[194:197], v[226:229], v[64:67]
	v_mfma_f32_16x16x32_bf16 v[116:119], v[190:193], v[206:209], v[116:119]
	v_mfma_f32_16x16x32_bf16 v[112:115], v[198:201], v[206:209], v[112:115]
	v_mfma_f32_16x16x32_bf16 v[100:103], v[190:193], v[214:217], v[100:103]
	v_mfma_f32_16x16x32_bf16 v[96:99], v[198:201], v[214:217], v[96:99]
	v_mfma_f32_16x16x32_bf16 v[84:87], v[190:193], v[222:225], v[84:87]
	v_mfma_f32_16x16x32_bf16 v[80:83], v[198:201], v[222:225], v[80:83]
	v_mfma_f32_16x16x32_bf16 v[68:71], v[190:193], v[230:233], v[68:71]
	v_mfma_f32_16x16x32_bf16 v[64:67], v[198:201], v[230:233], v[64:67]
	s_setprio 0
	s_barrier
	s_add_i32 s57, s60, s39
	v_lshl_add_u64 v[154:155], s[6:7], 0, v[130:131]
	s_mov_b32 m0, s57
	v_lshl_add_u64 v[234:235], s[6:7], 0, v[134:135]
	global_load_lds_dwordx4 v[154:155], off
	s_add_i32 m0, s57, 0x2000
	s_add_u32 s70, s6, 0x40000
	s_addc_u32 s71, s7, 0
	s_add_i32 s57, s61, s39
	global_load_lds_dwordx4 v[234:235], off
	v_lshl_add_u64 v[236:237], s[70:71], 0, v[130:131]
	s_mov_b32 m0, s57
	v_lshl_add_u64 v[238:239], s[8:9], 0, v[132:133]
	global_load_lds_dwordx4 v[236:237], off
	v_lshl_add_u64 v[236:237], s[70:71], 0, v[134:135]
	s_add_i32 m0, s57, 0x2000
	ds_read_b128 v[202:205], v171 offset:16384
	global_load_lds_dwordx4 v[236:237], off
	v_lshl_add_u64 v[236:237], s[8:9], 0, v[128:129]
	s_mov_b32 m0, s40
	ds_read_b128 v[206:209], v171 offset:17408
	global_load_lds_dwordx4 v[236:237], off
	s_mov_b32 m0, s41
	ds_read_b128 v[210:213], v171 offset:18432
	global_load_lds_dwordx4 v[238:239], off
	ds_read_b128 v[214:217], v171 offset:19456
	ds_read_b128 v[218:221], v171 offset:20480
	ds_read_b128 v[222:225], v171 offset:21504
	ds_read_b128 v[226:229], v171 offset:22528
	ds_read_b128 v[230:233], v171 offset:23552
	s_waitcnt vmcnt(8)
	s_waitcnt lgkmcnt(0)
	s_barrier
; #define PG8_STAGE(bufoff, gbase, voff) do { _Pragma("unroll") for (int _i = 0; _i < 2; ++_i) \
;         __builtin_amdgcn_global_load_lds((const unsigned*)((const char*)(gbase) + (voff)[_i]), (PG8_LAS unsigned*)(lds + (bufoff) + ldsw + _i * 8192), 16, 0, 0); } while (0)
; #define PG8_LDA(dst, b, h) do { _Pragma("unroll") for (int m = 0; m < 4; ++m) _Pragma("unroll") for (int k = 0; k < 2; ++k) dst[m][k] = *(const PG8_LAS bf16x8*)(lds + PG8_SA(b, h) + aoff + m * 2048 + k * 1024); } while (0)
; #define PG8_LDB(dst, b, h) do { _Pragma("unroll") for (int n = 0; n < 2; ++n) _Pragma("unroll") for (int k = 0; k < 2; ++k) dst[n][k] = *(const PG8_LAS bf16x8*)(lds + PG8_SB(b, h) + boff + n * 2048 + k * 1024); } while (0)
; #define PG8_MMA(ai, bj, At, Bt) do { __builtin_amdgcn_s_setprio(1); _Pragma("unroll") for (int m = 0; m < 4; ++m) _Pragma("unroll") for (int n = 0; n < 2; ++n) _Pragma("unroll") for (int k = 0; k < 2; ++k) \
;         acc[ai][bj][m][n] = __builtin_amdgcn_mfma_f32_16x16x32_bf16(Bt[n][k], At[m][k], acc[ai][bj][m][n], 0, 0, 0); __builtin_amdgcn_s_setprio(0); } while (0)
; #define PG8_WAIT_V(n) asm volatile("s_waitcnt vmcnt(" #n ")" ::: "memory")
; #define PG8_WAIT_L(n) asm volatile("s_waitcnt lgkmcnt(" #n ")" ::: "memory")
; #define PG8_BAR __builtin_amdgcn_s_barrier()
; #define PG8_SCHED __builtin_amdgcn_sched_barrier(0)
; template <class Epi, class Sched, bool ALIGN_EPI = false, bool SP2 = false>
; __device__ __forceinline__ void gemm_phase(PG8_LAS unsigned char* lds, const Gemm g, const Sched& S, const Epi& E) {
;     ...
;             PG8_WAIT_V(8); PG8_WAIT_L(0); PG8_BAR; PG8_MMA(1, 0, At, B0); PG8_MMA(1, 1, At, B1); PG8_BAR; PG8_SCHED;
;             PG8_LDB(B0, 1, 0); PG8_LDB(B1, 1, 1); PG8_SCHED; PG8_LDA(At, 1, 0); PG8_STAGE(PG8_SA(0, 1), a2 + hstep, voffA);
;             PG8_WAIT_V(8); PG8_WAIT_L(0); PG8_BAR; PG8_MMA(0, 0, At, B0); PG8_MMA(0, 1, At, B1); PG8_BAR; PG8_SCHED;
	s_setprio 1
	s_waitcnt lgkmcnt(0)
	v_mfma_f32_16x16x32_bf16 v[60:63], v[144:147], v[202:205], v[60:63]
	v_mfma_f32_16x16x32_bf16 v[56:59], v[178:181], v[202:205], v[56:59]
	v_mfma_f32_16x16x32_bf16 v[44:47], v[144:147], v[210:213], v[44:47]
	v_mfma_f32_16x16x32_bf16 v[40:43], v[178:181], v[210:213], v[40:43]
	v_mfma_f32_16x16x32_bf16 v[28:31], v[144:147], v[218:221], v[28:31]
	v_mfma_f32_16x16x32_bf16 v[24:27], v[178:181], v[218:221], v[24:27]
	v_mfma_f32_16x16x32_bf16 v[12:15], v[144:147], v[226:229], v[12:15]
	v_mfma_f32_16x16x32_bf16 v[8:11], v[178:181], v[226:229], v[8:11]
	v_mfma_f32_16x16x32_bf16 v[60:63], v[174:177], v[206:209], v[60:63]
	v_mfma_f32_16x16x32_bf16 v[56:59], v[182:185], v[206:209], v[56:59]
	v_mfma_f32_16x16x32_bf16 v[44:47], v[174:177], v[214:217], v[44:47]
	v_mfma_f32_16x16x32_bf16 v[40:43], v[182:185], v[214:217], v[40:43]
	v_mfma_f32_16x16x32_bf16 v[28:31], v[174:177], v[222:225], v[28:31]
	v_mfma_f32_16x16x32_bf16 v[24:27], v[182:185], v[222:225], v[24:27]
	v_mfma_f32_16x16x32_bf16 v[12:15], v[174:177], v[230:233], v[12:15]
	v_mfma_f32_16x16x32_bf16 v[8:11], v[182:185], v[230:233], v[8:11]
	s_setprio 0
	s_setprio 1
	v_mfma_f32_16x16x32_bf16 v[52:55], v[186:189], v[202:205], v[52:55]
	v_mfma_f32_16x16x32_bf16 v[48:51], v[194:197], v[202:205], v[48:51]
	v_mfma_f32_16x16x32_bf16 v[36:39], v[186:189], v[210:213], v[36:39]
	v_mfma_f32_16x16x32_bf16 v[32:35], v[194:197], v[210:213], v[32:35]
	v_mfma_f32_16x16x32_bf16 v[20:23], v[186:189], v[218:221], v[20:23]
	v_mfma_f32_16x16x32_bf16 v[16:19], v[194:197], v[218:221], v[16:19]
	v_mfma_f32_16x16x32_bf16 v[4:7], v[186:189], v[226:229], v[4:7]
	v_mfma_f32_16x16x32_bf16 v[0:3], v[194:197], v[226:229], v[0:3]
	v_mfma_f32_16x16x32_bf16 v[52:55], v[190:193], v[206:209], v[52:55]
	v_mfma_f32_16x16x32_bf16 v[48:51], v[198:201], v[206:209], v[48:51]
	v_mfma_f32_16x16x32_bf16 v[36:39], v[190:193], v[214:217], v[36:39]
	v_mfma_f32_16x16x32_bf16 v[32:35], v[198:201], v[214:217], v[32:35]
	v_mfma_f32_16x16x32_bf16 v[20:23], v[190:193], v[222:225], v[20:23]
	v_mfma_f32_16x16x32_bf16 v[16:19], v[198:201], v[222:225], v[16:19]
	v_mfma_f32_16x16x32_bf16 v[4:7], v[190:193], v[230:233], v[4:7]
	v_mfma_f32_16x16x32_bf16 v[0:3], v[198:201], v[230:233], v[0:3]
	s_setprio 0
	s_barrier
	s_add_i32 s57, 0, 0x18000
	s_add_i32 s69, 0, 0x1c000
	s_add_u32 s8, s8, 0x40000
	s_addc_u32 s9, s9, 0
	s_mov_b32 m0, s42
	v_lshl_add_u64 v[240:241], s[8:9], 0, v[128:129]
	global_load_lds_dwordx4 v[240:241], off
	v_lshl_add_u64 v[240:241], s[8:9], 0, v[132:133]
	s_mov_b32 m0, s43
	v_add_u32_e32 v152, s57, v161
	global_load_lds_dwordx4 v[240:241], off
	ds_read_b128 v[144:147], v152
	ds_read_b128 v[174:177], v152 offset:1024
	ds_read_b128 v[178:181], v152 offset:2048
	ds_read_b128 v[182:185], v152 offset:3072
	v_add_u32_e32 v152, s69, v161
	ds_read_b128 v[186:189], v152
	ds_read_b128 v[190:193], v152 offset:1024
	ds_read_b128 v[194:197], v152 offset:2048
	ds_read_b128 v[198:201], v152 offset:3072
	ds_read_b128 v[202:205], v171 offset:32768
	ds_read_b128 v[206:209], v171 offset:33792
	ds_read_b128 v[210:213], v171 offset:34816
	ds_read_b128 v[214:217], v171 offset:35840
	ds_read_b128 v[218:221], v171 offset:36864
	ds_read_b128 v[222:225], v171 offset:37888
	ds_read_b128 v[226:229], v171 offset:38912
	ds_read_b128 v[230:233], v171 offset:39936
	s_waitcnt vmcnt(8)
	s_waitcnt lgkmcnt(0)
	s_barrier
	s_setprio 1
	s_waitcnt lgkmcnt(0)
	v_mfma_f32_16x16x32_bf16 v[124:127], v[144:147], v[202:205], v[124:127]
	v_mfma_f32_16x16x32_bf16 v[120:123], v[178:181], v[202:205], v[120:123]
	v_mfma_f32_16x16x32_bf16 v[108:111], v[144:147], v[210:213], v[108:111]
	v_mfma_f32_16x16x32_bf16 v[104:107], v[178:181], v[210:213], v[104:107]
	v_mfma_f32_16x16x32_bf16 v[92:95], v[144:147], v[218:221], v[92:95]
	v_mfma_f32_16x16x32_bf16 v[88:91], v[178:181], v[218:221], v[88:91]
	v_mfma_f32_16x16x32_bf16 v[76:79], v[144:147], v[226:229], v[76:79]
	v_mfma_f32_16x16x32_bf16 v[72:75], v[178:181], v[226:229], v[72:75]
	v_mfma_f32_16x16x32_bf16 v[124:127], v[174:177], v[206:209], v[124:127]
	v_mfma_f32_16x16x32_bf16 v[120:123], v[182:185], v[206:209], v[120:123]
	v_mfma_f32_16x16x32_bf16 v[108:111], v[174:177], v[214:217], v[108:111]
	v_mfma_f32_16x16x32_bf16 v[104:107], v[182:185], v[214:217], v[104:107]
	v_mfma_f32_16x16x32_bf16 v[92:95], v[174:177], v[222:225], v[92:95]
	v_mfma_f32_16x16x32_bf16 v[88:91], v[182:185], v[222:225], v[88:91]
	v_mfma_f32_16x16x32_bf16 v[76:79], v[174:177], v[230:233], v[76:79]
	v_mfma_f32_16x16x32_bf16 v[72:75], v[182:185], v[230:233], v[72:75]
	s_setprio 0
	s_setprio 1
	v_mfma_f32_16x16x32_bf16 v[116:119], v[186:189], v[202:205], v[116:119]
	v_mfma_f32_16x16x32_bf16 v[112:115], v[194:197], v[202:205], v[112:115]
	v_mfma_f32_16x16x32_bf16 v[100:103], v[186:189], v[210:213], v[100:103]
	v_mfma_f32_16x16x32_bf16 v[96:99], v[194:197], v[210:213], v[96:99]
	v_mfma_f32_16x16x32_bf16 v[84:87], v[186:189], v[218:221], v[84:87]
	v_mfma_f32_16x16x32_bf16 v[80:83], v[194:197], v[218:221], v[80:83]
	v_mfma_f32_16x16x32_bf16 v[68:71], v[186:189], v[226:229], v[68:71]
	v_mfma_f32_16x16x32_bf16 v[64:67], v[194:197], v[226:229], v[64:67]
	v_mfma_f32_16x16x32_bf16 v[116:119], v[190:193], v[206:209], v[116:119]
	v_mfma_f32_16x16x32_bf16 v[112:115], v[198:201], v[206:209], v[112:115]
	v_mfma_f32_16x16x32_bf16 v[100:103], v[190:193], v[214:217], v[100:103]
	v_mfma_f32_16x16x32_bf16 v[96:99], v[198:201], v[214:217], v[96:99]
	v_mfma_f32_16x16x32_bf16 v[84:87], v[190:193], v[222:225], v[84:87]
	v_mfma_f32_16x16x32_bf16 v[80:83], v[198:201], v[222:225], v[80:83]
	v_mfma_f32_16x16x32_bf16 v[68:71], v[190:193], v[230:233], v[68:71]
	v_mfma_f32_16x16x32_bf16 v[64:67], v[198:201], v[230:233], v[64:67]
	s_setprio 0
	s_barrier
; #define PG8_STAGE(bufoff, gbase, voff) do { _Pragma("unroll") for (int _i = 0; _i < 2; ++_i) \
;         __builtin_amdgcn_global_load_lds((const unsigned*)((const char*)(gbase) + (voff)[_i]), (PG8_LAS unsigned*)(lds + (bufoff) + ldsw + _i * 8192), 16, 0, 0); } while (0)
; #define PG8_LDA(dst, b, h) do { _Pragma("unroll") for (int m = 0; m < 4; ++m) _Pragma("unroll") for (int k = 0; k < 2; ++k) dst[m][k] = *(const PG8_LAS bf16x8*)(lds + PG8_SA(b, h) + aoff + m * 2048 + k * 1024); } while (0)
; #define PG8_MMA(ai, bj, At, Bt) do { __builtin_amdgcn_s_setprio(1); _Pragma("unroll") for (int m = 0; m < 4; ++m) _Pragma("unroll") for (int n = 0; n < 2; ++n) _Pragma("unroll") for (int k = 0; k < 2; ++k) \
;         acc[ai][bj][m][n] = __builtin_amdgcn_mfma_f32_16x16x32_bf16(Bt[n][k], At[m][k], acc[ai][bj][m][n], 0, 0, 0); __builtin_amdgcn_s_setprio(0); } while (0)
; #define PG8_WAIT_V(n) asm volatile("s_waitcnt vmcnt(" #n ")" ::: "memory")
; #define PG8_WAIT_L(n) asm volatile("s_waitcnt lgkmcnt(" #n ")" ::: "memory")
; #define PG8_BAR __builtin_amdgcn_s_barrier()
; #define PG8_SCHED __builtin_amdgcn_sched_barrier(0)
; template <class Epi, class Sched, bool ALIGN_EPI = false, bool SP2 = false>
; __device__ __forceinline__ void gemm_phase(PG8_LAS unsigned char* lds, const Gemm g, const Sched& S, const Epi& E) {
;     ...
;             PG8_LDA(At, 1, 1); PG8_STAGE(PG8_SB(1, 0), b3, voffB); PG8_STAGE(PG8_SB(1, 1), b3 + hstep, voffB); PG8_STAGE(PG8_SA(1, 0), a3, voffA);
;             PG8_WAIT_V(8); PG8_WAIT_L(0); PG8_BAR; PG8_MMA(1, 0, At, B0); PG8_MMA(1, 1, At, B1); PG8_BAR; PG8_SCHED;
;     ...
;         if constexpr (ALIGN_EPI) { if (wr == 0) PG8_BAR; }
	s_add_i32 s8, s57, s39
	v_lshl_add_u64 v[154:155], v[154:155], 0, s[18:19]
	s_mov_b32 m0, s8
	ds_read_b128 v[202:205], v171 offset:49152
	global_load_lds_dwordx4 v[154:155], off
	s_add_i32 m0, s8, 0x2000
	s_add_u32 s6, s6, 0x40080
	v_lshl_add_u64 v[154:155], v[234:235], 0, s[18:19]
	s_addc_u32 s7, s7, 0
	s_add_i32 s8, s69, s39
	global_load_lds_dwordx4 v[154:155], off
	v_lshl_add_u64 v[154:155], s[6:7], 0, v[130:131]
	s_mov_b32 m0, s8
	ds_read_b128 v[206:209], v171 offset:50176
	global_load_lds_dwordx4 v[154:155], off
	v_lshl_add_u64 v[154:155], s[6:7], 0, v[134:135]
	s_add_i32 m0, s8, 0x2000
	ds_read_b128 v[210:213], v171 offset:51200
	global_load_lds_dwordx4 v[154:155], off
	v_lshl_add_u64 v[154:155], v[236:237], 0, s[18:19]
	s_mov_b32 m0, s45
	ds_read_b128 v[214:217], v171 offset:52224
	global_load_lds_dwordx4 v[154:155], off
	v_lshl_add_u64 v[154:155], v[238:239], 0, s[18:19]
	s_mov_b32 m0, s50
	ds_read_b128 v[218:221], v171 offset:53248
	global_load_lds_dwordx4 v[154:155], off
	ds_read_b128 v[222:225], v171 offset:54272
	ds_read_b128 v[226:229], v171 offset:55296
	ds_read_b128 v[230:233], v171 offset:56320
	s_waitcnt vmcnt(8)
	s_waitcnt lgkmcnt(0)
	s_barrier
	s_setprio 1
	s_waitcnt lgkmcnt(0)
	v_mfma_f32_16x16x32_bf16 v[60:63], v[144:147], v[202:205], v[60:63]
	v_mfma_f32_16x16x32_bf16 v[56:59], v[178:181], v[202:205], v[56:59]
	v_mfma_f32_16x16x32_bf16 v[44:47], v[144:147], v[210:213], v[44:47]
	v_mfma_f32_16x16x32_bf16 v[40:43], v[178:181], v[210:213], v[40:43]
	v_mfma_f32_16x16x32_bf16 v[28:31], v[144:147], v[218:221], v[28:31]
	v_mfma_f32_16x16x32_bf16 v[24:27], v[178:181], v[218:221], v[24:27]
	v_mfma_f32_16x16x32_bf16 v[12:15], v[144:147], v[226:229], v[12:15]
	v_mfma_f32_16x16x32_bf16 v[8:11], v[178:181], v[226:229], v[8:11]
	v_mfma_f32_16x16x32_bf16 v[60:63], v[174:177], v[206:209], v[60:63]
	v_mfma_f32_16x16x32_bf16 v[56:59], v[182:185], v[206:209], v[56:59]
	v_mfma_f32_16x16x32_bf16 v[44:47], v[174:177], v[214:217], v[44:47]
	v_mfma_f32_16x16x32_bf16 v[40:43], v[182:185], v[214:217], v[40:43]
	v_mfma_f32_16x16x32_bf16 v[28:31], v[174:177], v[222:225], v[28:31]
	v_mfma_f32_16x16x32_bf16 v[24:27], v[182:185], v[222:225], v[24:27]
	v_mfma_f32_16x16x32_bf16 v[12:15], v[174:177], v[230:233], v[12:15]
	v_mfma_f32_16x16x32_bf16 v[8:11], v[182:185], v[230:233], v[8:11]
	s_setprio 0
	s_setprio 1
	v_mfma_f32_16x16x32_bf16 v[52:55], v[186:189], v[202:205], v[52:55]
	v_mfma_f32_16x16x32_bf16 v[48:51], v[194:197], v[202:205], v[48:51]
	v_mfma_f32_16x16x32_bf16 v[36:39], v[186:189], v[210:213], v[36:39]
	v_mfma_f32_16x16x32_bf16 v[32:35], v[194:197], v[210:213], v[32:35]
	v_mfma_f32_16x16x32_bf16 v[20:23], v[186:189], v[218:221], v[20:23]
	v_mfma_f32_16x16x32_bf16 v[16:19], v[194:197], v[218:221], v[16:19]
	v_mfma_f32_16x16x32_bf16 v[4:7], v[186:189], v[226:229], v[4:7]
	v_mfma_f32_16x16x32_bf16 v[0:3], v[194:197], v[226:229], v[0:3]
	v_mfma_f32_16x16x32_bf16 v[52:55], v[190:193], v[206:209], v[52:55]
	v_mfma_f32_16x16x32_bf16 v[48:51], v[198:201], v[206:209], v[48:51]
	v_mfma_f32_16x16x32_bf16 v[36:39], v[190:193], v[214:217], v[36:39]
	v_mfma_f32_16x16x32_bf16 v[32:35], v[198:201], v[214:217], v[32:35]
	v_mfma_f32_16x16x32_bf16 v[20:23], v[190:193], v[222:225], v[20:23]
	v_mfma_f32_16x16x32_bf16 v[16:19], v[198:201], v[222:225], v[16:19]
	v_mfma_f32_16x16x32_bf16 v[4:7], v[190:193], v[230:233], v[4:7]
	v_mfma_f32_16x16x32_bf16 v[0:3], v[198:201], v[230:233], v[0:3]
	s_setprio 0
	s_barrier
	s_add_i32 s56, s56, 2
	s_add_u32 s4, s4, 0x100
	s_addc_u32 s5, s5, 0
	s_add_u32 s52, s52, 0x100
	s_addc_u32 s53, s53, 0
	s_cmp_gt_u32 s56, 13
	s_cbranch_scc0 .LBB0_1247
	s_nop 0
	s_nop 0
	s_nop 0
	s_nop 0
	s_nop 0
	s_nop 0
	s_nop 0
	s_nop 0
	s_nop 0
	s_and_b64 vcc, exec, s[20:21]
	s_cbranch_vccz .LBB0_1250
	s_barrier

; #define PG8_STAGE(bufoff, gbase, voff) do { _Pragma("unroll") for (int _i = 0; _i < 2; ++_i) \
;         __builtin_amdgcn_global_load_lds((const unsigned*)((const char*)(gbase) + (voff)[_i]), (PG8_LAS unsigned*)(lds + (bufoff) + ldsw + _i * 8192), 16, 0, 0); } while (0)
; #define PG8_LDA(dst, b, h) do { _Pragma("unroll") for (int m = 0; m < 4; ++m) _Pragma("unroll") for (int k = 0; k < 2; ++k) dst[m][k] = *(const PG8_LAS bf16x8*)(lds + PG8_SA(b, h) + aoff + m * 2048 + k * 1024); } while (0)
; #define PG8_LDB(dst, b, h) do { _Pragma("unroll") for (int n = 0; n < 2; ++n) _Pragma("unroll") for (int k = 0; k < 2; ++k) dst[n][k] = *(const PG8_LAS bf16x8*)(lds + PG8_SB(b, h) + boff + n * 2048 + k * 1024); } while (0)
; #define PG8_MMA(ai, bj, At, Bt) do { __builtin_amdgcn_s_setprio(1); _Pragma("unroll") for (int m = 0; m < 4; ++m) _Pragma("unroll") for (int n = 0; n < 2; ++n) _Pragma("unroll") for (int k = 0; k < 2; ++k) \
;         acc[ai][bj][m][n] = __builtin_amdgcn_mfma_f32_16x16x32_bf16(Bt[n][k], At[m][k], acc[ai][bj][m][n], 0, 0, 0); __builtin_amdgcn_s_setprio(0); } while (0)
; #define PG8_WAIT_V(n) asm volatile("s_waitcnt vmcnt(" #n ")" ::: "memory")
; #define PG8_WAIT_L(n) asm volatile("s_waitcnt lgkmcnt(" #n ")" ::: "memory")
; template <class Epi, class Sched, bool ALIGN_EPI = false, bool SP2 = false>
; __device__ __forceinline__ void gemm_phase(PG8_LAS unsigned char* lds, const Gemm g, const Sched& S, const Epi& E) {
;     ...
;             const bool last = (t == nt - 2);
;             const char* a1 = cA + (size_t)(t + 1) * kstep;
;             const char* a2 = last ? nA : cA + (size_t)(t + 2) * kstep; const char* b2 = last ? nB : cB + (size_t)(t + 2) * kstep;
;             const char* a3 = a2 + kstep; const char* b3 = b2 + kstep;
;             if (last && has_next) S.a_ready(nxt);
;             if constexpr (SP2) {
;             PG8_LDB(B0, 0, 0); PG8_LDB(B1, 0, 1); PG8_SCHED; PG8_LDA(At, 0, 0); PG8_STAGE(PG8_SA(1, 1), a1 + hstep, voffA);
;             PG8_WAIT_V(8); PG8_WAIT_L(0); PG8_BAR; PG8_MMA(0, 0, At, B0); PG8_MMA(0, 1, At, B1); PG8_BAR; PG8_SCHED;
;             PG8_LDA(At, 0, 1); PG8_STAGE(PG8_SB(0, 0), b2, voffB); PG8_STAGE(PG8_SB(0, 1), b2 + hstep, voffB); PG8_STAGE(PG8_SA(0, 0), a2, voffA);
;             PG8_WAIT_V(8); PG8_WAIT_L(0); PG8_BAR; PG8_MMA(1, 0, At, B0); PG8_MMA(1, 1, At, B1); PG8_BAR; PG8_SCHED;
.LBB0_1271:
	v_lshl_add_u64 v[160:161], s[28:29], 0, v[144:145]
	s_add_i32 m0, s27, 0xc000
	ds_read_b128 v[156:159], v135
	global_load_lds_dwordx4 v[160:161], off
	v_lshl_add_u64 v[160:161], s[28:29], 0, v[146:147]
	s_add_i32 m0, s27, 0xe000
	ds_read_b128 v[170:173], v135 offset:1024
	global_load_lds_dwordx4 v[160:161], off
	s_add_u32 s30, s28, 0xfffe0080
	s_addc_u32 s31, s29, -1
	s_cmp_eq_u32 s63, 4
	s_cselect_b32 s35, s21, s31
	s_cselect_b32 s34, s56, s30
	s_cselect_b32 s31, s19, s62
	s_cselect_b32 s30, s57, s61
	ds_read_b128 v[174:177], v135 offset:2048
	ds_read_b128 v[178:181], v135 offset:3072
	ds_read_b128 v[182:185], v162
	ds_read_b128 v[186:189], v162 offset:1024
	ds_read_b128 v[190:193], v162 offset:2048
	ds_read_b128 v[194:197], v162 offset:3072
	ds_read_b128 v[198:201], v163
	ds_read_b128 v[202:205], v163 offset:1024
	ds_read_b128 v[206:209], v163 offset:2048
	ds_read_b128 v[210:213], v163 offset:3072
	ds_read_b128 v[214:217], v163 offset:4096
	ds_read_b128 v[218:221], v163 offset:5120
	ds_read_b128 v[222:225], v163 offset:6144
	ds_read_b128 v[226:229], v163 offset:7168
	s_waitcnt vmcnt(8)
	s_waitcnt lgkmcnt(0)
	s_barrier
	s_setprio 1
	s_waitcnt lgkmcnt(0)
	v_mfma_f32_16x16x32_bf16 v[124:127], v[156:159], v[198:201], v[124:127]
	v_mfma_f32_16x16x32_bf16 v[120:123], v[174:177], v[198:201], v[120:123]
	v_mfma_f32_16x16x32_bf16 v[108:111], v[156:159], v[206:209], v[108:111]
	v_mfma_f32_16x16x32_bf16 v[104:107], v[174:177], v[206:209], v[104:107]
	v_mfma_f32_16x16x32_bf16 v[92:95], v[156:159], v[214:217], v[92:95]
	v_mfma_f32_16x16x32_bf16 v[88:91], v[174:177], v[214:217], v[88:91]
	v_mfma_f32_16x16x32_bf16 v[76:79], v[156:159], v[222:225], v[76:79]
	v_mfma_f32_16x16x32_bf16 v[72:75], v[174:177], v[222:225], v[72:75]
	v_mfma_f32_16x16x32_bf16 v[124:127], v[170:173], v[202:205], v[124:127]
	v_mfma_f32_16x16x32_bf16 v[120:123], v[178:181], v[202:205], v[120:123]
	v_mfma_f32_16x16x32_bf16 v[108:111], v[170:173], v[210:213], v[108:111]
	v_mfma_f32_16x16x32_bf16 v[104:107], v[178:181], v[210:213], v[104:107]
	v_mfma_f32_16x16x32_bf16 v[92:95], v[170:173], v[218:221], v[92:95]
	v_mfma_f32_16x16x32_bf16 v[88:91], v[178:181], v[218:221], v[88:91]
	v_mfma_f32_16x16x32_bf16 v[76:79], v[170:173], v[226:229], v[76:79]
	v_mfma_f32_16x16x32_bf16 v[72:75], v[178:181], v[226:229], v[72:75]
	s_setprio 0
	s_setprio 1
	v_mfma_f32_16x16x32_bf16 v[116:119], v[182:185], v[198:201], v[116:119]
	v_mfma_f32_16x16x32_bf16 v[112:115], v[190:193], v[198:201], v[112:115]
	v_mfma_f32_16x16x32_bf16 v[100:103], v[182:185], v[206:209], v[100:103]
	v_mfma_f32_16x16x32_bf16 v[96:99], v[190:193], v[206:209], v[96:99]
	v_mfma_f32_16x16x32_bf16 v[84:87], v[182:185], v[214:217], v[84:87]
	v_mfma_f32_16x16x32_bf16 v[80:83], v[190:193], v[214:217], v[80:83]
	v_mfma_f32_16x16x32_bf16 v[68:71], v[182:185], v[222:225], v[68:71]
	v_mfma_f32_16x16x32_bf16 v[64:67], v[190:193], v[222:225], v[64:67]
	v_mfma_f32_16x16x32_bf16 v[116:119], v[186:189], v[202:205], v[116:119]
	v_mfma_f32_16x16x32_bf16 v[112:115], v[194:197], v[202:205], v[112:115]
	v_mfma_f32_16x16x32_bf16 v[100:103], v[186:189], v[210:213], v[100:103]
	v_mfma_f32_16x16x32_bf16 v[96:99], v[194:197], v[210:213], v[96:99]
	v_mfma_f32_16x16x32_bf16 v[84:87], v[186:189], v[218:221], v[84:87]
	v_mfma_f32_16x16x32_bf16 v[80:83], v[194:197], v[218:221], v[80:83]
	v_mfma_f32_16x16x32_bf16 v[68:71], v[186:189], v[226:229], v[68:71]
	v_mfma_f32_16x16x32_bf16 v[64:67], v[194:197], v[226:229], v[64:67]
	s_setprio 0
	s_barrier
	s_add_i32 s68, s45, s37
	v_lshl_add_u64 v[160:161], s[30:31], 0, v[138:139]
	s_mov_b32 m0, s68
	v_lshl_add_u64 v[230:231], s[30:31], 0, v[142:143]
	global_load_lds_dwordx4 v[160:161], off
	s_add_i32 m0, s68, 0x2000
	s_add_u32 s68, s30, 0x20000
	s_addc_u32 s69, s31, 0
	s_add_i32 s70, s50, s37
	global_load_lds_dwordx4 v[230:231], off
	v_lshl_add_u64 v[232:233], s[68:69], 0, v[138:139]
	s_mov_b32 m0, s70
	v_lshl_add_u64 v[234:235], s[34:35], 0, v[140:141]
	global_load_lds_dwordx4 v[232:233], off
	v_lshl_add_u64 v[232:233], s[68:69], 0, v[142:143]
	s_add_i32 m0, s70, 0x2000
	ds_read_b128 v[198:201], v163 offset:16384
	global_load_lds_dwordx4 v[232:233], off
	v_lshl_add_u64 v[232:233], s[34:35], 0, v[136:137]
	s_mov_b32 m0, s27
	ds_read_b128 v[202:205], v163 offset:17408
	global_load_lds_dwordx4 v[232:233], off
	s_mov_b32 m0, s38
	ds_read_b128 v[206:209], v163 offset:18432
	global_load_lds_dwordx4 v[234:235], off
	ds_read_b128 v[210:213], v163 offset:19456
	ds_read_b128 v[214:217], v163 offset:20480
	ds_read_b128 v[218:221], v163 offset:21504
	ds_read_b128 v[222:225], v163 offset:22528
	ds_read_b128 v[226:229], v163 offset:23552
	s_waitcnt vmcnt(8)
	s_waitcnt lgkmcnt(0)
	s_barrier
; #define PG8_STAGE(bufoff, gbase, voff) do { _Pragma("unroll") for (int _i = 0; _i < 2; ++_i) \
;         __builtin_amdgcn_global_load_lds((const unsigned*)((const char*)(gbase) + (voff)[_i]), (PG8_LAS unsigned*)(lds + (bufoff) + ldsw + _i * 8192), 16, 0, 0); } while (0)
; #define PG8_LDA(dst, b, h) do { _Pragma("unroll") for (int m = 0; m < 4; ++m) _Pragma("unroll") for (int k = 0; k < 2; ++k) dst[m][k] = *(const PG8_LAS bf16x8*)(lds + PG8_SA(b, h) + aoff + m * 2048 + k * 1024); } while (0)
; #define PG8_LDB(dst, b, h) do { _Pragma("unroll") for (int n = 0; n < 2; ++n) _Pragma("unroll") for (int k = 0; k < 2; ++k) dst[n][k] = *(const PG8_LAS bf16x8*)(lds + PG8_SB(b, h) + boff + n * 2048 + k * 1024); } while (0)
; #define PG8_MMA(ai, bj, At, Bt) do { __builtin_amdgcn_s_setprio(1); _Pragma("unroll") for (int m = 0; m < 4; ++m) _Pragma("unroll") for (int n = 0; n < 2; ++n) _Pragma("unroll") for (int k = 0; k < 2; ++k) \
;         acc[ai][bj][m][n] = __builtin_amdgcn_mfma_f32_16x16x32_bf16(Bt[n][k], At[m][k], acc[ai][bj][m][n], 0, 0, 0); __builtin_amdgcn_s_setprio(0); } while (0)
; #define PG8_WAIT_V(n) asm volatile("s_waitcnt vmcnt(" #n ")" ::: "memory")
; #define PG8_WAIT_L(n) asm volatile("s_waitcnt lgkmcnt(" #n ")" ::: "memory")
; #define PG8_BAR __builtin_amdgcn_s_barrier()
; #define PG8_SCHED __builtin_amdgcn_sched_barrier(0)
; template <class Epi, class Sched, bool ALIGN_EPI = false, bool SP2 = false>
; __device__ __forceinline__ void gemm_phase(PG8_LAS unsigned char* lds, const Gemm g, const Sched& S, const Epi& E) {
;     ...
;             PG8_WAIT_V(8); PG8_WAIT_L(0); PG8_BAR; PG8_MMA(1, 0, At, B0); PG8_MMA(1, 1, At, B1); PG8_BAR; PG8_SCHED;
;             PG8_LDB(B0, 1, 0); PG8_LDB(B1, 1, 1); PG8_SCHED; PG8_LDA(At, 1, 0); PG8_STAGE(PG8_SA(0, 1), a2 + hstep, voffA);
;             PG8_WAIT_V(8); PG8_WAIT_L(0); PG8_BAR; PG8_MMA(0, 0, At, B0); PG8_MMA(0, 1, At, B1); PG8_BAR; PG8_SCHED;
	s_setprio 1
	s_waitcnt lgkmcnt(0)
	v_mfma_f32_16x16x32_bf16 v[60:63], v[156:159], v[198:201], v[60:63]
	v_mfma_f32_16x16x32_bf16 v[56:59], v[174:177], v[198:201], v[56:59]
	v_mfma_f32_16x16x32_bf16 v[44:47], v[156:159], v[206:209], v[44:47]
	v_mfma_f32_16x16x32_bf16 v[40:43], v[174:177], v[206:209], v[40:43]
	v_mfma_f32_16x16x32_bf16 v[28:31], v[156:159], v[214:217], v[28:31]
	v_mfma_f32_16x16x32_bf16 v[24:27], v[174:177], v[214:217], v[24:27]
	v_mfma_f32_16x16x32_bf16 v[12:15], v[156:159], v[222:225], v[12:15]
	v_mfma_f32_16x16x32_bf16 v[8:11], v[174:177], v[222:225], v[8:11]
	v_mfma_f32_16x16x32_bf16 v[60:63], v[170:173], v[202:205], v[60:63]
	v_mfma_f32_16x16x32_bf16 v[56:59], v[178:181], v[202:205], v[56:59]
	v_mfma_f32_16x16x32_bf16 v[44:47], v[170:173], v[210:213], v[44:47]
	v_mfma_f32_16x16x32_bf16 v[40:43], v[178:181], v[210:213], v[40:43]
	v_mfma_f32_16x16x32_bf16 v[28:31], v[170:173], v[218:221], v[28:31]
	v_mfma_f32_16x16x32_bf16 v[24:27], v[178:181], v[218:221], v[24:27]
	v_mfma_f32_16x16x32_bf16 v[12:15], v[170:173], v[226:229], v[12:15]
	v_mfma_f32_16x16x32_bf16 v[8:11], v[178:181], v[226:229], v[8:11]
	s_setprio 0
	s_setprio 1
	v_mfma_f32_16x16x32_bf16 v[52:55], v[182:185], v[198:201], v[52:55]
	v_mfma_f32_16x16x32_bf16 v[48:51], v[190:193], v[198:201], v[48:51]
	v_mfma_f32_16x16x32_bf16 v[36:39], v[182:185], v[206:209], v[36:39]
	v_mfma_f32_16x16x32_bf16 v[32:35], v[190:193], v[206:209], v[32:35]
	v_mfma_f32_16x16x32_bf16 v[20:23], v[182:185], v[214:217], v[20:23]
	v_mfma_f32_16x16x32_bf16 v[16:19], v[190:193], v[214:217], v[16:19]
	v_mfma_f32_16x16x32_bf16 v[4:7], v[182:185], v[222:225], v[4:7]
	v_mfma_f32_16x16x32_bf16 v[0:3], v[190:193], v[222:225], v[0:3]
	v_mfma_f32_16x16x32_bf16 v[52:55], v[186:189], v[202:205], v[52:55]
	v_mfma_f32_16x16x32_bf16 v[48:51], v[194:197], v[202:205], v[48:51]
	v_mfma_f32_16x16x32_bf16 v[36:39], v[186:189], v[210:213], v[36:39]
	v_mfma_f32_16x16x32_bf16 v[32:35], v[194:197], v[210:213], v[32:35]
	v_mfma_f32_16x16x32_bf16 v[20:23], v[186:189], v[218:221], v[20:23]
	v_mfma_f32_16x16x32_bf16 v[16:19], v[194:197], v[218:221], v[16:19]
	v_mfma_f32_16x16x32_bf16 v[4:7], v[186:189], v[226:229], v[4:7]
	v_mfma_f32_16x16x32_bf16 v[0:3], v[194:197], v[226:229], v[0:3]
	s_setprio 0
	s_barrier
	s_add_i32 s68, 0, 0x18000
	s_add_i32 s69, 0, 0x1c000
	s_add_u32 s34, s34, 0x20000
	s_addc_u32 s35, s35, 0
	s_mov_b32 m0, s39
	v_lshl_add_u64 v[236:237], s[34:35], 0, v[136:137]
	global_load_lds_dwordx4 v[236:237], off
	v_lshl_add_u64 v[236:237], s[34:35], 0, v[140:141]
	s_mov_b32 m0, s40
	v_add_u32_e32 v178, s68, v131
	global_load_lds_dwordx4 v[236:237], off
	v_add_u32_e32 v194, s69, v131
	ds_read_b128 v[156:159], v178
	ds_read_b128 v[170:173], v178 offset:1024
	ds_read_b128 v[174:177], v178 offset:2048
	ds_read_b128 v[178:181], v178 offset:3072
	ds_read_b128 v[182:185], v194
	ds_read_b128 v[186:189], v194 offset:1024
	ds_read_b128 v[190:193], v194 offset:2048
	ds_read_b128 v[194:197], v194 offset:3072
	ds_read_b128 v[198:201], v163 offset:32768
	ds_read_b128 v[202:205], v163 offset:33792
	ds_read_b128 v[206:209], v163 offset:34816
	ds_read_b128 v[210:213], v163 offset:35840
	ds_read_b128 v[214:217], v163 offset:36864
	ds_read_b128 v[218:221], v163 offset:37888
	ds_read_b128 v[222:225], v163 offset:38912
	ds_read_b128 v[226:229], v163 offset:39936
	s_waitcnt vmcnt(8)
	s_waitcnt lgkmcnt(0)
	s_barrier
	s_setprio 1
	s_waitcnt lgkmcnt(0)
	v_mfma_f32_16x16x32_bf16 v[124:127], v[156:159], v[198:201], v[124:127]
	v_mfma_f32_16x16x32_bf16 v[120:123], v[174:177], v[198:201], v[120:123]
	v_mfma_f32_16x16x32_bf16 v[108:111], v[156:159], v[206:209], v[108:111]
	v_mfma_f32_16x16x32_bf16 v[104:107], v[174:177], v[206:209], v[104:107]
	v_mfma_f32_16x16x32_bf16 v[92:95], v[156:159], v[214:217], v[92:95]
	v_mfma_f32_16x16x32_bf16 v[88:91], v[174:177], v[214:217], v[88:91]
	v_mfma_f32_16x16x32_bf16 v[76:79], v[156:159], v[222:225], v[76:79]
	v_mfma_f32_16x16x32_bf16 v[72:75], v[174:177], v[222:225], v[72:75]
	v_mfma_f32_16x16x32_bf16 v[124:127], v[170:173], v[202:205], v[124:127]
	v_mfma_f32_16x16x32_bf16 v[120:123], v[178:181], v[202:205], v[120:123]
	v_mfma_f32_16x16x32_bf16 v[108:111], v[170:173], v[210:213], v[108:111]
	v_mfma_f32_16x16x32_bf16 v[104:107], v[178:181], v[210:213], v[104:107]
	v_mfma_f32_16x16x32_bf16 v[92:95], v[170:173], v[218:221], v[92:95]
	v_mfma_f32_16x16x32_bf16 v[88:91], v[178:181], v[218:221], v[88:91]
	v_mfma_f32_16x16x32_bf16 v[76:79], v[170:173], v[226:229], v[76:79]
	v_mfma_f32_16x16x32_bf16 v[72:75], v[178:181], v[226:229], v[72:75]
	s_setprio 0
	s_setprio 1
	v_mfma_f32_16x16x32_bf16 v[116:119], v[182:185], v[198:201], v[116:119]
	v_mfma_f32_16x16x32_bf16 v[112:115], v[190:193], v[198:201], v[112:115]
	v_mfma_f32_16x16x32_bf16 v[100:103], v[182:185], v[206:209], v[100:103]
	v_mfma_f32_16x16x32_bf16 v[96:99], v[190:193], v[206:209], v[96:99]
	v_mfma_f32_16x16x32_bf16 v[84:87], v[182:185], v[214:217], v[84:87]
	v_mfma_f32_16x16x32_bf16 v[80:83], v[190:193], v[214:217], v[80:83]
	v_mfma_f32_16x16x32_bf16 v[68:71], v[182:185], v[222:225], v[68:71]
	v_mfma_f32_16x16x32_bf16 v[64:67], v[190:193], v[222:225], v[64:67]
	v_mfma_f32_16x16x32_bf16 v[116:119], v[186:189], v[202:205], v[116:119]
	v_mfma_f32_16x16x32_bf16 v[112:115], v[194:197], v[202:205], v[112:115]
	v_mfma_f32_16x16x32_bf16 v[100:103], v[186:189], v[210:213], v[100:103]
	v_mfma_f32_16x16x32_bf16 v[96:99], v[194:197], v[210:213], v[96:99]
	v_mfma_f32_16x16x32_bf16 v[84:87], v[186:189], v[218:221], v[84:87]
	v_mfma_f32_16x16x32_bf16 v[80:83], v[194:197], v[218:221], v[80:83]
	v_mfma_f32_16x16x32_bf16 v[68:71], v[186:189], v[226:229], v[68:71]
	v_mfma_f32_16x16x32_bf16 v[64:67], v[194:197], v[226:229], v[64:67]
	s_setprio 0
	s_barrier
; #define PG8_STAGE(bufoff, gbase, voff) do { _Pragma("unroll") for (int _i = 0; _i < 2; ++_i) \
;         __builtin_amdgcn_global_load_lds((const unsigned*)((const char*)(gbase) + (voff)[_i]), (PG8_LAS unsigned*)(lds + (bufoff) + ldsw + _i * 8192), 16, 0, 0); } while (0)
; #define PG8_LDA(dst, b, h) do { _Pragma("unroll") for (int m = 0; m < 4; ++m) _Pragma("unroll") for (int k = 0; k < 2; ++k) dst[m][k] = *(const PG8_LAS bf16x8*)(lds + PG8_SA(b, h) + aoff + m * 2048 + k * 1024); } while (0)
; #define PG8_MMA(ai, bj, At, Bt) do { __builtin_amdgcn_s_setprio(1); _Pragma("unroll") for (int m = 0; m < 4; ++m) _Pragma("unroll") for (int n = 0; n < 2; ++n) _Pragma("unroll") for (int k = 0; k < 2; ++k) \
;         acc[ai][bj][m][n] = __builtin_amdgcn_mfma_f32_16x16x32_bf16(Bt[n][k], At[m][k], acc[ai][bj][m][n], 0, 0, 0); __builtin_amdgcn_s_setprio(0); } while (0)
; #define PG8_WAIT_V(n) asm volatile("s_waitcnt vmcnt(" #n ")" ::: "memory")
; #define PG8_WAIT_L(n) asm volatile("s_waitcnt lgkmcnt(" #n ")" ::: "memory")
; #define PG8_BAR __builtin_amdgcn_s_barrier()
; #define PG8_SCHED __builtin_amdgcn_sched_barrier(0)
; template <class Epi, class Sched, bool ALIGN_EPI = false, bool SP2 = false>
; __device__ __forceinline__ void gemm_phase(PG8_LAS unsigned char* lds, const Gemm g, const Sched& S, const Epi& E) {
;     ...
;             PG8_LDA(At, 1, 1); PG8_STAGE(PG8_SB(1, 0), b3, voffB); PG8_STAGE(PG8_SB(1, 1), b3 + hstep, voffB); PG8_STAGE(PG8_SA(1, 0), a3, voffA);
;             PG8_WAIT_V(8); PG8_WAIT_L(0); PG8_BAR; PG8_MMA(1, 0, At, B0); PG8_MMA(1, 1, At, B1); PG8_BAR; PG8_SCHED;
;     ...
;         if constexpr (ALIGN_EPI) { if (wr == 0) PG8_BAR; }
	s_add_i32 s34, s68, s37
	v_lshl_add_u64 v[160:161], v[160:161], 0, s[6:7]
	s_mov_b32 m0, s34
	ds_read_b128 v[198:201], v163 offset:49152
	global_load_lds_dwordx4 v[160:161], off
	s_add_i32 m0, s34, 0x2000
	s_add_u32 s30, s30, 0x20080
	v_lshl_add_u64 v[160:161], v[230:231], 0, s[6:7]
	s_addc_u32 s31, s31, 0
	s_add_i32 s34, s69, s37
	global_load_lds_dwordx4 v[160:161], off
	v_lshl_add_u64 v[160:161], s[30:31], 0, v[138:139]
	s_mov_b32 m0, s34
	ds_read_b128 v[202:205], v163 offset:50176
	global_load_lds_dwordx4 v[160:161], off
	v_lshl_add_u64 v[160:161], s[30:31], 0, v[142:143]
	s_add_i32 m0, s34, 0x2000
	ds_read_b128 v[206:209], v163 offset:51200
	global_load_lds_dwordx4 v[160:161], off
	v_lshl_add_u64 v[160:161], v[232:233], 0, s[6:7]
	s_mov_b32 m0, s42
	ds_read_b128 v[210:213], v163 offset:52224
	global_load_lds_dwordx4 v[160:161], off
	v_lshl_add_u64 v[160:161], v[234:235], 0, s[6:7]
	s_mov_b32 m0, s43
	ds_read_b128 v[214:217], v163 offset:53248
	global_load_lds_dwordx4 v[160:161], off
	ds_read_b128 v[218:221], v163 offset:54272
	ds_read_b128 v[222:225], v163 offset:55296
	ds_read_b128 v[226:229], v163 offset:56320
	s_waitcnt vmcnt(8)
	s_waitcnt lgkmcnt(0)
	s_barrier
	s_setprio 1
	s_waitcnt lgkmcnt(0)
	v_mfma_f32_16x16x32_bf16 v[60:63], v[156:159], v[198:201], v[60:63]
	v_mfma_f32_16x16x32_bf16 v[56:59], v[174:177], v[198:201], v[56:59]
	v_mfma_f32_16x16x32_bf16 v[44:47], v[156:159], v[206:209], v[44:47]
	v_mfma_f32_16x16x32_bf16 v[40:43], v[174:177], v[206:209], v[40:43]
	v_mfma_f32_16x16x32_bf16 v[28:31], v[156:159], v[214:217], v[28:31]
	v_mfma_f32_16x16x32_bf16 v[24:27], v[174:177], v[214:217], v[24:27]
	v_mfma_f32_16x16x32_bf16 v[12:15], v[156:159], v[222:225], v[12:15]
	v_mfma_f32_16x16x32_bf16 v[8:11], v[174:177], v[222:225], v[8:11]
	v_mfma_f32_16x16x32_bf16 v[60:63], v[170:173], v[202:205], v[60:63]
	v_mfma_f32_16x16x32_bf16 v[56:59], v[178:181], v[202:205], v[56:59]
	v_mfma_f32_16x16x32_bf16 v[44:47], v[170:173], v[210:213], v[44:47]
	v_mfma_f32_16x16x32_bf16 v[40:43], v[178:181], v[210:213], v[40:43]
	v_mfma_f32_16x16x32_bf16 v[28:31], v[170:173], v[218:221], v[28:31]
	v_mfma_f32_16x16x32_bf16 v[24:27], v[178:181], v[218:221], v[24:27]
	v_mfma_f32_16x16x32_bf16 v[12:15], v[170:173], v[226:229], v[12:15]
	v_mfma_f32_16x16x32_bf16 v[8:11], v[178:181], v[226:229], v[8:11]
	s_setprio 0
	s_setprio 1
	v_mfma_f32_16x16x32_bf16 v[52:55], v[182:185], v[198:201], v[52:55]
	v_mfma_f32_16x16x32_bf16 v[48:51], v[190:193], v[198:201], v[48:51]
	v_mfma_f32_16x16x32_bf16 v[36:39], v[182:185], v[206:209], v[36:39]
	v_mfma_f32_16x16x32_bf16 v[32:35], v[190:193], v[206:209], v[32:35]
	v_mfma_f32_16x16x32_bf16 v[20:23], v[182:185], v[214:217], v[20:23]
	v_mfma_f32_16x16x32_bf16 v[16:19], v[190:193], v[214:217], v[16:19]
	v_mfma_f32_16x16x32_bf16 v[4:7], v[182:185], v[222:225], v[4:7]
	v_mfma_f32_16x16x32_bf16 v[0:3], v[190:193], v[222:225], v[0:3]
	v_mfma_f32_16x16x32_bf16 v[52:55], v[186:189], v[202:205], v[52:55]
	v_mfma_f32_16x16x32_bf16 v[48:51], v[194:197], v[202:205], v[48:51]
	v_mfma_f32_16x16x32_bf16 v[36:39], v[186:189], v[210:213], v[36:39]
	v_mfma_f32_16x16x32_bf16 v[32:35], v[194:197], v[210:213], v[32:35]
	v_mfma_f32_16x16x32_bf16 v[20:23], v[186:189], v[218:221], v[20:23]
	v_mfma_f32_16x16x32_bf16 v[16:19], v[194:197], v[218:221], v[16:19]
	v_mfma_f32_16x16x32_bf16 v[4:7], v[186:189], v[226:229], v[4:7]
	v_mfma_f32_16x16x32_bf16 v[0:3], v[194:197], v[226:229], v[0:3]
	s_setprio 0
	s_barrier
	s_add_i32 s63, s63, 2
	s_add_u32 s28, s28, 0x100
	s_addc_u32 s29, s29, 0
	s_add_u32 s61, s61, 0x100
	s_addc_u32 s62, s62, 0
	s_cmp_gt_u32 s63, 5
	s_cbranch_scc0 .LBB0_1271
	s_nop 0
	s_nop 0
	s_nop 0
	s_nop 0
	s_nop 0
	s_nop 0
	s_nop 0
	s_nop 0
	s_nop 0
	s_and_b64 vcc, exec, s[8:9]
	s_cbranch_vccz .LBB0_1274
	s_barrier

; #define PG8_STAGE(bufoff, gbase, voff) do { _Pragma("unroll") for (int _i = 0; _i < 2; ++_i) \
;         __builtin_amdgcn_global_load_lds((const unsigned*)((const char*)(gbase) + (voff)[_i]), (PG8_LAS unsigned*)(lds + (bufoff) + ldsw + _i * 8192), 16, 0, 0); } while (0)
; #define PG8_LDA(dst, b, h) do { _Pragma("unroll") for (int m = 0; m < 4; ++m) _Pragma("unroll") for (int k = 0; k < 2; ++k) dst[m][k] = *(const PG8_LAS bf16x8*)(lds + PG8_SA(b, h) + aoff + m * 2048 + k * 1024); } while (0)
; #define PG8_LDB(dst, b, h) do { _Pragma("unroll") for (int n = 0; n < 2; ++n) _Pragma("unroll") for (int k = 0; k < 2; ++k) dst[n][k] = *(const PG8_LAS bf16x8*)(lds + PG8_SB(b, h) + boff + n * 2048 + k * 1024); } while (0)
; #define PG8_MMA(ai, bj, At, Bt) do { __builtin_amdgcn_s_setprio(1); _Pragma("unroll") for (int m = 0; m < 4; ++m) _Pragma("unroll") for (int n = 0; n < 2; ++n) _Pragma("unroll") for (int k = 0; k < 2; ++k) \
;         acc[ai][bj][m][n] = __builtin_amdgcn_mfma_f32_16x16x32_bf16(Bt[n][k], At[m][k], acc[ai][bj][m][n], 0, 0, 0); __builtin_amdgcn_s_setprio(0); } while (0)
; #define PG8_WAIT_V(n) asm volatile("s_waitcnt vmcnt(" #n ")" ::: "memory")
; #define PG8_WAIT_L(n) asm volatile("s_waitcnt lgkmcnt(" #n ")" ::: "memory")
; template <class Epi, class Sched, bool ALIGN_EPI = false, bool SP2 = false>
; __device__ __forceinline__ void gemm_phase(PG8_LAS unsigned char* lds, const Gemm g, const Sched& S, const Epi& E) {
;     ...
;             const bool last = (t == nt - 2);
;             const char* a1 = cA + (size_t)(t + 1) * kstep;
;             const char* a2 = last ? nA : cA + (size_t)(t + 2) * kstep; const char* b2 = last ? nB : cB + (size_t)(t + 2) * kstep;
;             const char* a3 = a2 + kstep; const char* b3 = b2 + kstep;
;             if (last && has_next) S.a_ready(nxt);
;             if constexpr (SP2) {
;             PG8_LDB(B0, 0, 0); PG8_LDB(B1, 0, 1); PG8_SCHED; PG8_LDA(At, 0, 0); PG8_STAGE(PG8_SA(1, 1), a1 + hstep, voffA);
;             PG8_WAIT_V(8); PG8_WAIT_L(0); PG8_BAR; PG8_MMA(0, 0, At, B0); PG8_MMA(0, 1, At, B1); PG8_BAR; PG8_SCHED;
;             PG8_LDA(At, 0, 1); PG8_STAGE(PG8_SB(0, 0), b2, voffB); PG8_STAGE(PG8_SB(0, 1), b2 + hstep, voffB); PG8_STAGE(PG8_SA(0, 0), a2, voffA);
;             PG8_WAIT_V(8); PG8_WAIT_L(0); PG8_BAR; PG8_MMA(1, 0, At, B0); PG8_MMA(1, 1, At, B1); PG8_BAR; PG8_SCHED;
.LBB0_1295:
	v_lshl_add_u64 v[162:163], s[6:7], 0, v[144:145]
	s_add_i32 m0, s40, 0xc000
	ds_read_b128 v[156:159], v143
	global_load_lds_dwordx4 v[162:163], off
	v_lshl_add_u64 v[162:163], s[6:7], 0, v[146:147]
	s_add_i32 m0, s40, 0xe000
	ds_read_b128 v[172:175], v143 offset:1024
	global_load_lds_dwordx4 v[162:163], off
	s_add_u32 s8, s6, 0xfffc0080
	s_addc_u32 s9, s7, -1
	s_cmp_eq_u32 s68, 12
	s_cselect_b32 s11, s12, s9
	s_cselect_b32 s10, s13, s8
	s_cselect_b32 s9, s27, s53
	s_cselect_b32 s8, s29, s52
	ds_read_b128 v[176:179], v143 offset:2048
	ds_read_b128 v[180:183], v143 offset:3072
	ds_read_b128 v[184:187], v161
	ds_read_b128 v[188:191], v161 offset:1024
	ds_read_b128 v[192:195], v161 offset:2048
	ds_read_b128 v[196:199], v161 offset:3072
	ds_read_b128 v[200:203], v170
	ds_read_b128 v[204:207], v170 offset:1024
	ds_read_b128 v[208:211], v170 offset:2048
	ds_read_b128 v[212:215], v170 offset:3072
	ds_read_b128 v[216:219], v170 offset:4096
	ds_read_b128 v[220:223], v170 offset:5120
	ds_read_b128 v[224:227], v170 offset:6144
	ds_read_b128 v[228:231], v170 offset:7168
	s_waitcnt vmcnt(8)
	s_waitcnt lgkmcnt(0)
	s_barrier
	s_setprio 1
	s_waitcnt lgkmcnt(0)
	v_mfma_f32_16x16x32_bf16 v[124:127], v[156:159], v[200:203], v[124:127]
	v_mfma_f32_16x16x32_bf16 v[120:123], v[176:179], v[200:203], v[120:123]
	v_mfma_f32_16x16x32_bf16 v[108:111], v[156:159], v[208:211], v[108:111]
	v_mfma_f32_16x16x32_bf16 v[104:107], v[176:179], v[208:211], v[104:107]
	v_mfma_f32_16x16x32_bf16 v[92:95], v[156:159], v[216:219], v[92:95]
	v_mfma_f32_16x16x32_bf16 v[88:91], v[176:179], v[216:219], v[88:91]
	v_mfma_f32_16x16x32_bf16 v[76:79], v[156:159], v[224:227], v[76:79]
	v_mfma_f32_16x16x32_bf16 v[72:75], v[176:179], v[224:227], v[72:75]
	v_mfma_f32_16x16x32_bf16 v[124:127], v[172:175], v[204:207], v[124:127]
	v_mfma_f32_16x16x32_bf16 v[120:123], v[180:183], v[204:207], v[120:123]
	v_mfma_f32_16x16x32_bf16 v[108:111], v[172:175], v[212:215], v[108:111]
	v_mfma_f32_16x16x32_bf16 v[104:107], v[180:183], v[212:215], v[104:107]
	v_mfma_f32_16x16x32_bf16 v[92:95], v[172:175], v[220:223], v[92:95]
	v_mfma_f32_16x16x32_bf16 v[88:91], v[180:183], v[220:223], v[88:91]
	v_mfma_f32_16x16x32_bf16 v[76:79], v[172:175], v[228:231], v[76:79]
	v_mfma_f32_16x16x32_bf16 v[72:75], v[180:183], v[228:231], v[72:75]
	s_setprio 0
	s_setprio 1
	v_mfma_f32_16x16x32_bf16 v[116:119], v[184:187], v[200:203], v[116:119]
	v_mfma_f32_16x16x32_bf16 v[112:115], v[192:195], v[200:203], v[112:115]
	v_mfma_f32_16x16x32_bf16 v[100:103], v[184:187], v[208:211], v[100:103]
	v_mfma_f32_16x16x32_bf16 v[96:99], v[192:195], v[208:211], v[96:99]
	v_mfma_f32_16x16x32_bf16 v[84:87], v[184:187], v[216:219], v[84:87]
	v_mfma_f32_16x16x32_bf16 v[80:83], v[192:195], v[216:219], v[80:83]
	v_mfma_f32_16x16x32_bf16 v[68:71], v[184:187], v[224:227], v[68:71]
	v_mfma_f32_16x16x32_bf16 v[64:67], v[192:195], v[224:227], v[64:67]
	v_mfma_f32_16x16x32_bf16 v[116:119], v[188:191], v[204:207], v[116:119]
	v_mfma_f32_16x16x32_bf16 v[112:115], v[196:199], v[204:207], v[112:115]
	v_mfma_f32_16x16x32_bf16 v[100:103], v[188:191], v[212:215], v[100:103]
	v_mfma_f32_16x16x32_bf16 v[96:99], v[196:199], v[212:215], v[96:99]
	v_mfma_f32_16x16x32_bf16 v[84:87], v[188:191], v[220:223], v[84:87]
	v_mfma_f32_16x16x32_bf16 v[80:83], v[196:199], v[220:223], v[80:83]
	v_mfma_f32_16x16x32_bf16 v[68:71], v[188:191], v[228:231], v[68:71]
	v_mfma_f32_16x16x32_bf16 v[64:67], v[196:199], v[228:231], v[64:67]
	s_setprio 0
	s_barrier
	s_add_i32 s69, s56, s39
	v_lshl_add_u64 v[162:163], s[8:9], 0, v[130:131]
	s_mov_b32 m0, s69
	v_lshl_add_u64 v[232:233], s[8:9], 0, v[134:135]
	global_load_lds_dwordx4 v[162:163], off
	s_add_i32 m0, s69, 0x2000
	s_add_u32 s70, s8, 0x40000
	s_addc_u32 s71, s9, 0
	s_add_i32 s69, s57, s39
	global_load_lds_dwordx4 v[232:233], off
	v_lshl_add_u64 v[234:235], s[70:71], 0, v[130:131]
	s_mov_b32 m0, s69
	v_lshl_add_u64 v[236:237], s[10:11], 0, v[132:133]
	global_load_lds_dwordx4 v[234:235], off
	v_lshl_add_u64 v[234:235], s[70:71], 0, v[134:135]
	s_add_i32 m0, s69, 0x2000
	ds_read_b128 v[200:203], v170 offset:16384
	global_load_lds_dwordx4 v[234:235], off
	v_lshl_add_u64 v[234:235], s[10:11], 0, v[128:129]
	s_mov_b32 m0, s40
	ds_read_b128 v[204:207], v170 offset:17408
	global_load_lds_dwordx4 v[234:235], off
	s_mov_b32 m0, s41
	ds_read_b128 v[208:211], v170 offset:18432
	global_load_lds_dwordx4 v[236:237], off
	ds_read_b128 v[212:215], v170 offset:19456
	ds_read_b128 v[216:219], v170 offset:20480
	ds_read_b128 v[220:223], v170 offset:21504
	ds_read_b128 v[224:227], v170 offset:22528
	ds_read_b128 v[228:231], v170 offset:23552
	s_waitcnt vmcnt(8)
	s_waitcnt lgkmcnt(0)
	s_barrier
; #define PG8_STAGE(bufoff, gbase, voff) do { _Pragma("unroll") for (int _i = 0; _i < 2; ++_i) \
;         __builtin_amdgcn_global_load_lds((const unsigned*)((const char*)(gbase) + (voff)[_i]), (PG8_LAS unsigned*)(lds + (bufoff) + ldsw + _i * 8192), 16, 0, 0); } while (0)
; #define PG8_LDA(dst, b, h) do { _Pragma("unroll") for (int m = 0; m < 4; ++m) _Pragma("unroll") for (int k = 0; k < 2; ++k) dst[m][k] = *(const PG8_LAS bf16x8*)(lds + PG8_SA(b, h) + aoff + m * 2048 + k * 1024); } while (0)
; #define PG8_LDB(dst, b, h) do { _Pragma("unroll") for (int n = 0; n < 2; ++n) _Pragma("unroll") for (int k = 0; k < 2; ++k) dst[n][k] = *(const PG8_LAS bf16x8*)(lds + PG8_SB(b, h) + boff + n * 2048 + k * 1024); } while (0)
; #define PG8_MMA(ai, bj, At, Bt) do { __builtin_amdgcn_s_setprio(1); _Pragma("unroll") for (int m = 0; m < 4; ++m) _Pragma("unroll") for (int n = 0; n < 2; ++n) _Pragma("unroll") for (int k = 0; k < 2; ++k) \
;         acc[ai][bj][m][n] = __builtin_amdgcn_mfma_f32_16x16x32_bf16(Bt[n][k], At[m][k], acc[ai][bj][m][n], 0, 0, 0); __builtin_amdgcn_s_setprio(0); } while (0)
; #define PG8_WAIT_V(n) asm volatile("s_waitcnt vmcnt(" #n ")" ::: "memory")
; #define PG8_WAIT_L(n) asm volatile("s_waitcnt lgkmcnt(" #n ")" ::: "memory")
; #define PG8_BAR __builtin_amdgcn_s_barrier()
; #define PG8_SCHED __builtin_amdgcn_sched_barrier(0)
; template <class Epi, class Sched, bool ALIGN_EPI = false, bool SP2 = false>
; __device__ __forceinline__ void gemm_phase(PG8_LAS unsigned char* lds, const Gemm g, const Sched& S, const Epi& E) {
;     ...
;             PG8_WAIT_V(8); PG8_WAIT_L(0); PG8_BAR; PG8_MMA(1, 0, At, B0); PG8_MMA(1, 1, At, B1); PG8_BAR; PG8_SCHED;
;             PG8_LDB(B0, 1, 0); PG8_LDB(B1, 1, 1); PG8_SCHED; PG8_LDA(At, 1, 0); PG8_STAGE(PG8_SA(0, 1), a2 + hstep, voffA);
;             PG8_WAIT_V(8); PG8_WAIT_L(0); PG8_BAR; PG8_MMA(0, 0, At, B0); PG8_MMA(0, 1, At, B1); PG8_BAR; PG8_SCHED;
	s_setprio 1
	s_waitcnt lgkmcnt(0)
	v_mfma_f32_16x16x32_bf16 v[60:63], v[156:159], v[200:203], v[60:63]
	v_mfma_f32_16x16x32_bf16 v[56:59], v[176:179], v[200:203], v[56:59]
	v_mfma_f32_16x16x32_bf16 v[44:47], v[156:159], v[208:211], v[44:47]
	v_mfma_f32_16x16x32_bf16 v[40:43], v[176:179], v[208:211], v[40:43]
	v_mfma_f32_16x16x32_bf16 v[28:31], v[156:159], v[216:219], v[28:31]
	v_mfma_f32_16x16x32_bf16 v[24:27], v[176:179], v[216:219], v[24:27]
	v_mfma_f32_16x16x32_bf16 v[12:15], v[156:159], v[224:227], v[12:15]
	v_mfma_f32_16x16x32_bf16 v[8:11], v[176:179], v[224:227], v[8:11]
	v_mfma_f32_16x16x32_bf16 v[60:63], v[172:175], v[204:207], v[60:63]
	v_mfma_f32_16x16x32_bf16 v[56:59], v[180:183], v[204:207], v[56:59]
	v_mfma_f32_16x16x32_bf16 v[44:47], v[172:175], v[212:215], v[44:47]
	v_mfma_f32_16x16x32_bf16 v[40:43], v[180:183], v[212:215], v[40:43]
	v_mfma_f32_16x16x32_bf16 v[28:31], v[172:175], v[220:223], v[28:31]
	v_mfma_f32_16x16x32_bf16 v[24:27], v[180:183], v[220:223], v[24:27]
	v_mfma_f32_16x16x32_bf16 v[12:15], v[172:175], v[228:231], v[12:15]
	v_mfma_f32_16x16x32_bf16 v[8:11], v[180:183], v[228:231], v[8:11]
	s_setprio 0
	s_setprio 1
	v_mfma_f32_16x16x32_bf16 v[52:55], v[184:187], v[200:203], v[52:55]
	v_mfma_f32_16x16x32_bf16 v[48:51], v[192:195], v[200:203], v[48:51]
	v_mfma_f32_16x16x32_bf16 v[36:39], v[184:187], v[208:211], v[36:39]
	v_mfma_f32_16x16x32_bf16 v[32:35], v[192:195], v[208:211], v[32:35]
	v_mfma_f32_16x16x32_bf16 v[20:23], v[184:187], v[216:219], v[20:23]
	v_mfma_f32_16x16x32_bf16 v[16:19], v[192:195], v[216:219], v[16:19]
	v_mfma_f32_16x16x32_bf16 v[4:7], v[184:187], v[224:227], v[4:7]
	v_mfma_f32_16x16x32_bf16 v[0:3], v[192:195], v[224:227], v[0:3]
	v_mfma_f32_16x16x32_bf16 v[52:55], v[188:191], v[204:207], v[52:55]
	v_mfma_f32_16x16x32_bf16 v[48:51], v[196:199], v[204:207], v[48:51]
	v_mfma_f32_16x16x32_bf16 v[36:39], v[188:191], v[212:215], v[36:39]
	v_mfma_f32_16x16x32_bf16 v[32:35], v[196:199], v[212:215], v[32:35]
	v_mfma_f32_16x16x32_bf16 v[20:23], v[188:191], v[220:223], v[20:23]
	v_mfma_f32_16x16x32_bf16 v[16:19], v[196:199], v[220:223], v[16:19]
	v_mfma_f32_16x16x32_bf16 v[4:7], v[188:191], v[228:231], v[4:7]
	v_mfma_f32_16x16x32_bf16 v[0:3], v[196:199], v[228:231], v[0:3]
	s_setprio 0
	s_barrier
	s_add_i32 s69, 0, 0x18000
	s_add_i32 s70, 0, 0x1c000
	s_add_u32 s10, s10, 0x40000
	s_addc_u32 s11, s11, 0
	s_mov_b32 m0, s42
	v_lshl_add_u64 v[238:239], s[10:11], 0, v[128:129]
	global_load_lds_dwordx4 v[238:239], off
	v_lshl_add_u64 v[238:239], s[10:11], 0, v[132:133]
	s_mov_b32 m0, s43
	v_add_u32_e32 v160, s69, v139
	global_load_lds_dwordx4 v[238:239], off
	ds_read_b128 v[156:159], v160
	ds_read_b128 v[172:175], v160 offset:1024
	ds_read_b128 v[176:179], v160 offset:2048
	ds_read_b128 v[180:183], v160 offset:3072
	v_add_u32_e32 v160, s70, v139
	ds_read_b128 v[184:187], v160
	ds_read_b128 v[188:191], v160 offset:1024
	ds_read_b128 v[192:195], v160 offset:2048
	ds_read_b128 v[196:199], v160 offset:3072
	ds_read_b128 v[200:203], v170 offset:32768
	ds_read_b128 v[204:207], v170 offset:33792
	ds_read_b128 v[208:211], v170 offset:34816
	ds_read_b128 v[212:215], v170 offset:35840
	ds_read_b128 v[216:219], v170 offset:36864
	ds_read_b128 v[220:223], v170 offset:37888
	ds_read_b128 v[224:227], v170 offset:38912
	ds_read_b128 v[228:231], v170 offset:39936
	s_waitcnt vmcnt(8)
	s_waitcnt lgkmcnt(0)
	s_barrier
	s_setprio 1
	s_waitcnt lgkmcnt(0)
	v_mfma_f32_16x16x32_bf16 v[124:127], v[156:159], v[200:203], v[124:127]
	v_mfma_f32_16x16x32_bf16 v[120:123], v[176:179], v[200:203], v[120:123]
	v_mfma_f32_16x16x32_bf16 v[108:111], v[156:159], v[208:211], v[108:111]
	v_mfma_f32_16x16x32_bf16 v[104:107], v[176:179], v[208:211], v[104:107]
	v_mfma_f32_16x16x32_bf16 v[92:95], v[156:159], v[216:219], v[92:95]
	v_mfma_f32_16x16x32_bf16 v[88:91], v[176:179], v[216:219], v[88:91]
	v_mfma_f32_16x16x32_bf16 v[76:79], v[156:159], v[224:227], v[76:79]
	v_mfma_f32_16x16x32_bf16 v[72:75], v[176:179], v[224:227], v[72:75]
	v_mfma_f32_16x16x32_bf16 v[124:127], v[172:175], v[204:207], v[124:127]
	v_mfma_f32_16x16x32_bf16 v[120:123], v[180:183], v[204:207], v[120:123]
	v_mfma_f32_16x16x32_bf16 v[108:111], v[172:175], v[212:215], v[108:111]
	v_mfma_f32_16x16x32_bf16 v[104:107], v[180:183], v[212:215], v[104:107]
	v_mfma_f32_16x16x32_bf16 v[92:95], v[172:175], v[220:223], v[92:95]
	v_mfma_f32_16x16x32_bf16 v[88:91], v[180:183], v[220:223], v[88:91]
	v_mfma_f32_16x16x32_bf16 v[76:79], v[172:175], v[228:231], v[76:79]
	v_mfma_f32_16x16x32_bf16 v[72:75], v[180:183], v[228:231], v[72:75]
	s_setprio 0
	s_setprio 1
	v_mfma_f32_16x16x32_bf16 v[116:119], v[184:187], v[200:203], v[116:119]
	v_mfma_f32_16x16x32_bf16 v[112:115], v[192:195], v[200:203], v[112:115]
	v_mfma_f32_16x16x32_bf16 v[100:103], v[184:187], v[208:211], v[100:103]
	v_mfma_f32_16x16x32_bf16 v[96:99], v[192:195], v[208:211], v[96:99]
	v_mfma_f32_16x16x32_bf16 v[84:87], v[184:187], v[216:219], v[84:87]
	v_mfma_f32_16x16x32_bf16 v[80:83], v[192:195], v[216:219], v[80:83]
	v_mfma_f32_16x16x32_bf16 v[68:71], v[184:187], v[224:227], v[68:71]
	v_mfma_f32_16x16x32_bf16 v[64:67], v[192:195], v[224:227], v[64:67]
	v_mfma_f32_16x16x32_bf16 v[116:119], v[188:191], v[204:207], v[116:119]
	v_mfma_f32_16x16x32_bf16 v[112:115], v[196:199], v[204:207], v[112:115]
	v_mfma_f32_16x16x32_bf16 v[100:103], v[188:191], v[212:215], v[100:103]
	v_mfma_f32_16x16x32_bf16 v[96:99], v[196:199], v[212:215], v[96:99]
	v_mfma_f32_16x16x32_bf16 v[84:87], v[188:191], v[220:223], v[84:87]
	v_mfma_f32_16x16x32_bf16 v[80:83], v[196:199], v[220:223], v[80:83]
	v_mfma_f32_16x16x32_bf16 v[68:71], v[188:191], v[228:231], v[68:71]
	v_mfma_f32_16x16x32_bf16 v[64:67], v[196:199], v[228:231], v[64:67]
	s_setprio 0
	s_barrier
; #define PG8_STAGE(bufoff, gbase, voff) do { _Pragma("unroll") for (int _i = 0; _i < 2; ++_i) \
;         __builtin_amdgcn_global_load_lds((const unsigned*)((const char*)(gbase) + (voff)[_i]), (PG8_LAS unsigned*)(lds + (bufoff) + ldsw + _i * 8192), 16, 0, 0); } while (0)
; #define PG8_LDA(dst, b, h) do { _Pragma("unroll") for (int m = 0; m < 4; ++m) _Pragma("unroll") for (int k = 0; k < 2; ++k) dst[m][k] = *(const PG8_LAS bf16x8*)(lds + PG8_SA(b, h) + aoff + m * 2048 + k * 1024); } while (0)
; #define PG8_MMA(ai, bj, At, Bt) do { __builtin_amdgcn_s_setprio(1); _Pragma("unroll") for (int m = 0; m < 4; ++m) _Pragma("unroll") for (int n = 0; n < 2; ++n) _Pragma("unroll") for (int k = 0; k < 2; ++k) \
;         acc[ai][bj][m][n] = __builtin_amdgcn_mfma_f32_16x16x32_bf16(Bt[n][k], At[m][k], acc[ai][bj][m][n], 0, 0, 0); __builtin_amdgcn_s_setprio(0); } while (0)
; #define PG8_WAIT_V(n) asm volatile("s_waitcnt vmcnt(" #n ")" ::: "memory")
; #define PG8_WAIT_L(n) asm volatile("s_waitcnt lgkmcnt(" #n ")" ::: "memory")
; #define PG8_BAR __builtin_amdgcn_s_barrier()
; #define PG8_SCHED __builtin_amdgcn_sched_barrier(0)
; template <class Epi, class Sched, bool ALIGN_EPI = false, bool SP2 = false>
; __device__ __forceinline__ void gemm_phase(PG8_LAS unsigned char* lds, const Gemm g, const Sched& S, const Epi& E) {
;     ...
;             PG8_LDA(At, 1, 1); PG8_STAGE(PG8_SB(1, 0), b3, voffB); PG8_STAGE(PG8_SB(1, 1), b3 + hstep, voffB); PG8_STAGE(PG8_SA(1, 0), a3, voffA);
;             PG8_WAIT_V(8); PG8_WAIT_L(0); PG8_BAR; PG8_MMA(1, 0, At, B0); PG8_MMA(1, 1, At, B1); PG8_BAR; PG8_SCHED;
;     ...
;         if constexpr (ALIGN_EPI) { if (wr == 0) PG8_BAR; }
	s_add_i32 s10, s69, s39
	v_lshl_add_u64 v[162:163], v[162:163], 0, s[18:19]
	s_mov_b32 m0, s10
	ds_read_b128 v[200:203], v170 offset:49152
	global_load_lds_dwordx4 v[162:163], off
	s_add_i32 m0, s10, 0x2000
	s_add_u32 s8, s8, 0x40080
	v_lshl_add_u64 v[162:163], v[232:233], 0, s[18:19]
	s_addc_u32 s9, s9, 0
	s_add_i32 s10, s70, s39
	global_load_lds_dwordx4 v[162:163], off
	v_lshl_add_u64 v[162:163], s[8:9], 0, v[130:131]
	s_mov_b32 m0, s10
	ds_read_b128 v[204:207], v170 offset:50176
	global_load_lds_dwordx4 v[162:163], off
	v_lshl_add_u64 v[162:163], s[8:9], 0, v[134:135]
	s_add_i32 m0, s10, 0x2000
	ds_read_b128 v[208:211], v170 offset:51200
	global_load_lds_dwordx4 v[162:163], off
	v_lshl_add_u64 v[162:163], v[234:235], 0, s[18:19]
	s_mov_b32 m0, s45
	ds_read_b128 v[212:215], v170 offset:52224
	global_load_lds_dwordx4 v[162:163], off
	v_lshl_add_u64 v[162:163], v[236:237], 0, s[18:19]
	s_mov_b32 m0, s50
	ds_read_b128 v[216:219], v170 offset:53248
	global_load_lds_dwordx4 v[162:163], off
	ds_read_b128 v[220:223], v170 offset:54272
	ds_read_b128 v[224:227], v170 offset:55296
	ds_read_b128 v[228:231], v170 offset:56320
	s_waitcnt vmcnt(8)
	s_waitcnt lgkmcnt(0)
	s_barrier
	s_setprio 1
	s_waitcnt lgkmcnt(0)
	v_mfma_f32_16x16x32_bf16 v[60:63], v[156:159], v[200:203], v[60:63]
	v_mfma_f32_16x16x32_bf16 v[56:59], v[176:179], v[200:203], v[56:59]
	v_mfma_f32_16x16x32_bf16 v[44:47], v[156:159], v[208:211], v[44:47]
	v_mfma_f32_16x16x32_bf16 v[40:43], v[176:179], v[208:211], v[40:43]
	v_mfma_f32_16x16x32_bf16 v[28:31], v[156:159], v[216:219], v[28:31]
	v_mfma_f32_16x16x32_bf16 v[24:27], v[176:179], v[216:219], v[24:27]
	v_mfma_f32_16x16x32_bf16 v[12:15], v[156:159], v[224:227], v[12:15]
	v_mfma_f32_16x16x32_bf16 v[8:11], v[176:179], v[224:227], v[8:11]
	v_mfma_f32_16x16x32_bf16 v[60:63], v[172:175], v[204:207], v[60:63]
	v_mfma_f32_16x16x32_bf16 v[56:59], v[180:183], v[204:207], v[56:59]
	v_mfma_f32_16x16x32_bf16 v[44:47], v[172:175], v[212:215], v[44:47]
	v_mfma_f32_16x16x32_bf16 v[40:43], v[180:183], v[212:215], v[40:43]
	v_mfma_f32_16x16x32_bf16 v[28:31], v[172:175], v[220:223], v[28:31]
	v_mfma_f32_16x16x32_bf16 v[24:27], v[180:183], v[220:223], v[24:27]
	v_mfma_f32_16x16x32_bf16 v[12:15], v[172:175], v[228:231], v[12:15]
	v_mfma_f32_16x16x32_bf16 v[8:11], v[180:183], v[228:231], v[8:11]
	s_setprio 0
	s_setprio 1
	v_mfma_f32_16x16x32_bf16 v[52:55], v[184:187], v[200:203], v[52:55]
	v_mfma_f32_16x16x32_bf16 v[48:51], v[192:195], v[200:203], v[48:51]
	v_mfma_f32_16x16x32_bf16 v[36:39], v[184:187], v[208:211], v[36:39]
	v_mfma_f32_16x16x32_bf16 v[32:35], v[192:195], v[208:211], v[32:35]
	v_mfma_f32_16x16x32_bf16 v[20:23], v[184:187], v[216:219], v[20:23]
	v_mfma_f32_16x16x32_bf16 v[16:19], v[192:195], v[216:219], v[16:19]
	v_mfma_f32_16x16x32_bf16 v[4:7], v[184:187], v[224:227], v[4:7]
	v_mfma_f32_16x16x32_bf16 v[0:3], v[192:195], v[224:227], v[0:3]
	v_mfma_f32_16x16x32_bf16 v[52:55], v[188:191], v[204:207], v[52:55]
	v_mfma_f32_16x16x32_bf16 v[48:51], v[196:199], v[204:207], v[48:51]
	v_mfma_f32_16x16x32_bf16 v[36:39], v[188:191], v[212:215], v[36:39]
	v_mfma_f32_16x16x32_bf16 v[32:35], v[196:199], v[212:215], v[32:35]
	v_mfma_f32_16x16x32_bf16 v[20:23], v[188:191], v[220:223], v[20:23]
	v_mfma_f32_16x16x32_bf16 v[16:19], v[196:199], v[220:223], v[16:19]
	v_mfma_f32_16x16x32_bf16 v[4:7], v[188:191], v[228:231], v[4:7]
	v_mfma_f32_16x16x32_bf16 v[0:3], v[196:199], v[228:231], v[0:3]
	s_setprio 0
	s_barrier
	s_add_i32 s68, s68, 2
	s_add_u32 s6, s6, 0x100
	s_addc_u32 s7, s7, 0
	s_add_u32 s52, s52, 0x100
	s_addc_u32 s53, s53, 0
	s_cmp_gt_u32 s68, 13
	s_cbranch_scc0 .LBB0_1295
	s_nop 0
	s_nop 0
	s_nop 0
	s_nop 0
	s_nop 0
	s_nop 0
	s_nop 0
	s_nop 0
	s_nop 0
	s_and_b64 vcc, exec, s[20:21]
	s_cbranch_vccz .LBB0_1298
	s_barrier

; #define PG8_STAGE(bufoff, gbase, voff) do { _Pragma("unroll") for (int _i = 0; _i < 2; ++_i) \
;         __builtin_amdgcn_global_load_lds((const unsigned*)((const char*)(gbase) + (voff)[_i]), (PG8_LAS unsigned*)(lds + (bufoff) + ldsw + _i * 8192), 16, 0, 0); } while (0)
; #define PG8_LDA(dst, b, h) do { _Pragma("unroll") for (int m = 0; m < 4; ++m) _Pragma("unroll") for (int k = 0; k < 2; ++k) dst[m][k] = *(const PG8_LAS bf16x8*)(lds + PG8_SA(b, h) + aoff + m * 2048 + k * 1024); } while (0)
; #define PG8_LDB(dst, b, h) do { _Pragma("unroll") for (int n = 0; n < 2; ++n) _Pragma("unroll") for (int k = 0; k < 2; ++k) dst[n][k] = *(const PG8_LAS bf16x8*)(lds + PG8_SB(b, h) + boff + n * 2048 + k * 1024); } while (0)
; #define PG8_MMA(ai, bj, At, Bt) do { __builtin_amdgcn_s_setprio(1); _Pragma("unroll") for (int m = 0; m < 4; ++m) _Pragma("unroll") for (int n = 0; n < 2; ++n) _Pragma("unroll") for (int k = 0; k < 2; ++k) \
;         acc[ai][bj][m][n] = __builtin_amdgcn_mfma_f32_16x16x32_bf16(Bt[n][k], At[m][k], acc[ai][bj][m][n], 0, 0, 0); __builtin_amdgcn_s_setprio(0); } while (0)
; #define PG8_WAIT_V(n) asm volatile("s_waitcnt vmcnt(" #n ")" ::: "memory")
; #define PG8_WAIT_L(n) asm volatile("s_waitcnt lgkmcnt(" #n ")" ::: "memory")
; template <class Epi, class Sched, bool ALIGN_EPI = false, bool SP2 = false>
; __device__ __forceinline__ void gemm_phase(PG8_LAS unsigned char* lds, const Gemm g, const Sched& S, const Epi& E) {
;     ...
;             const bool last = (t == nt - 2);
;             const char* a1 = cA + (size_t)(t + 1) * kstep;
;             const char* a2 = last ? nA : cA + (size_t)(t + 2) * kstep; const char* b2 = last ? nB : cB + (size_t)(t + 2) * kstep;
;             const char* a3 = a2 + kstep; const char* b3 = b2 + kstep;
;             if (last && has_next) S.a_ready(nxt);
;             if constexpr (SP2) {
;             PG8_LDB(B0, 0, 0); PG8_LDB(B1, 0, 1); PG8_SCHED; PG8_LDA(At, 0, 0); PG8_STAGE(PG8_SA(1, 1), a1 + hstep, voffA);
;             PG8_WAIT_V(8); PG8_WAIT_L(0); PG8_BAR; PG8_MMA(0, 0, At, B0); PG8_MMA(0, 1, At, B1); PG8_BAR; PG8_SCHED;
;             PG8_LDA(At, 0, 1); PG8_STAGE(PG8_SB(0, 0), b2, voffB); PG8_STAGE(PG8_SB(0, 1), b2 + hstep, voffB); PG8_STAGE(PG8_SA(0, 0), a2, voffA);
;             PG8_WAIT_V(8); PG8_WAIT_L(0); PG8_BAR; PG8_MMA(1, 0, At, B0); PG8_MMA(1, 1, At, B1); PG8_BAR; PG8_SCHED;
.LBB0_1319:
	v_lshl_add_u64 v[216:217], s[30:31], 0, v[128:129]
	s_add_i32 m0, s29, 0xc000
	ds_read_b128 v[144:147], v149
	global_load_lds_dwordx4 v[216:217], off
	v_lshl_add_u64 v[216:217], s[30:31], 0, v[130:131]
	s_add_i32 m0, s29, 0xe000
	ds_read_b128 v[152:155], v149 offset:1024
	global_load_lds_dwordx4 v[216:217], off
	s_add_u32 s34, s30, 0xfffe0080
	s_addc_u32 s35, s31, -1
	s_cmp_eq_u32 s69, 4
	s_cselect_b32 s37, s23, s35
	s_cselect_b32 s36, s53, s34
	s_cselect_b32 s35, s21, s68
	s_cselect_b32 s34, s62, s63
	ds_read_b128 v[160:163], v149 offset:2048
	ds_read_b128 v[164:167], v149 offset:3072
	ds_read_b128 v[168:171], v151
	ds_read_b128 v[172:175], v151 offset:1024
	ds_read_b128 v[176:179], v151 offset:2048
	ds_read_b128 v[180:183], v151 offset:3072
	ds_read_b128 v[184:187], v159
	ds_read_b128 v[188:191], v159 offset:1024
	ds_read_b128 v[192:195], v159 offset:2048
	ds_read_b128 v[196:199], v159 offset:3072
	ds_read_b128 v[200:203], v159 offset:4096
	ds_read_b128 v[204:207], v159 offset:5120
	ds_read_b128 v[208:211], v159 offset:6144
	ds_read_b128 v[212:215], v159 offset:7168
	s_waitcnt vmcnt(8)
	s_waitcnt lgkmcnt(0)
	s_barrier
	s_setprio 1
	s_waitcnt lgkmcnt(0)
	v_mfma_f32_16x16x32_bf16 v[124:127], v[144:147], v[184:187], v[124:127]
	v_mfma_f32_16x16x32_bf16 v[120:123], v[160:163], v[184:187], v[120:123]
	v_mfma_f32_16x16x32_bf16 v[108:111], v[144:147], v[192:195], v[108:111]
	v_mfma_f32_16x16x32_bf16 v[104:107], v[160:163], v[192:195], v[104:107]
	v_mfma_f32_16x16x32_bf16 v[92:95], v[144:147], v[200:203], v[92:95]
	v_mfma_f32_16x16x32_bf16 v[88:91], v[160:163], v[200:203], v[88:91]
	v_mfma_f32_16x16x32_bf16 v[76:79], v[144:147], v[208:211], v[76:79]
	v_mfma_f32_16x16x32_bf16 v[72:75], v[160:163], v[208:211], v[72:75]
	v_mfma_f32_16x16x32_bf16 v[124:127], v[152:155], v[188:191], v[124:127]
	v_mfma_f32_16x16x32_bf16 v[120:123], v[164:167], v[188:191], v[120:123]
	v_mfma_f32_16x16x32_bf16 v[108:111], v[152:155], v[196:199], v[108:111]
	v_mfma_f32_16x16x32_bf16 v[104:107], v[164:167], v[196:199], v[104:107]
	v_mfma_f32_16x16x32_bf16 v[92:95], v[152:155], v[204:207], v[92:95]
	v_mfma_f32_16x16x32_bf16 v[88:91], v[164:167], v[204:207], v[88:91]
	v_mfma_f32_16x16x32_bf16 v[76:79], v[152:155], v[212:215], v[76:79]
	v_mfma_f32_16x16x32_bf16 v[72:75], v[164:167], v[212:215], v[72:75]
	s_setprio 0
	s_setprio 1
	v_mfma_f32_16x16x32_bf16 v[116:119], v[168:171], v[184:187], v[116:119]
	v_mfma_f32_16x16x32_bf16 v[112:115], v[176:179], v[184:187], v[112:115]
	v_mfma_f32_16x16x32_bf16 v[100:103], v[168:171], v[192:195], v[100:103]
	v_mfma_f32_16x16x32_bf16 v[96:99], v[176:179], v[192:195], v[96:99]
	v_mfma_f32_16x16x32_bf16 v[84:87], v[168:171], v[200:203], v[84:87]
	v_mfma_f32_16x16x32_bf16 v[80:83], v[176:179], v[200:203], v[80:83]
	v_mfma_f32_16x16x32_bf16 v[68:71], v[168:171], v[208:211], v[68:71]
	v_mfma_f32_16x16x32_bf16 v[64:67], v[176:179], v[208:211], v[64:67]
	v_mfma_f32_16x16x32_bf16 v[116:119], v[172:175], v[188:191], v[116:119]
	v_mfma_f32_16x16x32_bf16 v[112:115], v[180:183], v[188:191], v[112:115]
	v_mfma_f32_16x16x32_bf16 v[100:103], v[172:175], v[196:199], v[100:103]
	v_mfma_f32_16x16x32_bf16 v[96:99], v[180:183], v[196:199], v[96:99]
	v_mfma_f32_16x16x32_bf16 v[84:87], v[172:175], v[204:207], v[84:87]
	v_mfma_f32_16x16x32_bf16 v[80:83], v[180:183], v[204:207], v[80:83]
	v_mfma_f32_16x16x32_bf16 v[68:71], v[172:175], v[212:215], v[68:71]
	v_mfma_f32_16x16x32_bf16 v[64:67], v[180:183], v[212:215], v[64:67]
	s_setprio 0
	s_barrier
	s_add_i32 s70, s51, s39
	v_lshl_add_u64 v[216:217], s[34:35], 0, v[138:139]
	s_mov_b32 m0, s70
	v_lshl_add_u64 v[218:219], s[34:35], 0, v[142:143]
	global_load_lds_dwordx4 v[216:217], off
	s_add_i32 m0, s70, 0x2000
	s_add_u32 s70, s34, 0x20000
	s_addc_u32 s71, s35, 0
	s_add_i32 s72, s56, s39
	global_load_lds_dwordx4 v[218:219], off
	v_lshl_add_u64 v[220:221], s[70:71], 0, v[138:139]
	s_mov_b32 m0, s72
	v_lshl_add_u64 v[222:223], s[36:37], 0, v[140:141]
	global_load_lds_dwordx4 v[220:221], off
	v_lshl_add_u64 v[220:221], s[70:71], 0, v[142:143]
	s_add_i32 m0, s72, 0x2000
	ds_read_b128 v[184:187], v159 offset:16384
	global_load_lds_dwordx4 v[220:221], off
	v_lshl_add_u64 v[220:221], s[36:37], 0, v[136:137]
	s_mov_b32 m0, s29
	ds_read_b128 v[188:191], v159 offset:17408
	global_load_lds_dwordx4 v[220:221], off
	s_mov_b32 m0, s40
	ds_read_b128 v[192:195], v159 offset:18432
	global_load_lds_dwordx4 v[222:223], off
	ds_read_b128 v[196:199], v159 offset:19456
	ds_read_b128 v[200:203], v159 offset:20480
	ds_read_b128 v[204:207], v159 offset:21504
	ds_read_b128 v[208:211], v159 offset:22528
	ds_read_b128 v[212:215], v159 offset:23552
	s_waitcnt vmcnt(8)
	s_waitcnt lgkmcnt(0)
	s_barrier
; #define PG8_STAGE(bufoff, gbase, voff) do { _Pragma("unroll") for (int _i = 0; _i < 2; ++_i) \
;         __builtin_amdgcn_global_load_lds((const unsigned*)((const char*)(gbase) + (voff)[_i]), (PG8_LAS unsigned*)(lds + (bufoff) + ldsw + _i * 8192), 16, 0, 0); } while (0)
; #define PG8_LDA(dst, b, h) do { _Pragma("unroll") for (int m = 0; m < 4; ++m) _Pragma("unroll") for (int k = 0; k < 2; ++k) dst[m][k] = *(const PG8_LAS bf16x8*)(lds + PG8_SA(b, h) + aoff + m * 2048 + k * 1024); } while (0)
; #define PG8_LDB(dst, b, h) do { _Pragma("unroll") for (int n = 0; n < 2; ++n) _Pragma("unroll") for (int k = 0; k < 2; ++k) dst[n][k] = *(const PG8_LAS bf16x8*)(lds + PG8_SB(b, h) + boff + n * 2048 + k * 1024); } while (0)
; #define PG8_MMA(ai, bj, At, Bt) do { __builtin_amdgcn_s_setprio(1); _Pragma("unroll") for (int m = 0; m < 4; ++m) _Pragma("unroll") for (int n = 0; n < 2; ++n) _Pragma("unroll") for (int k = 0; k < 2; ++k) \
;         acc[ai][bj][m][n] = __builtin_amdgcn_mfma_f32_16x16x32_bf16(Bt[n][k], At[m][k], acc[ai][bj][m][n], 0, 0, 0); __builtin_amdgcn_s_setprio(0); } while (0)
; #define PG8_WAIT_V(n) asm volatile("s_waitcnt vmcnt(" #n ")" ::: "memory")
; #define PG8_WAIT_L(n) asm volatile("s_waitcnt lgkmcnt(" #n ")" ::: "memory")
; #define PG8_BAR __builtin_amdgcn_s_barrier()
; #define PG8_SCHED __builtin_amdgcn_sched_barrier(0)
; template <class Epi, class Sched, bool ALIGN_EPI = false, bool SP2 = false>
; __device__ __forceinline__ void gemm_phase(PG8_LAS unsigned char* lds, const Gemm g, const Sched& S, const Epi& E) {
;     ...
;             PG8_WAIT_V(8); PG8_WAIT_L(0); PG8_BAR; PG8_MMA(1, 0, At, B0); PG8_MMA(1, 1, At, B1); PG8_BAR; PG8_SCHED;
;             PG8_LDB(B0, 1, 0); PG8_LDB(B1, 1, 1); PG8_SCHED; PG8_LDA(At, 1, 0); PG8_STAGE(PG8_SA(0, 1), a2 + hstep, voffA);
;             PG8_WAIT_V(8); PG8_WAIT_L(0); PG8_BAR; PG8_MMA(0, 0, At, B0); PG8_MMA(0, 1, At, B1); PG8_BAR; PG8_SCHED;
	s_setprio 1
	s_waitcnt lgkmcnt(0)
	v_mfma_f32_16x16x32_bf16 v[60:63], v[144:147], v[184:187], v[60:63]
	v_mfma_f32_16x16x32_bf16 v[56:59], v[160:163], v[184:187], v[56:59]
	v_mfma_f32_16x16x32_bf16 v[44:47], v[144:147], v[192:195], v[44:47]
	v_mfma_f32_16x16x32_bf16 v[40:43], v[160:163], v[192:195], v[40:43]
	v_mfma_f32_16x16x32_bf16 v[28:31], v[144:147], v[200:203], v[28:31]
	v_mfma_f32_16x16x32_bf16 v[24:27], v[160:163], v[200:203], v[24:27]
	v_mfma_f32_16x16x32_bf16 v[12:15], v[144:147], v[208:211], v[12:15]
	v_mfma_f32_16x16x32_bf16 v[8:11], v[160:163], v[208:211], v[8:11]
	v_mfma_f32_16x16x32_bf16 v[60:63], v[152:155], v[188:191], v[60:63]
	v_mfma_f32_16x16x32_bf16 v[56:59], v[164:167], v[188:191], v[56:59]
	v_mfma_f32_16x16x32_bf16 v[44:47], v[152:155], v[196:199], v[44:47]
	v_mfma_f32_16x16x32_bf16 v[40:43], v[164:167], v[196:199], v[40:43]
	v_mfma_f32_16x16x32_bf16 v[28:31], v[152:155], v[204:207], v[28:31]
	v_mfma_f32_16x16x32_bf16 v[24:27], v[164:167], v[204:207], v[24:27]
	v_mfma_f32_16x16x32_bf16 v[12:15], v[152:155], v[212:215], v[12:15]
	v_mfma_f32_16x16x32_bf16 v[8:11], v[164:167], v[212:215], v[8:11]
	s_setprio 0
	s_setprio 1
	v_mfma_f32_16x16x32_bf16 v[52:55], v[168:171], v[184:187], v[52:55]
	v_mfma_f32_16x16x32_bf16 v[48:51], v[176:179], v[184:187], v[48:51]
	v_mfma_f32_16x16x32_bf16 v[36:39], v[168:171], v[192:195], v[36:39]
	v_mfma_f32_16x16x32_bf16 v[32:35], v[176:179], v[192:195], v[32:35]
	v_mfma_f32_16x16x32_bf16 v[20:23], v[168:171], v[200:203], v[20:23]
	v_mfma_f32_16x16x32_bf16 v[16:19], v[176:179], v[200:203], v[16:19]
	v_mfma_f32_16x16x32_bf16 v[4:7], v[168:171], v[208:211], v[4:7]
	v_mfma_f32_16x16x32_bf16 v[0:3], v[176:179], v[208:211], v[0:3]
	v_mfma_f32_16x16x32_bf16 v[52:55], v[172:175], v[188:191], v[52:55]
	v_mfma_f32_16x16x32_bf16 v[48:51], v[180:183], v[188:191], v[48:51]
	v_mfma_f32_16x16x32_bf16 v[36:39], v[172:175], v[196:199], v[36:39]
	v_mfma_f32_16x16x32_bf16 v[32:35], v[180:183], v[196:199], v[32:35]
	v_mfma_f32_16x16x32_bf16 v[20:23], v[172:175], v[204:207], v[20:23]
	v_mfma_f32_16x16x32_bf16 v[16:19], v[180:183], v[204:207], v[16:19]
	v_mfma_f32_16x16x32_bf16 v[4:7], v[172:175], v[212:215], v[4:7]
	v_mfma_f32_16x16x32_bf16 v[0:3], v[180:183], v[212:215], v[0:3]
	s_setprio 0
	s_barrier
	s_add_i32 s70, 0, 0x18000
	s_add_i32 s71, 0, 0x1c000
	s_add_u32 s36, s36, 0x20000
	s_addc_u32 s37, s37, 0
	s_mov_b32 m0, s41
	v_lshl_add_u64 v[224:225], s[36:37], 0, v[136:137]
	global_load_lds_dwordx4 v[224:225], off
	v_lshl_add_u64 v[224:225], s[36:37], 0, v[140:141]
	s_mov_b32 m0, s42
	v_add_u32_e32 v164, s70, v157
	global_load_lds_dwordx4 v[224:225], off
	v_add_u32_e32 v180, s71, v157
	ds_read_b128 v[144:147], v164
	ds_read_b128 v[152:155], v164 offset:1024
	ds_read_b128 v[160:163], v164 offset:2048
	ds_read_b128 v[164:167], v164 offset:3072
	ds_read_b128 v[168:171], v180
	ds_read_b128 v[172:175], v180 offset:1024
	ds_read_b128 v[176:179], v180 offset:2048
	ds_read_b128 v[180:183], v180 offset:3072
	ds_read_b128 v[184:187], v159 offset:32768
	ds_read_b128 v[188:191], v159 offset:33792
	ds_read_b128 v[192:195], v159 offset:34816
	ds_read_b128 v[196:199], v159 offset:35840
	ds_read_b128 v[200:203], v159 offset:36864
	ds_read_b128 v[204:207], v159 offset:37888
	ds_read_b128 v[208:211], v159 offset:38912
	ds_read_b128 v[212:215], v159 offset:39936
	s_waitcnt vmcnt(8)
	s_waitcnt lgkmcnt(0)
	s_barrier
	s_setprio 1
	s_waitcnt lgkmcnt(0)
	v_mfma_f32_16x16x32_bf16 v[124:127], v[144:147], v[184:187], v[124:127]
	v_mfma_f32_16x16x32_bf16 v[120:123], v[160:163], v[184:187], v[120:123]
	v_mfma_f32_16x16x32_bf16 v[108:111], v[144:147], v[192:195], v[108:111]
	v_mfma_f32_16x16x32_bf16 v[104:107], v[160:163], v[192:195], v[104:107]
	v_mfma_f32_16x16x32_bf16 v[92:95], v[144:147], v[200:203], v[92:95]
	v_mfma_f32_16x16x32_bf16 v[88:91], v[160:163], v[200:203], v[88:91]
	v_mfma_f32_16x16x32_bf16 v[76:79], v[144:147], v[208:211], v[76:79]
	v_mfma_f32_16x16x32_bf16 v[72:75], v[160:163], v[208:211], v[72:75]
	v_mfma_f32_16x16x32_bf16 v[124:127], v[152:155], v[188:191], v[124:127]
	v_mfma_f32_16x16x32_bf16 v[120:123], v[164:167], v[188:191], v[120:123]
	v_mfma_f32_16x16x32_bf16 v[108:111], v[152:155], v[196:199], v[108:111]
	v_mfma_f32_16x16x32_bf16 v[104:107], v[164:167], v[196:199], v[104:107]
	v_mfma_f32_16x16x32_bf16 v[92:95], v[152:155], v[204:207], v[92:95]
	v_mfma_f32_16x16x32_bf16 v[88:91], v[164:167], v[204:207], v[88:91]
	v_mfma_f32_16x16x32_bf16 v[76:79], v[152:155], v[212:215], v[76:79]
	v_mfma_f32_16x16x32_bf16 v[72:75], v[164:167], v[212:215], v[72:75]
	s_setprio 0
	s_setprio 1
	v_mfma_f32_16x16x32_bf16 v[116:119], v[168:171], v[184:187], v[116:119]
	v_mfma_f32_16x16x32_bf16 v[112:115], v[176:179], v[184:187], v[112:115]
	v_mfma_f32_16x16x32_bf16 v[100:103], v[168:171], v[192:195], v[100:103]
	v_mfma_f32_16x16x32_bf16 v[96:99], v[176:179], v[192:195], v[96:99]
	v_mfma_f32_16x16x32_bf16 v[84:87], v[168:171], v[200:203], v[84:87]
	v_mfma_f32_16x16x32_bf16 v[80:83], v[176:179], v[200:203], v[80:83]
	v_mfma_f32_16x16x32_bf16 v[68:71], v[168:171], v[208:211], v[68:71]
	v_mfma_f32_16x16x32_bf16 v[64:67], v[176:179], v[208:211], v[64:67]
	v_mfma_f32_16x16x32_bf16 v[116:119], v[172:175], v[188:191], v[116:119]
	v_mfma_f32_16x16x32_bf16 v[112:115], v[180:183], v[188:191], v[112:115]
	v_mfma_f32_16x16x32_bf16 v[100:103], v[172:175], v[196:199], v[100:103]
	v_mfma_f32_16x16x32_bf16 v[96:99], v[180:183], v[196:199], v[96:99]
	v_mfma_f32_16x16x32_bf16 v[84:87], v[172:175], v[204:207], v[84:87]
	v_mfma_f32_16x16x32_bf16 v[80:83], v[180:183], v[204:207], v[80:83]
	v_mfma_f32_16x16x32_bf16 v[68:71], v[172:175], v[212:215], v[68:71]
	v_mfma_f32_16x16x32_bf16 v[64:67], v[180:183], v[212:215], v[64:67]
	s_setprio 0
	s_barrier
; #define PG8_STAGE(bufoff, gbase, voff) do { _Pragma("unroll") for (int _i = 0; _i < 2; ++_i) \
;         __builtin_amdgcn_global_load_lds((const unsigned*)((const char*)(gbase) + (voff)[_i]), (PG8_LAS unsigned*)(lds + (bufoff) + ldsw + _i * 8192), 16, 0, 0); } while (0)
; #define PG8_LDA(dst, b, h) do { _Pragma("unroll") for (int m = 0; m < 4; ++m) _Pragma("unroll") for (int k = 0; k < 2; ++k) dst[m][k] = *(const PG8_LAS bf16x8*)(lds + PG8_SA(b, h) + aoff + m * 2048 + k * 1024); } while (0)
; #define PG8_MMA(ai, bj, At, Bt) do { __builtin_amdgcn_s_setprio(1); _Pragma("unroll") for (int m = 0; m < 4; ++m) _Pragma("unroll") for (int n = 0; n < 2; ++n) _Pragma("unroll") for (int k = 0; k < 2; ++k) \
;         acc[ai][bj][m][n] = __builtin_amdgcn_mfma_f32_16x16x32_bf16(Bt[n][k], At[m][k], acc[ai][bj][m][n], 0, 0, 0); __builtin_amdgcn_s_setprio(0); } while (0)
; #define PG8_WAIT_V(n) asm volatile("s_waitcnt vmcnt(" #n ")" ::: "memory")
; #define PG8_WAIT_L(n) asm volatile("s_waitcnt lgkmcnt(" #n ")" ::: "memory")
; #define PG8_BAR __builtin_amdgcn_s_barrier()
; #define PG8_SCHED __builtin_amdgcn_sched_barrier(0)
; template <class Epi, class Sched, bool ALIGN_EPI = false, bool SP2 = false>
; __device__ __forceinline__ void gemm_phase(PG8_LAS unsigned char* lds, const Gemm g, const Sched& S, const Epi& E) {
;     ...
;             PG8_LDA(At, 1, 1); PG8_STAGE(PG8_SB(1, 0), b3, voffB); PG8_STAGE(PG8_SB(1, 1), b3 + hstep, voffB); PG8_STAGE(PG8_SA(1, 0), a3, voffA);
;             PG8_WAIT_V(8); PG8_WAIT_L(0); PG8_BAR; PG8_MMA(1, 0, At, B0); PG8_MMA(1, 1, At, B1); PG8_BAR; PG8_SCHED;
;     ...
;         if constexpr (ALIGN_EPI) { if (wr == 0) PG8_BAR; }
	s_add_i32 s36, s70, s39
	v_lshl_add_u64 v[216:217], v[216:217], 0, s[4:5]
	s_mov_b32 m0, s36
	ds_read_b128 v[184:187], v159 offset:49152
	global_load_lds_dwordx4 v[216:217], off
	s_add_i32 m0, s36, 0x2000
	s_add_u32 s34, s34, 0x20080
	v_lshl_add_u64 v[216:217], v[218:219], 0, s[4:5]
	s_addc_u32 s35, s35, 0
	s_add_i32 s36, s71, s39
	global_load_lds_dwordx4 v[216:217], off
	v_lshl_add_u64 v[216:217], s[34:35], 0, v[138:139]
	s_mov_b32 m0, s36
	ds_read_b128 v[188:191], v159 offset:50176
	global_load_lds_dwordx4 v[216:217], off
	v_lshl_add_u64 v[216:217], s[34:35], 0, v[142:143]
	s_add_i32 m0, s36, 0x2000
	ds_read_b128 v[192:195], v159 offset:51200
	global_load_lds_dwordx4 v[216:217], off
	v_lshl_add_u64 v[216:217], v[220:221], 0, s[4:5]
	s_mov_b32 m0, s44
	ds_read_b128 v[196:199], v159 offset:52224
	global_load_lds_dwordx4 v[216:217], off
	v_lshl_add_u64 v[216:217], v[222:223], 0, s[4:5]
	s_mov_b32 m0, s45
	ds_read_b128 v[200:203], v159 offset:53248
	global_load_lds_dwordx4 v[216:217], off
	ds_read_b128 v[204:207], v159 offset:54272
	ds_read_b128 v[208:211], v159 offset:55296
	ds_read_b128 v[212:215], v159 offset:56320
	s_waitcnt vmcnt(8)
	s_waitcnt lgkmcnt(0)
	s_barrier
	s_setprio 1
	s_waitcnt lgkmcnt(0)
	v_mfma_f32_16x16x32_bf16 v[60:63], v[144:147], v[184:187], v[60:63]
	v_mfma_f32_16x16x32_bf16 v[56:59], v[160:163], v[184:187], v[56:59]
	v_mfma_f32_16x16x32_bf16 v[44:47], v[144:147], v[192:195], v[44:47]
	v_mfma_f32_16x16x32_bf16 v[40:43], v[160:163], v[192:195], v[40:43]
	v_mfma_f32_16x16x32_bf16 v[28:31], v[144:147], v[200:203], v[28:31]
	v_mfma_f32_16x16x32_bf16 v[24:27], v[160:163], v[200:203], v[24:27]
	v_mfma_f32_16x16x32_bf16 v[12:15], v[144:147], v[208:211], v[12:15]
	v_mfma_f32_16x16x32_bf16 v[8:11], v[160:163], v[208:211], v[8:11]
	v_mfma_f32_16x16x32_bf16 v[60:63], v[152:155], v[188:191], v[60:63]
	v_mfma_f32_16x16x32_bf16 v[56:59], v[164:167], v[188:191], v[56:59]
	v_mfma_f32_16x16x32_bf16 v[44:47], v[152:155], v[196:199], v[44:47]
	v_mfma_f32_16x16x32_bf16 v[40:43], v[164:167], v[196:199], v[40:43]
	v_mfma_f32_16x16x32_bf16 v[28:31], v[152:155], v[204:207], v[28:31]
	v_mfma_f32_16x16x32_bf16 v[24:27], v[164:167], v[204:207], v[24:27]
	v_mfma_f32_16x16x32_bf16 v[12:15], v[152:155], v[212:215], v[12:15]
	v_mfma_f32_16x16x32_bf16 v[8:11], v[164:167], v[212:215], v[8:11]
	s_setprio 0
	s_setprio 1
	v_mfma_f32_16x16x32_bf16 v[52:55], v[168:171], v[184:187], v[52:55]
	v_mfma_f32_16x16x32_bf16 v[48:51], v[176:179], v[184:187], v[48:51]
	v_mfma_f32_16x16x32_bf16 v[36:39], v[168:171], v[192:195], v[36:39]
	v_mfma_f32_16x16x32_bf16 v[32:35], v[176:179], v[192:195], v[32:35]
	v_mfma_f32_16x16x32_bf16 v[20:23], v[168:171], v[200:203], v[20:23]
	v_mfma_f32_16x16x32_bf16 v[16:19], v[176:179], v[200:203], v[16:19]
	v_mfma_f32_16x16x32_bf16 v[4:7], v[168:171], v[208:211], v[4:7]
	v_mfma_f32_16x16x32_bf16 v[0:3], v[176:179], v[208:211], v[0:3]
	v_mfma_f32_16x16x32_bf16 v[52:55], v[172:175], v[188:191], v[52:55]
	v_mfma_f32_16x16x32_bf16 v[48:51], v[180:183], v[188:191], v[48:51]
	v_mfma_f32_16x16x32_bf16 v[36:39], v[172:175], v[196:199], v[36:39]
	v_mfma_f32_16x16x32_bf16 v[32:35], v[180:183], v[196:199], v[32:35]
	v_mfma_f32_16x16x32_bf16 v[20:23], v[172:175], v[204:207], v[20:23]
	v_mfma_f32_16x16x32_bf16 v[16:19], v[180:183], v[204:207], v[16:19]
	v_mfma_f32_16x16x32_bf16 v[4:7], v[172:175], v[212:215], v[4:7]
	v_mfma_f32_16x16x32_bf16 v[0:3], v[180:183], v[212:215], v[0:3]
	s_setprio 0
	s_barrier
	s_add_i32 s69, s69, 2
	s_add_u32 s30, s30, 0x100
	s_addc_u32 s31, s31, 0
	s_add_u32 s63, s63, 0x100
	s_addc_u32 s68, s68, 0
	s_cmp_gt_u32 s69, 5
	s_cbranch_scc0 .LBB0_1319
	s_nop 0
	s_nop 0
	s_nop 0
	s_nop 0
	s_nop 0
	s_nop 0
	s_nop 0
	s_nop 0
	s_nop 0
	s_and_b64 vcc, exec, s[6:7]
	s_cbranch_vccz .LBB0_1322
	s_barrier

; #define PG8_STAGE(bufoff, gbase, voff) do { _Pragma("unroll") for (int _i = 0; _i < 2; ++_i) \
;         __builtin_amdgcn_global_load_lds((const unsigned*)((const char*)(gbase) + (voff)[_i]), (PG8_LAS unsigned*)(lds + (bufoff) + ldsw + _i * 8192), 16, 0, 0); } while (0)
; #define PG8_LDA(dst, b, h) do { _Pragma("unroll") for (int m = 0; m < 4; ++m) _Pragma("unroll") for (int k = 0; k < 2; ++k) dst[m][k] = *(const PG8_LAS bf16x8*)(lds + PG8_SA(b, h) + aoff + m * 2048 + k * 1024); } while (0)
; #define PG8_LDB(dst, b, h) do { _Pragma("unroll") for (int n = 0; n < 2; ++n) _Pragma("unroll") for (int k = 0; k < 2; ++k) dst[n][k] = *(const PG8_LAS bf16x8*)(lds + PG8_SB(b, h) + boff + n * 2048 + k * 1024); } while (0)
; #define PG8_MMA(ai, bj, At, Bt) do { __builtin_amdgcn_s_setprio(1); _Pragma("unroll") for (int m = 0; m < 4; ++m) _Pragma("unroll") for (int n = 0; n < 2; ++n) _Pragma("unroll") for (int k = 0; k < 2; ++k) \
;         acc[ai][bj][m][n] = __builtin_amdgcn_mfma_f32_16x16x32_bf16(Bt[n][k], At[m][k], acc[ai][bj][m][n], 0, 0, 0); __builtin_amdgcn_s_setprio(0); } while (0)
; #define PG8_WAIT_V(n) asm volatile("s_waitcnt vmcnt(" #n ")" ::: "memory")
; #define PG8_WAIT_L(n) asm volatile("s_waitcnt lgkmcnt(" #n ")" ::: "memory")
; template <class Epi, class Sched, bool ALIGN_EPI = false, bool SP2 = false>
; __device__ __forceinline__ void gemm_phase(PG8_LAS unsigned char* lds, const Gemm g, const Sched& S, const Epi& E) {
;     ...
;             const bool last = (t == nt - 2);
;             const char* a1 = cA + (size_t)(t + 1) * kstep;
;             const char* a2 = last ? nA : cA + (size_t)(t + 2) * kstep; const char* b2 = last ? nB : cB + (size_t)(t + 2) * kstep;
;             const char* a3 = a2 + kstep; const char* b3 = b2 + kstep;
;             if (last && has_next) S.a_ready(nxt);
;             if constexpr (SP2) {
;             PG8_LDB(B0, 0, 0); PG8_LDB(B1, 0, 1); PG8_SCHED; PG8_LDA(At, 0, 0); PG8_STAGE(PG8_SA(1, 1), a1 + hstep, voffA);
;             PG8_WAIT_V(8); PG8_WAIT_L(0); PG8_BAR; PG8_MMA(0, 0, At, B0); PG8_MMA(0, 1, At, B1); PG8_BAR; PG8_SCHED;
;             PG8_LDA(At, 0, 1); PG8_STAGE(PG8_SB(0, 0), b2, voffB); PG8_STAGE(PG8_SB(0, 1), b2 + hstep, voffB); PG8_STAGE(PG8_SA(0, 0), a2, voffA);
;             PG8_WAIT_V(8); PG8_WAIT_L(0); PG8_BAR; PG8_MMA(1, 0, At, B0); PG8_MMA(1, 1, At, B1); PG8_BAR; PG8_SCHED;
.LBB0_1400:
	v_lshl_add_u64 v[214:215], s[24:25], 0, v[132:133]
	s_add_i32 m0, s23, 0xc000
	ds_read_b128 v[140:143], v147
	global_load_lds_dwordx4 v[214:215], off
	v_lshl_add_u64 v[214:215], s[24:25], 0, v[134:135]
	s_add_i32 m0, s23, 0xe000
	ds_read_b128 v[154:157], v147 offset:1024
	global_load_lds_dwordx4 v[214:215], off
	s_add_u32 s26, s24, 0xfffc0080
	s_addc_u32 s27, s25, -1
	s_cmp_eq_u32 s60, 12
	s_cselect_b32 s29, s15, s27
	s_cselect_b32 s28, s21, s26
	s_cselect_b32 s27, s13, s59
	s_cselect_b32 s26, s57, s58
	ds_read_b128 v[158:161], v147 offset:2048
	ds_read_b128 v[162:165], v147 offset:3072
	ds_read_b128 v[166:169], v149
	ds_read_b128 v[170:173], v149 offset:1024
	ds_read_b128 v[174:177], v149 offset:2048
	ds_read_b128 v[178:181], v149 offset:3072
	ds_read_b128 v[182:185], v151
	ds_read_b128 v[186:189], v151 offset:1024
	ds_read_b128 v[190:193], v151 offset:2048
	ds_read_b128 v[194:197], v151 offset:3072
	ds_read_b128 v[198:201], v151 offset:4096
	ds_read_b128 v[202:205], v151 offset:5120
	ds_read_b128 v[206:209], v151 offset:6144
	ds_read_b128 v[210:213], v151 offset:7168
	s_waitcnt vmcnt(8)
	s_waitcnt lgkmcnt(0)
	s_barrier
	s_setprio 1
	s_waitcnt lgkmcnt(0)
	v_mfma_f32_16x16x32_bf16 v[124:127], v[140:143], v[182:185], v[124:127]
	v_mfma_f32_16x16x32_bf16 v[120:123], v[158:161], v[182:185], v[120:123]
	v_mfma_f32_16x16x32_bf16 v[108:111], v[140:143], v[190:193], v[108:111]
	v_mfma_f32_16x16x32_bf16 v[104:107], v[158:161], v[190:193], v[104:107]
	v_mfma_f32_16x16x32_bf16 v[92:95], v[140:143], v[198:201], v[92:95]
	v_mfma_f32_16x16x32_bf16 v[88:91], v[158:161], v[198:201], v[88:91]
	v_mfma_f32_16x16x32_bf16 v[76:79], v[140:143], v[206:209], v[76:79]
	v_mfma_f32_16x16x32_bf16 v[72:75], v[158:161], v[206:209], v[72:75]
	v_mfma_f32_16x16x32_bf16 v[124:127], v[154:157], v[186:189], v[124:127]
	v_mfma_f32_16x16x32_bf16 v[120:123], v[162:165], v[186:189], v[120:123]
	v_mfma_f32_16x16x32_bf16 v[108:111], v[154:157], v[194:197], v[108:111]
	v_mfma_f32_16x16x32_bf16 v[104:107], v[162:165], v[194:197], v[104:107]
	v_mfma_f32_16x16x32_bf16 v[92:95], v[154:157], v[202:205], v[92:95]
	v_mfma_f32_16x16x32_bf16 v[88:91], v[162:165], v[202:205], v[88:91]
	v_mfma_f32_16x16x32_bf16 v[76:79], v[154:157], v[210:213], v[76:79]
	v_mfma_f32_16x16x32_bf16 v[72:75], v[162:165], v[210:213], v[72:75]
	s_setprio 0
	s_setprio 1
	v_mfma_f32_16x16x32_bf16 v[116:119], v[166:169], v[182:185], v[116:119]
	v_mfma_f32_16x16x32_bf16 v[112:115], v[174:177], v[182:185], v[112:115]
	v_mfma_f32_16x16x32_bf16 v[100:103], v[166:169], v[190:193], v[100:103]
	v_mfma_f32_16x16x32_bf16 v[96:99], v[174:177], v[190:193], v[96:99]
	v_mfma_f32_16x16x32_bf16 v[84:87], v[166:169], v[198:201], v[84:87]
	v_mfma_f32_16x16x32_bf16 v[80:83], v[174:177], v[198:201], v[80:83]
	v_mfma_f32_16x16x32_bf16 v[68:71], v[166:169], v[206:209], v[68:71]
	v_mfma_f32_16x16x32_bf16 v[64:67], v[174:177], v[206:209], v[64:67]
	v_mfma_f32_16x16x32_bf16 v[116:119], v[170:173], v[186:189], v[116:119]
	v_mfma_f32_16x16x32_bf16 v[112:115], v[178:181], v[186:189], v[112:115]
	v_mfma_f32_16x16x32_bf16 v[100:103], v[170:173], v[194:197], v[100:103]
	v_mfma_f32_16x16x32_bf16 v[96:99], v[178:181], v[194:197], v[96:99]
	v_mfma_f32_16x16x32_bf16 v[84:87], v[170:173], v[202:205], v[84:87]
	v_mfma_f32_16x16x32_bf16 v[80:83], v[178:181], v[202:205], v[80:83]
	v_mfma_f32_16x16x32_bf16 v[68:71], v[170:173], v[210:213], v[68:71]
	v_mfma_f32_16x16x32_bf16 v[64:67], v[178:181], v[210:213], v[64:67]
	s_setprio 0
	s_barrier
	s_add_i32 s61, s42, s30
	v_lshl_add_u64 v[214:215], s[26:27], 0, v[128:129]
	s_mov_b32 m0, s61
	v_lshl_add_u64 v[216:217], s[26:27], 0, v[130:131]
	global_load_lds_dwordx4 v[214:215], off
	s_add_i32 m0, s61, 0x2000
	s_add_u32 s62, s26, 0x40000
	s_addc_u32 s63, s27, 0
	s_add_i32 s61, s43, s30
	global_load_lds_dwordx4 v[216:217], off
	v_lshl_add_u64 v[218:219], s[62:63], 0, v[128:129]
	s_mov_b32 m0, s61
	v_lshl_add_u64 v[220:221], s[28:29], 0, v[130:131]
	global_load_lds_dwordx4 v[218:219], off
	v_lshl_add_u64 v[218:219], s[62:63], 0, v[130:131]
	s_add_i32 m0, s61, 0x2000
	ds_read_b128 v[182:185], v151 offset:16384
	global_load_lds_dwordx4 v[218:219], off
	v_lshl_add_u64 v[218:219], s[28:29], 0, v[128:129]
	s_mov_b32 m0, s23
	ds_read_b128 v[186:189], v151 offset:17408
	global_load_lds_dwordx4 v[218:219], off
	s_mov_b32 m0, s31
	ds_read_b128 v[190:193], v151 offset:18432
	global_load_lds_dwordx4 v[220:221], off
	ds_read_b128 v[194:197], v151 offset:19456
	ds_read_b128 v[198:201], v151 offset:20480
	ds_read_b128 v[202:205], v151 offset:21504
	ds_read_b128 v[206:209], v151 offset:22528
	ds_read_b128 v[210:213], v151 offset:23552
	s_waitcnt vmcnt(8)
	s_waitcnt lgkmcnt(0)
	s_barrier
; #define PG8_STAGE(bufoff, gbase, voff) do { _Pragma("unroll") for (int _i = 0; _i < 2; ++_i) \
;         __builtin_amdgcn_global_load_lds((const unsigned*)((const char*)(gbase) + (voff)[_i]), (PG8_LAS unsigned*)(lds + (bufoff) + ldsw + _i * 8192), 16, 0, 0); } while (0)
; #define PG8_LDA(dst, b, h) do { _Pragma("unroll") for (int m = 0; m < 4; ++m) _Pragma("unroll") for (int k = 0; k < 2; ++k) dst[m][k] = *(const PG8_LAS bf16x8*)(lds + PG8_SA(b, h) + aoff + m * 2048 + k * 1024); } while (0)
; #define PG8_LDB(dst, b, h) do { _Pragma("unroll") for (int n = 0; n < 2; ++n) _Pragma("unroll") for (int k = 0; k < 2; ++k) dst[n][k] = *(const PG8_LAS bf16x8*)(lds + PG8_SB(b, h) + boff + n * 2048 + k * 1024); } while (0)
; #define PG8_MMA(ai, bj, At, Bt) do { __builtin_amdgcn_s_setprio(1); _Pragma("unroll") for (int m = 0; m < 4; ++m) _Pragma("unroll") for (int n = 0; n < 2; ++n) _Pragma("unroll") for (int k = 0; k < 2; ++k) \
;         acc[ai][bj][m][n] = __builtin_amdgcn_mfma_f32_16x16x32_bf16(Bt[n][k], At[m][k], acc[ai][bj][m][n], 0, 0, 0); __builtin_amdgcn_s_setprio(0); } while (0)
; #define PG8_WAIT_V(n) asm volatile("s_waitcnt vmcnt(" #n ")" ::: "memory")
; #define PG8_WAIT_L(n) asm volatile("s_waitcnt lgkmcnt(" #n ")" ::: "memory")
; #define PG8_BAR __builtin_amdgcn_s_barrier()
; #define PG8_SCHED __builtin_amdgcn_sched_barrier(0)
; template <class Epi, class Sched, bool ALIGN_EPI = false, bool SP2 = false>
; __device__ __forceinline__ void gemm_phase(PG8_LAS unsigned char* lds, const Gemm g, const Sched& S, const Epi& E) {
;     ...
;             PG8_WAIT_V(8); PG8_WAIT_L(0); PG8_BAR; PG8_MMA(1, 0, At, B0); PG8_MMA(1, 1, At, B1); PG8_BAR; PG8_SCHED;
;             PG8_LDB(B0, 1, 0); PG8_LDB(B1, 1, 1); PG8_SCHED; PG8_LDA(At, 1, 0); PG8_STAGE(PG8_SA(0, 1), a2 + hstep, voffA);
;             PG8_WAIT_V(8); PG8_WAIT_L(0); PG8_BAR; PG8_MMA(0, 0, At, B0); PG8_MMA(0, 1, At, B1); PG8_BAR; PG8_SCHED;
	s_setprio 1
	s_waitcnt lgkmcnt(0)
	v_mfma_f32_16x16x32_bf16 v[60:63], v[140:143], v[182:185], v[60:63]
	v_mfma_f32_16x16x32_bf16 v[56:59], v[158:161], v[182:185], v[56:59]
	v_mfma_f32_16x16x32_bf16 v[44:47], v[140:143], v[190:193], v[44:47]
	v_mfma_f32_16x16x32_bf16 v[40:43], v[158:161], v[190:193], v[40:43]
	v_mfma_f32_16x16x32_bf16 v[28:31], v[140:143], v[198:201], v[28:31]
	v_mfma_f32_16x16x32_bf16 v[24:27], v[158:161], v[198:201], v[24:27]
	v_mfma_f32_16x16x32_bf16 v[12:15], v[140:143], v[206:209], v[12:15]
	v_mfma_f32_16x16x32_bf16 v[8:11], v[158:161], v[206:209], v[8:11]
	v_mfma_f32_16x16x32_bf16 v[60:63], v[154:157], v[186:189], v[60:63]
	v_mfma_f32_16x16x32_bf16 v[56:59], v[162:165], v[186:189], v[56:59]
	v_mfma_f32_16x16x32_bf16 v[44:47], v[154:157], v[194:197], v[44:47]
	v_mfma_f32_16x16x32_bf16 v[40:43], v[162:165], v[194:197], v[40:43]
	v_mfma_f32_16x16x32_bf16 v[28:31], v[154:157], v[202:205], v[28:31]
	v_mfma_f32_16x16x32_bf16 v[24:27], v[162:165], v[202:205], v[24:27]
	v_mfma_f32_16x16x32_bf16 v[12:15], v[154:157], v[210:213], v[12:15]
	v_mfma_f32_16x16x32_bf16 v[8:11], v[162:165], v[210:213], v[8:11]
	s_setprio 0
	s_setprio 1
	v_mfma_f32_16x16x32_bf16 v[52:55], v[166:169], v[182:185], v[52:55]
	v_mfma_f32_16x16x32_bf16 v[48:51], v[174:177], v[182:185], v[48:51]
	v_mfma_f32_16x16x32_bf16 v[36:39], v[166:169], v[190:193], v[36:39]
	v_mfma_f32_16x16x32_bf16 v[32:35], v[174:177], v[190:193], v[32:35]
	v_mfma_f32_16x16x32_bf16 v[20:23], v[166:169], v[198:201], v[20:23]
	v_mfma_f32_16x16x32_bf16 v[16:19], v[174:177], v[198:201], v[16:19]
	v_mfma_f32_16x16x32_bf16 v[4:7], v[166:169], v[206:209], v[4:7]
	v_mfma_f32_16x16x32_bf16 v[0:3], v[174:177], v[206:209], v[0:3]
	v_mfma_f32_16x16x32_bf16 v[52:55], v[170:173], v[186:189], v[52:55]
	v_mfma_f32_16x16x32_bf16 v[48:51], v[178:181], v[186:189], v[48:51]
	v_mfma_f32_16x16x32_bf16 v[36:39], v[170:173], v[194:197], v[36:39]
	v_mfma_f32_16x16x32_bf16 v[32:35], v[178:181], v[194:197], v[32:35]
	v_mfma_f32_16x16x32_bf16 v[20:23], v[170:173], v[202:205], v[20:23]
	v_mfma_f32_16x16x32_bf16 v[16:19], v[178:181], v[202:205], v[16:19]
	v_mfma_f32_16x16x32_bf16 v[4:7], v[170:173], v[210:213], v[4:7]
	v_mfma_f32_16x16x32_bf16 v[0:3], v[178:181], v[210:213], v[0:3]
	s_setprio 0
	s_barrier
	s_add_i32 s61, 0, 0x18000
	s_add_i32 s62, 0, 0x1c000
	s_add_u32 s28, s28, 0x40000
	s_addc_u32 s29, s29, 0
	s_mov_b32 m0, s34
	v_lshl_add_u64 v[222:223], s[28:29], 0, v[128:129]
	global_load_lds_dwordx4 v[222:223], off
	v_lshl_add_u64 v[222:223], s[28:29], 0, v[130:131]
	s_mov_b32 m0, s35
	v_add_u32_e32 v153, s61, v145
	global_load_lds_dwordx4 v[222:223], off
	ds_read_b128 v[140:143], v153
	ds_read_b128 v[154:157], v153 offset:1024
	ds_read_b128 v[158:161], v153 offset:2048
	ds_read_b128 v[162:165], v153 offset:3072
	v_add_u32_e32 v153, s62, v145
	ds_read_b128 v[166:169], v153
	ds_read_b128 v[170:173], v153 offset:1024
	ds_read_b128 v[174:177], v153 offset:2048
	ds_read_b128 v[178:181], v153 offset:3072
	ds_read_b128 v[182:185], v151 offset:32768
	ds_read_b128 v[186:189], v151 offset:33792
	ds_read_b128 v[190:193], v151 offset:34816
	ds_read_b128 v[194:197], v151 offset:35840
	ds_read_b128 v[198:201], v151 offset:36864
	ds_read_b128 v[202:205], v151 offset:37888
	ds_read_b128 v[206:209], v151 offset:38912
	ds_read_b128 v[210:213], v151 offset:39936
	s_waitcnt vmcnt(8)
	s_waitcnt lgkmcnt(0)
	s_barrier
	s_setprio 1
	s_waitcnt lgkmcnt(0)
	v_mfma_f32_16x16x32_bf16 v[124:127], v[140:143], v[182:185], v[124:127]
	v_mfma_f32_16x16x32_bf16 v[120:123], v[158:161], v[182:185], v[120:123]
	v_mfma_f32_16x16x32_bf16 v[108:111], v[140:143], v[190:193], v[108:111]
	v_mfma_f32_16x16x32_bf16 v[104:107], v[158:161], v[190:193], v[104:107]
	v_mfma_f32_16x16x32_bf16 v[92:95], v[140:143], v[198:201], v[92:95]
	v_mfma_f32_16x16x32_bf16 v[88:91], v[158:161], v[198:201], v[88:91]
	v_mfma_f32_16x16x32_bf16 v[76:79], v[140:143], v[206:209], v[76:79]
	v_mfma_f32_16x16x32_bf16 v[72:75], v[158:161], v[206:209], v[72:75]
	v_mfma_f32_16x16x32_bf16 v[124:127], v[154:157], v[186:189], v[124:127]
	v_mfma_f32_16x16x32_bf16 v[120:123], v[162:165], v[186:189], v[120:123]
	v_mfma_f32_16x16x32_bf16 v[108:111], v[154:157], v[194:197], v[108:111]
	v_mfma_f32_16x16x32_bf16 v[104:107], v[162:165], v[194:197], v[104:107]
	v_mfma_f32_16x16x32_bf16 v[92:95], v[154:157], v[202:205], v[92:95]
	v_mfma_f32_16x16x32_bf16 v[88:91], v[162:165], v[202:205], v[88:91]
	v_mfma_f32_16x16x32_bf16 v[76:79], v[154:157], v[210:213], v[76:79]
	v_mfma_f32_16x16x32_bf16 v[72:75], v[162:165], v[210:213], v[72:75]
	s_setprio 0
	s_setprio 1
	v_mfma_f32_16x16x32_bf16 v[116:119], v[166:169], v[182:185], v[116:119]
	v_mfma_f32_16x16x32_bf16 v[112:115], v[174:177], v[182:185], v[112:115]
	v_mfma_f32_16x16x32_bf16 v[100:103], v[166:169], v[190:193], v[100:103]
	v_mfma_f32_16x16x32_bf16 v[96:99], v[174:177], v[190:193], v[96:99]
	v_mfma_f32_16x16x32_bf16 v[84:87], v[166:169], v[198:201], v[84:87]
	v_mfma_f32_16x16x32_bf16 v[80:83], v[174:177], v[198:201], v[80:83]
	v_mfma_f32_16x16x32_bf16 v[68:71], v[166:169], v[206:209], v[68:71]
	v_mfma_f32_16x16x32_bf16 v[64:67], v[174:177], v[206:209], v[64:67]
	v_mfma_f32_16x16x32_bf16 v[116:119], v[170:173], v[186:189], v[116:119]
	v_mfma_f32_16x16x32_bf16 v[112:115], v[178:181], v[186:189], v[112:115]
	v_mfma_f32_16x16x32_bf16 v[100:103], v[170:173], v[194:197], v[100:103]
	v_mfma_f32_16x16x32_bf16 v[96:99], v[178:181], v[194:197], v[96:99]
	v_mfma_f32_16x16x32_bf16 v[84:87], v[170:173], v[202:205], v[84:87]
	v_mfma_f32_16x16x32_bf16 v[80:83], v[178:181], v[202:205], v[80:83]
	v_mfma_f32_16x16x32_bf16 v[68:71], v[170:173], v[210:213], v[68:71]
	v_mfma_f32_16x16x32_bf16 v[64:67], v[178:181], v[210:213], v[64:67]
	s_setprio 0
	s_barrier
; #define PG8_STAGE(bufoff, gbase, voff) do { _Pragma("unroll") for (int _i = 0; _i < 2; ++_i) \
;         __builtin_amdgcn_global_load_lds((const unsigned*)((const char*)(gbase) + (voff)[_i]), (PG8_LAS unsigned*)(lds + (bufoff) + ldsw + _i * 8192), 16, 0, 0); } while (0)
; #define PG8_LDA(dst, b, h) do { _Pragma("unroll") for (int m = 0; m < 4; ++m) _Pragma("unroll") for (int k = 0; k < 2; ++k) dst[m][k] = *(const PG8_LAS bf16x8*)(lds + PG8_SA(b, h) + aoff + m * 2048 + k * 1024); } while (0)
; #define PG8_MMA(ai, bj, At, Bt) do { __builtin_amdgcn_s_setprio(1); _Pragma("unroll") for (int m = 0; m < 4; ++m) _Pragma("unroll") for (int n = 0; n < 2; ++n) _Pragma("unroll") for (int k = 0; k < 2; ++k) \
;         acc[ai][bj][m][n] = __builtin_amdgcn_mfma_f32_16x16x32_bf16(Bt[n][k], At[m][k], acc[ai][bj][m][n], 0, 0, 0); __builtin_amdgcn_s_setprio(0); } while (0)
; #define PG8_WAIT_V(n) asm volatile("s_waitcnt vmcnt(" #n ")" ::: "memory")
; #define PG8_WAIT_L(n) asm volatile("s_waitcnt lgkmcnt(" #n ")" ::: "memory")
; #define PG8_BAR __builtin_amdgcn_s_barrier()
; #define PG8_SCHED __builtin_amdgcn_sched_barrier(0)
; template <class Epi, class Sched, bool ALIGN_EPI = false, bool SP2 = false>
; __device__ __forceinline__ void gemm_phase(PG8_LAS unsigned char* lds, const Gemm g, const Sched& S, const Epi& E) {
;     ...
;             PG8_LDA(At, 1, 1); PG8_STAGE(PG8_SB(1, 0), b3, voffB); PG8_STAGE(PG8_SB(1, 1), b3 + hstep, voffB); PG8_STAGE(PG8_SA(1, 0), a3, voffA);
;             PG8_WAIT_V(8); PG8_WAIT_L(0); PG8_BAR; PG8_MMA(1, 0, At, B0); PG8_MMA(1, 1, At, B1); PG8_BAR; PG8_SCHED;
;     ...
;         if constexpr (ALIGN_EPI) { if (wr == 0) PG8_BAR; }
	s_add_i32 s28, s61, s30
	v_lshl_add_u64 v[214:215], v[214:215], 0, s[8:9]
	s_mov_b32 m0, s28
	ds_read_b128 v[182:185], v151 offset:49152
	global_load_lds_dwordx4 v[214:215], off
	s_add_i32 m0, s28, 0x2000
	s_add_u32 s26, s26, 0x40080
	v_lshl_add_u64 v[214:215], v[216:217], 0, s[8:9]
	s_addc_u32 s27, s27, 0
	s_add_i32 s28, s62, s30
	global_load_lds_dwordx4 v[214:215], off
	v_lshl_add_u64 v[214:215], s[26:27], 0, v[128:129]
	s_mov_b32 m0, s28
	ds_read_b128 v[186:189], v151 offset:50176
	global_load_lds_dwordx4 v[214:215], off
	v_lshl_add_u64 v[214:215], s[26:27], 0, v[130:131]
	s_add_i32 m0, s28, 0x2000
	ds_read_b128 v[190:193], v151 offset:51200
	global_load_lds_dwordx4 v[214:215], off
	v_lshl_add_u64 v[214:215], v[218:219], 0, s[8:9]
	s_mov_b32 m0, s38
	ds_read_b128 v[194:197], v151 offset:52224
	global_load_lds_dwordx4 v[214:215], off
	v_lshl_add_u64 v[214:215], v[220:221], 0, s[8:9]
	s_mov_b32 m0, s39
	ds_read_b128 v[198:201], v151 offset:53248
	global_load_lds_dwordx4 v[214:215], off
	ds_read_b128 v[202:205], v151 offset:54272
	ds_read_b128 v[206:209], v151 offset:55296
	ds_read_b128 v[210:213], v151 offset:56320
	s_waitcnt vmcnt(8)
	s_waitcnt lgkmcnt(0)
	s_barrier
	s_setprio 1
	s_waitcnt lgkmcnt(0)
	v_mfma_f32_16x16x32_bf16 v[60:63], v[140:143], v[182:185], v[60:63]
	v_mfma_f32_16x16x32_bf16 v[56:59], v[158:161], v[182:185], v[56:59]
	v_mfma_f32_16x16x32_bf16 v[44:47], v[140:143], v[190:193], v[44:47]
	v_mfma_f32_16x16x32_bf16 v[40:43], v[158:161], v[190:193], v[40:43]
	v_mfma_f32_16x16x32_bf16 v[28:31], v[140:143], v[198:201], v[28:31]
	v_mfma_f32_16x16x32_bf16 v[24:27], v[158:161], v[198:201], v[24:27]
	v_mfma_f32_16x16x32_bf16 v[12:15], v[140:143], v[206:209], v[12:15]
	v_mfma_f32_16x16x32_bf16 v[8:11], v[158:161], v[206:209], v[8:11]
	v_mfma_f32_16x16x32_bf16 v[60:63], v[154:157], v[186:189], v[60:63]
	v_mfma_f32_16x16x32_bf16 v[56:59], v[162:165], v[186:189], v[56:59]
	v_mfma_f32_16x16x32_bf16 v[44:47], v[154:157], v[194:197], v[44:47]
	v_mfma_f32_16x16x32_bf16 v[40:43], v[162:165], v[194:197], v[40:43]
	v_mfma_f32_16x16x32_bf16 v[28:31], v[154:157], v[202:205], v[28:31]
	v_mfma_f32_16x16x32_bf16 v[24:27], v[162:165], v[202:205], v[24:27]
	v_mfma_f32_16x16x32_bf16 v[12:15], v[154:157], v[210:213], v[12:15]
	v_mfma_f32_16x16x32_bf16 v[8:11], v[162:165], v[210:213], v[8:11]
	s_setprio 0
	s_setprio 1
	v_mfma_f32_16x16x32_bf16 v[52:55], v[166:169], v[182:185], v[52:55]
	v_mfma_f32_16x16x32_bf16 v[48:51], v[174:177], v[182:185], v[48:51]
	v_mfma_f32_16x16x32_bf16 v[36:39], v[166:169], v[190:193], v[36:39]
	v_mfma_f32_16x16x32_bf16 v[32:35], v[174:177], v[190:193], v[32:35]
	v_mfma_f32_16x16x32_bf16 v[20:23], v[166:169], v[198:201], v[20:23]
	v_mfma_f32_16x16x32_bf16 v[16:19], v[174:177], v[198:201], v[16:19]
	v_mfma_f32_16x16x32_bf16 v[4:7], v[166:169], v[206:209], v[4:7]
	v_mfma_f32_16x16x32_bf16 v[0:3], v[174:177], v[206:209], v[0:3]
	v_mfma_f32_16x16x32_bf16 v[52:55], v[170:173], v[186:189], v[52:55]
	v_mfma_f32_16x16x32_bf16 v[48:51], v[178:181], v[186:189], v[48:51]
	v_mfma_f32_16x16x32_bf16 v[36:39], v[170:173], v[194:197], v[36:39]
	v_mfma_f32_16x16x32_bf16 v[32:35], v[178:181], v[194:197], v[32:35]
	v_mfma_f32_16x16x32_bf16 v[20:23], v[170:173], v[202:205], v[20:23]
	v_mfma_f32_16x16x32_bf16 v[16:19], v[178:181], v[202:205], v[16:19]
	v_mfma_f32_16x16x32_bf16 v[4:7], v[170:173], v[210:213], v[4:7]
	v_mfma_f32_16x16x32_bf16 v[0:3], v[178:181], v[210:213], v[0:3]
	s_setprio 0
	s_barrier
	s_add_i32 s60, s60, 2
	s_add_u32 s24, s24, 0x100
	s_addc_u32 s25, s25, 0
	s_add_u32 s58, s58, 0x100
	s_addc_u32 s59, s59, 0
	s_cmp_gt_u32 s60, 13
	s_cbranch_scc0 .LBB0_1400
	s_nop 0
	s_nop 0
	s_nop 0
	s_nop 0
	s_nop 0
	s_nop 0
	s_nop 0
	s_nop 0
	s_nop 0
	s_and_b64 vcc, exec, s[10:11]
	s_cbranch_vccz .LBB0_1403
	s_barrier

; #define PG8_STAGE(bufoff, gbase, voff) do { _Pragma("unroll") for (int _i = 0; _i < 2; ++_i) \
;         __builtin_amdgcn_global_load_lds((const unsigned*)((const char*)(gbase) + (voff)[_i]), (PG8_LAS unsigned*)(lds + (bufoff) + ldsw + _i * 8192), 16, 0, 0); } while (0)
; #define PG8_LDA(dst, b, h) do { _Pragma("unroll") for (int m = 0; m < 4; ++m) _Pragma("unroll") for (int k = 0; k < 2; ++k) dst[m][k] = *(const PG8_LAS bf16x8*)(lds + PG8_SA(b, h) + aoff + m * 2048 + k * 1024); } while (0)
; #define PG8_LDB(dst, b, h) do { _Pragma("unroll") for (int n = 0; n < 2; ++n) _Pragma("unroll") for (int k = 0; k < 2; ++k) dst[n][k] = *(const PG8_LAS bf16x8*)(lds + PG8_SB(b, h) + boff + n * 2048 + k * 1024); } while (0)
; #define PG8_MMA(ai, bj, At, Bt) do { __builtin_amdgcn_s_setprio(1); _Pragma("unroll") for (int m = 0; m < 4; ++m) _Pragma("unroll") for (int n = 0; n < 2; ++n) _Pragma("unroll") for (int k = 0; k < 2; ++k) \
;         acc[ai][bj][m][n] = __builtin_amdgcn_mfma_f32_16x16x32_bf16(Bt[n][k], At[m][k], acc[ai][bj][m][n], 0, 0, 0); __builtin_amdgcn_s_setprio(0); } while (0)
; #define PG8_WAIT_V(n) asm volatile("s_waitcnt vmcnt(" #n ")" ::: "memory")
; #define PG8_WAIT_L(n) asm volatile("s_waitcnt lgkmcnt(" #n ")" ::: "memory")
; template <class Epi, class Sched, bool ALIGN_EPI = false, bool SP2 = false>
; __device__ __forceinline__ void gemm_phase(PG8_LAS unsigned char* lds, const Gemm g, const Sched& S, const Epi& E) {
;     ...
;             const bool last = (t == nt - 2);
;             const char* a1 = cA + (size_t)(t + 1) * kstep;
;             const char* a2 = last ? nA : cA + (size_t)(t + 2) * kstep; const char* b2 = last ? nB : cB + (size_t)(t + 2) * kstep;
;             const char* a3 = a2 + kstep; const char* b3 = b2 + kstep;
;             if (last && has_next) S.a_ready(nxt);
;             if constexpr (SP2) {
;             PG8_LDB(B0, 0, 0); PG8_LDB(B1, 0, 1); PG8_SCHED; PG8_LDA(At, 0, 0); PG8_STAGE(PG8_SA(1, 1), a1 + hstep, voffA);
;             PG8_WAIT_V(8); PG8_WAIT_L(0); PG8_BAR; PG8_MMA(0, 0, At, B0); PG8_MMA(0, 1, At, B1); PG8_BAR; PG8_SCHED;
;             PG8_LDA(At, 0, 1); PG8_STAGE(PG8_SB(0, 0), b2, voffB); PG8_STAGE(PG8_SB(0, 1), b2 + hstep, voffB); PG8_STAGE(PG8_SA(0, 0), a2, voffA);
;             PG8_WAIT_V(8); PG8_WAIT_L(0); PG8_BAR; PG8_MMA(1, 0, At, B0); PG8_MMA(1, 1, At, B1); PG8_BAR; PG8_SCHED;
.LBB0_1487:
	v_lshl_add_u64 v[152:153], s[4:5], 0, v[136:137]
	s_add_i32 m0, s31, 0xc000
	ds_read_b128 v[144:147], v155
	global_load_lds_dwordx4 v[152:153], off
	v_lshl_add_u64 v[152:153], s[4:5], 0, v[138:139]
	s_add_i32 m0, s31, 0xe000
	ds_read_b128 v[160:163], v155 offset:1024
	global_load_lds_dwordx4 v[152:153], off
	s_add_u32 s6, s4, 0xfffc0080
	s_addc_u32 s7, s5, -1
	s_cmp_eq_u32 s51, 12
	s_cselect_b32 s9, s10, s7
	s_cselect_b32 s8, s11, s6
	s_cselect_b32 s7, s21, s50
	s_cselect_b32 s6, s23, s45
	ds_read_b128 v[164:167], v155 offset:2048
	ds_read_b128 v[168:171], v155 offset:3072
	ds_read_b128 v[172:175], v156
	ds_read_b128 v[176:179], v156 offset:1024
	ds_read_b128 v[180:183], v156 offset:2048
	ds_read_b128 v[184:187], v156 offset:3072
	ds_read_b128 v[188:191], v157
	ds_read_b128 v[192:195], v157 offset:1024
	ds_read_b128 v[196:199], v157 offset:2048
	ds_read_b128 v[200:203], v157 offset:3072
	ds_read_b128 v[204:207], v157 offset:4096
	ds_read_b128 v[208:211], v157 offset:5120
	ds_read_b128 v[212:215], v157 offset:6144
	ds_read_b128 v[216:219], v157 offset:7168
	s_waitcnt vmcnt(8)
	s_waitcnt lgkmcnt(0)
	s_barrier
	s_setprio 1
	s_waitcnt lgkmcnt(0)
	v_mfma_f32_16x16x32_bf16 v[124:127], v[144:147], v[188:191], v[124:127]
	v_mfma_f32_16x16x32_bf16 v[116:119], v[164:167], v[188:191], v[116:119]
	v_mfma_f32_16x16x32_bf16 v[108:111], v[144:147], v[196:199], v[108:111]
	v_mfma_f32_16x16x32_bf16 v[100:103], v[164:167], v[196:199], v[100:103]
	v_mfma_f32_16x16x32_bf16 v[92:95], v[144:147], v[204:207], v[92:95]
	v_mfma_f32_16x16x32_bf16 v[84:87], v[164:167], v[204:207], v[84:87]
	v_mfma_f32_16x16x32_bf16 v[76:79], v[144:147], v[212:215], v[76:79]
	v_mfma_f32_16x16x32_bf16 v[68:71], v[164:167], v[212:215], v[68:71]
	v_mfma_f32_16x16x32_bf16 v[124:127], v[160:163], v[192:195], v[124:127]
	v_mfma_f32_16x16x32_bf16 v[116:119], v[168:171], v[192:195], v[116:119]
	v_mfma_f32_16x16x32_bf16 v[108:111], v[160:163], v[200:203], v[108:111]
	v_mfma_f32_16x16x32_bf16 v[100:103], v[168:171], v[200:203], v[100:103]
	v_mfma_f32_16x16x32_bf16 v[92:95], v[160:163], v[208:211], v[92:95]
	v_mfma_f32_16x16x32_bf16 v[84:87], v[168:171], v[208:211], v[84:87]
	v_mfma_f32_16x16x32_bf16 v[76:79], v[160:163], v[216:219], v[76:79]
	v_mfma_f32_16x16x32_bf16 v[68:71], v[168:171], v[216:219], v[68:71]
	s_setprio 0
	s_setprio 1
	v_mfma_f32_16x16x32_bf16 v[120:123], v[172:175], v[188:191], v[120:123]
	v_mfma_f32_16x16x32_bf16 v[112:115], v[180:183], v[188:191], v[112:115]
	v_mfma_f32_16x16x32_bf16 v[104:107], v[172:175], v[196:199], v[104:107]
	v_mfma_f32_16x16x32_bf16 v[96:99], v[180:183], v[196:199], v[96:99]
	v_mfma_f32_16x16x32_bf16 v[88:91], v[172:175], v[204:207], v[88:91]
	v_mfma_f32_16x16x32_bf16 v[80:83], v[180:183], v[204:207], v[80:83]
	v_mfma_f32_16x16x32_bf16 v[72:75], v[172:175], v[212:215], v[72:75]
	v_mfma_f32_16x16x32_bf16 v[64:67], v[180:183], v[212:215], v[64:67]
	v_mfma_f32_16x16x32_bf16 v[120:123], v[176:179], v[192:195], v[120:123]
	v_mfma_f32_16x16x32_bf16 v[112:115], v[184:187], v[192:195], v[112:115]
	v_mfma_f32_16x16x32_bf16 v[104:107], v[176:179], v[200:203], v[104:107]
	v_mfma_f32_16x16x32_bf16 v[96:99], v[184:187], v[200:203], v[96:99]
	v_mfma_f32_16x16x32_bf16 v[88:91], v[176:179], v[208:211], v[88:91]
	v_mfma_f32_16x16x32_bf16 v[80:83], v[184:187], v[208:211], v[80:83]
	v_mfma_f32_16x16x32_bf16 v[72:75], v[176:179], v[216:219], v[72:75]
	v_mfma_f32_16x16x32_bf16 v[64:67], v[184:187], v[216:219], v[64:67]
	s_setprio 0
	s_barrier
	s_add_i32 s52, s41, s28
	v_lshl_add_u64 v[152:153], s[6:7], 0, v[132:133]
	s_mov_b32 m0, s52
	v_lshl_add_u64 v[220:221], s[6:7], 0, v[128:129]
	global_load_lds_dwordx4 v[152:153], off
	s_add_i32 m0, s52, 0x2000
	s_add_u32 s52, s6, 0x40000
	s_addc_u32 s53, s7, 0
	s_add_i32 s54, s42, s28
	global_load_lds_dwordx4 v[220:221], off
	v_lshl_add_u64 v[222:223], s[52:53], 0, v[132:133]
	s_mov_b32 m0, s54
	v_lshl_add_u64 v[224:225], s[8:9], 0, v[130:131]
	global_load_lds_dwordx4 v[222:223], off
	v_lshl_add_u64 v[222:223], s[52:53], 0, v[128:129]
	s_add_i32 m0, s54, 0x2000
	ds_read_b128 v[188:191], v157 offset:16384
	global_load_lds_dwordx4 v[222:223], off
	v_lshl_add_u64 v[222:223], s[8:9], 0, v[134:135]
	s_mov_b32 m0, s31
	ds_read_b128 v[192:195], v157 offset:17408
	global_load_lds_dwordx4 v[222:223], off
	s_mov_b32 m0, s34
	ds_read_b128 v[196:199], v157 offset:18432
	global_load_lds_dwordx4 v[224:225], off
	ds_read_b128 v[200:203], v157 offset:19456
	ds_read_b128 v[204:207], v157 offset:20480
	ds_read_b128 v[208:211], v157 offset:21504
	ds_read_b128 v[212:215], v157 offset:22528
	ds_read_b128 v[216:219], v157 offset:23552
	s_waitcnt vmcnt(8)
	s_waitcnt lgkmcnt(0)
	s_barrier
; #define PG8_STAGE(bufoff, gbase, voff) do { _Pragma("unroll") for (int _i = 0; _i < 2; ++_i) \
;         __builtin_amdgcn_global_load_lds((const unsigned*)((const char*)(gbase) + (voff)[_i]), (PG8_LAS unsigned*)(lds + (bufoff) + ldsw + _i * 8192), 16, 0, 0); } while (0)
; #define PG8_LDA(dst, b, h) do { _Pragma("unroll") for (int m = 0; m < 4; ++m) _Pragma("unroll") for (int k = 0; k < 2; ++k) dst[m][k] = *(const PG8_LAS bf16x8*)(lds + PG8_SA(b, h) + aoff + m * 2048 + k * 1024); } while (0)
; #define PG8_LDB(dst, b, h) do { _Pragma("unroll") for (int n = 0; n < 2; ++n) _Pragma("unroll") for (int k = 0; k < 2; ++k) dst[n][k] = *(const PG8_LAS bf16x8*)(lds + PG8_SB(b, h) + boff + n * 2048 + k * 1024); } while (0)
; #define PG8_MMA(ai, bj, At, Bt) do { __builtin_amdgcn_s_setprio(1); _Pragma("unroll") for (int m = 0; m < 4; ++m) _Pragma("unroll") for (int n = 0; n < 2; ++n) _Pragma("unroll") for (int k = 0; k < 2; ++k) \
;         acc[ai][bj][m][n] = __builtin_amdgcn_mfma_f32_16x16x32_bf16(Bt[n][k], At[m][k], acc[ai][bj][m][n], 0, 0, 0); __builtin_amdgcn_s_setprio(0); } while (0)
; #define PG8_WAIT_V(n) asm volatile("s_waitcnt vmcnt(" #n ")" ::: "memory")
; #define PG8_WAIT_L(n) asm volatile("s_waitcnt lgkmcnt(" #n ")" ::: "memory")
; #define PG8_BAR __builtin_amdgcn_s_barrier()
; #define PG8_SCHED __builtin_amdgcn_sched_barrier(0)
; template <class Epi, class Sched, bool ALIGN_EPI = false, bool SP2 = false>
; __device__ __forceinline__ void gemm_phase(PG8_LAS unsigned char* lds, const Gemm g, const Sched& S, const Epi& E) {
;     ...
;             PG8_WAIT_V(8); PG8_WAIT_L(0); PG8_BAR; PG8_MMA(1, 0, At, B0); PG8_MMA(1, 1, At, B1); PG8_BAR; PG8_SCHED;
;             PG8_LDB(B0, 1, 0); PG8_LDB(B1, 1, 1); PG8_SCHED; PG8_LDA(At, 1, 0); PG8_STAGE(PG8_SA(0, 1), a2 + hstep, voffA);
;             PG8_WAIT_V(8); PG8_WAIT_L(0); PG8_BAR; PG8_MMA(0, 0, At, B0); PG8_MMA(0, 1, At, B1); PG8_BAR; PG8_SCHED;
	s_setprio 1
	s_waitcnt lgkmcnt(0)
	v_mfma_f32_16x16x32_bf16 v[60:63], v[144:147], v[188:191], v[60:63]
	v_mfma_f32_16x16x32_bf16 v[52:55], v[164:167], v[188:191], v[52:55]
	v_mfma_f32_16x16x32_bf16 v[44:47], v[144:147], v[196:199], v[44:47]
	v_mfma_f32_16x16x32_bf16 v[36:39], v[164:167], v[196:199], v[36:39]
	v_mfma_f32_16x16x32_bf16 v[28:31], v[144:147], v[204:207], v[28:31]
	v_mfma_f32_16x16x32_bf16 v[20:23], v[164:167], v[204:207], v[20:23]
	v_mfma_f32_16x16x32_bf16 v[12:15], v[144:147], v[212:215], v[12:15]
	v_mfma_f32_16x16x32_bf16 v[4:7], v[164:167], v[212:215], v[4:7]
	v_mfma_f32_16x16x32_bf16 v[60:63], v[160:163], v[192:195], v[60:63]
	v_mfma_f32_16x16x32_bf16 v[52:55], v[168:171], v[192:195], v[52:55]
	v_mfma_f32_16x16x32_bf16 v[44:47], v[160:163], v[200:203], v[44:47]
	v_mfma_f32_16x16x32_bf16 v[36:39], v[168:171], v[200:203], v[36:39]
	v_mfma_f32_16x16x32_bf16 v[28:31], v[160:163], v[208:211], v[28:31]
	v_mfma_f32_16x16x32_bf16 v[20:23], v[168:171], v[208:211], v[20:23]
	v_mfma_f32_16x16x32_bf16 v[12:15], v[160:163], v[216:219], v[12:15]
	v_mfma_f32_16x16x32_bf16 v[4:7], v[168:171], v[216:219], v[4:7]
	s_setprio 0
	s_setprio 1
	v_mfma_f32_16x16x32_bf16 v[56:59], v[172:175], v[188:191], v[56:59]
	v_mfma_f32_16x16x32_bf16 v[48:51], v[180:183], v[188:191], v[48:51]
	v_mfma_f32_16x16x32_bf16 v[40:43], v[172:175], v[196:199], v[40:43]
	v_mfma_f32_16x16x32_bf16 v[32:35], v[180:183], v[196:199], v[32:35]
	v_mfma_f32_16x16x32_bf16 v[24:27], v[172:175], v[204:207], v[24:27]
	v_mfma_f32_16x16x32_bf16 v[16:19], v[180:183], v[204:207], v[16:19]
	v_mfma_f32_16x16x32_bf16 v[8:11], v[172:175], v[212:215], v[8:11]
	v_mfma_f32_16x16x32_bf16 v[0:3], v[180:183], v[212:215], v[0:3]
	v_mfma_f32_16x16x32_bf16 v[56:59], v[176:179], v[192:195], v[56:59]
	v_mfma_f32_16x16x32_bf16 v[48:51], v[184:187], v[192:195], v[48:51]
	v_mfma_f32_16x16x32_bf16 v[40:43], v[176:179], v[200:203], v[40:43]
	v_mfma_f32_16x16x32_bf16 v[32:35], v[184:187], v[200:203], v[32:35]
	v_mfma_f32_16x16x32_bf16 v[24:27], v[176:179], v[208:211], v[24:27]
	v_mfma_f32_16x16x32_bf16 v[16:19], v[184:187], v[208:211], v[16:19]
	v_mfma_f32_16x16x32_bf16 v[8:11], v[176:179], v[216:219], v[8:11]
	v_mfma_f32_16x16x32_bf16 v[0:3], v[184:187], v[216:219], v[0:3]
	s_setprio 0
	s_barrier
	s_add_i32 s52, 0, 0x18000
	s_add_i32 s53, 0, 0x1c000
	s_add_u32 s8, s8, 0x40000
	s_addc_u32 s9, s9, 0
	s_mov_b32 m0, s35
	v_lshl_add_u64 v[226:227], s[8:9], 0, v[134:135]
	global_load_lds_dwordx4 v[226:227], off
	v_lshl_add_u64 v[226:227], s[8:9], 0, v[130:131]
	s_mov_b32 m0, s36
	v_add_u32_e32 v159, s52, v151
	global_load_lds_dwordx4 v[226:227], off
	ds_read_b128 v[144:147], v159
	ds_read_b128 v[160:163], v159 offset:1024
	ds_read_b128 v[164:167], v159 offset:2048
	ds_read_b128 v[168:171], v159 offset:3072
	v_add_u32_e32 v159, s53, v151
	ds_read_b128 v[172:175], v159
	ds_read_b128 v[176:179], v159 offset:1024
	ds_read_b128 v[180:183], v159 offset:2048
	ds_read_b128 v[184:187], v159 offset:3072
	ds_read_b128 v[188:191], v157 offset:32768
	ds_read_b128 v[192:195], v157 offset:33792
	ds_read_b128 v[196:199], v157 offset:34816
	ds_read_b128 v[200:203], v157 offset:35840
	ds_read_b128 v[204:207], v157 offset:36864
	ds_read_b128 v[208:211], v157 offset:37888
	ds_read_b128 v[212:215], v157 offset:38912
	ds_read_b128 v[216:219], v157 offset:39936
	s_waitcnt vmcnt(8)
	s_waitcnt lgkmcnt(0)
	s_barrier
	s_setprio 1
	s_waitcnt lgkmcnt(0)
	v_mfma_f32_16x16x32_bf16 v[124:127], v[144:147], v[188:191], v[124:127]
	v_mfma_f32_16x16x32_bf16 v[116:119], v[164:167], v[188:191], v[116:119]
	v_mfma_f32_16x16x32_bf16 v[108:111], v[144:147], v[196:199], v[108:111]
	v_mfma_f32_16x16x32_bf16 v[100:103], v[164:167], v[196:199], v[100:103]
	v_mfma_f32_16x16x32_bf16 v[92:95], v[144:147], v[204:207], v[92:95]
	v_mfma_f32_16x16x32_bf16 v[84:87], v[164:167], v[204:207], v[84:87]
	v_mfma_f32_16x16x32_bf16 v[76:79], v[144:147], v[212:215], v[76:79]
	v_mfma_f32_16x16x32_bf16 v[68:71], v[164:167], v[212:215], v[68:71]
	v_mfma_f32_16x16x32_bf16 v[124:127], v[160:163], v[192:195], v[124:127]
	v_mfma_f32_16x16x32_bf16 v[116:119], v[168:171], v[192:195], v[116:119]
	v_mfma_f32_16x16x32_bf16 v[108:111], v[160:163], v[200:203], v[108:111]
	v_mfma_f32_16x16x32_bf16 v[100:103], v[168:171], v[200:203], v[100:103]
	v_mfma_f32_16x16x32_bf16 v[92:95], v[160:163], v[208:211], v[92:95]
	v_mfma_f32_16x16x32_bf16 v[84:87], v[168:171], v[208:211], v[84:87]
	v_mfma_f32_16x16x32_bf16 v[76:79], v[160:163], v[216:219], v[76:79]
	v_mfma_f32_16x16x32_bf16 v[68:71], v[168:171], v[216:219], v[68:71]
	s_setprio 0
	s_setprio 1
	v_mfma_f32_16x16x32_bf16 v[120:123], v[172:175], v[188:191], v[120:123]
	v_mfma_f32_16x16x32_bf16 v[112:115], v[180:183], v[188:191], v[112:115]
	v_mfma_f32_16x16x32_bf16 v[104:107], v[172:175], v[196:199], v[104:107]
	v_mfma_f32_16x16x32_bf16 v[96:99], v[180:183], v[196:199], v[96:99]
	v_mfma_f32_16x16x32_bf16 v[88:91], v[172:175], v[204:207], v[88:91]
	v_mfma_f32_16x16x32_bf16 v[80:83], v[180:183], v[204:207], v[80:83]
	v_mfma_f32_16x16x32_bf16 v[72:75], v[172:175], v[212:215], v[72:75]
	v_mfma_f32_16x16x32_bf16 v[64:67], v[180:183], v[212:215], v[64:67]
	v_mfma_f32_16x16x32_bf16 v[120:123], v[176:179], v[192:195], v[120:123]
	v_mfma_f32_16x16x32_bf16 v[112:115], v[184:187], v[192:195], v[112:115]
	v_mfma_f32_16x16x32_bf16 v[104:107], v[176:179], v[200:203], v[104:107]
	v_mfma_f32_16x16x32_bf16 v[96:99], v[184:187], v[200:203], v[96:99]
	v_mfma_f32_16x16x32_bf16 v[88:91], v[176:179], v[208:211], v[88:91]
	v_mfma_f32_16x16x32_bf16 v[80:83], v[184:187], v[208:211], v[80:83]
	v_mfma_f32_16x16x32_bf16 v[72:75], v[176:179], v[216:219], v[72:75]
	v_mfma_f32_16x16x32_bf16 v[64:67], v[184:187], v[216:219], v[64:67]
	s_setprio 0
	s_barrier
; #define PG8_STAGE(bufoff, gbase, voff) do { _Pragma("unroll") for (int _i = 0; _i < 2; ++_i) \
;         __builtin_amdgcn_global_load_lds((const unsigned*)((const char*)(gbase) + (voff)[_i]), (PG8_LAS unsigned*)(lds + (bufoff) + ldsw + _i * 8192), 16, 0, 0); } while (0)
; #define PG8_LDA(dst, b, h) do { _Pragma("unroll") for (int m = 0; m < 4; ++m) _Pragma("unroll") for (int k = 0; k < 2; ++k) dst[m][k] = *(const PG8_LAS bf16x8*)(lds + PG8_SA(b, h) + aoff + m * 2048 + k * 1024); } while (0)
; #define PG8_MMA(ai, bj, At, Bt) do { __builtin_amdgcn_s_setprio(1); _Pragma("unroll") for (int m = 0; m < 4; ++m) _Pragma("unroll") for (int n = 0; n < 2; ++n) _Pragma("unroll") for (int k = 0; k < 2; ++k) \
;         acc[ai][bj][m][n] = __builtin_amdgcn_mfma_f32_16x16x32_bf16(Bt[n][k], At[m][k], acc[ai][bj][m][n], 0, 0, 0); __builtin_amdgcn_s_setprio(0); } while (0)
; #define PG8_WAIT_V(n) asm volatile("s_waitcnt vmcnt(" #n ")" ::: "memory")
; #define PG8_WAIT_L(n) asm volatile("s_waitcnt lgkmcnt(" #n ")" ::: "memory")
; #define PG8_BAR __builtin_amdgcn_s_barrier()
; #define PG8_SCHED __builtin_amdgcn_sched_barrier(0)
; template <class Epi, class Sched, bool ALIGN_EPI = false, bool SP2 = false>
; __device__ __forceinline__ void gemm_phase(PG8_LAS unsigned char* lds, const Gemm g, const Sched& S, const Epi& E) {
;     ...
;             PG8_LDA(At, 1, 1); PG8_STAGE(PG8_SB(1, 0), b3, voffB); PG8_STAGE(PG8_SB(1, 1), b3 + hstep, voffB); PG8_STAGE(PG8_SA(1, 0), a3, voffA);
;             PG8_WAIT_V(8); PG8_WAIT_L(0); PG8_BAR; PG8_MMA(1, 0, At, B0); PG8_MMA(1, 1, At, B1); PG8_BAR; PG8_SCHED;
;     ...
;         if constexpr (ALIGN_EPI) { if (wr == 0) PG8_BAR; }
	s_add_i32 s8, s52, s28
	v_lshl_add_u64 v[152:153], v[152:153], 0, s[16:17]
	s_mov_b32 m0, s8
	ds_read_b128 v[188:191], v157 offset:49152
	global_load_lds_dwordx4 v[152:153], off
	s_add_i32 m0, s8, 0x2000
	s_add_u32 s6, s6, 0x40080
	v_lshl_add_u64 v[152:153], v[220:221], 0, s[16:17]
	s_addc_u32 s7, s7, 0
	s_add_i32 s8, s53, s28
	global_load_lds_dwordx4 v[152:153], off
	v_lshl_add_u64 v[152:153], s[6:7], 0, v[132:133]
	s_mov_b32 m0, s8
	ds_read_b128 v[192:195], v157 offset:50176
	global_load_lds_dwordx4 v[152:153], off
	v_lshl_add_u64 v[152:153], s[6:7], 0, v[128:129]
	s_add_i32 m0, s8, 0x2000
	ds_read_b128 v[196:199], v157 offset:51200
	global_load_lds_dwordx4 v[152:153], off
	v_lshl_add_u64 v[152:153], v[222:223], 0, s[16:17]
	s_mov_b32 m0, s38
	ds_read_b128 v[200:203], v157 offset:52224
	global_load_lds_dwordx4 v[152:153], off
	v_lshl_add_u64 v[152:153], v[224:225], 0, s[16:17]
	s_mov_b32 m0, s39
	ds_read_b128 v[204:207], v157 offset:53248
	global_load_lds_dwordx4 v[152:153], off
	ds_read_b128 v[208:211], v157 offset:54272
	ds_read_b128 v[212:215], v157 offset:55296
	ds_read_b128 v[216:219], v157 offset:56320
	s_waitcnt vmcnt(8)
	s_waitcnt lgkmcnt(0)
	s_barrier
	s_setprio 1
	s_waitcnt lgkmcnt(0)
	v_mfma_f32_16x16x32_bf16 v[60:63], v[144:147], v[188:191], v[60:63]
	v_mfma_f32_16x16x32_bf16 v[52:55], v[164:167], v[188:191], v[52:55]
	v_mfma_f32_16x16x32_bf16 v[44:47], v[144:147], v[196:199], v[44:47]
	v_mfma_f32_16x16x32_bf16 v[36:39], v[164:167], v[196:199], v[36:39]
	v_mfma_f32_16x16x32_bf16 v[28:31], v[144:147], v[204:207], v[28:31]
	v_mfma_f32_16x16x32_bf16 v[20:23], v[164:167], v[204:207], v[20:23]
	v_mfma_f32_16x16x32_bf16 v[12:15], v[144:147], v[212:215], v[12:15]
	v_mfma_f32_16x16x32_bf16 v[4:7], v[164:167], v[212:215], v[4:7]
	v_mfma_f32_16x16x32_bf16 v[60:63], v[160:163], v[192:195], v[60:63]
	v_mfma_f32_16x16x32_bf16 v[52:55], v[168:171], v[192:195], v[52:55]
	v_mfma_f32_16x16x32_bf16 v[44:47], v[160:163], v[200:203], v[44:47]
	v_mfma_f32_16x16x32_bf16 v[36:39], v[168:171], v[200:203], v[36:39]
	v_mfma_f32_16x16x32_bf16 v[28:31], v[160:163], v[208:211], v[28:31]
	v_mfma_f32_16x16x32_bf16 v[20:23], v[168:171], v[208:211], v[20:23]
	v_mfma_f32_16x16x32_bf16 v[12:15], v[160:163], v[216:219], v[12:15]
	v_mfma_f32_16x16x32_bf16 v[4:7], v[168:171], v[216:219], v[4:7]
	s_setprio 0
	s_setprio 1
	v_mfma_f32_16x16x32_bf16 v[56:59], v[172:175], v[188:191], v[56:59]
	v_mfma_f32_16x16x32_bf16 v[48:51], v[180:183], v[188:191], v[48:51]
	v_mfma_f32_16x16x32_bf16 v[40:43], v[172:175], v[196:199], v[40:43]
	v_mfma_f32_16x16x32_bf16 v[32:35], v[180:183], v[196:199], v[32:35]
	v_mfma_f32_16x16x32_bf16 v[24:27], v[172:175], v[204:207], v[24:27]
	v_mfma_f32_16x16x32_bf16 v[16:19], v[180:183], v[204:207], v[16:19]
	v_mfma_f32_16x16x32_bf16 v[8:11], v[172:175], v[212:215], v[8:11]
	v_mfma_f32_16x16x32_bf16 v[0:3], v[180:183], v[212:215], v[0:3]
	v_mfma_f32_16x16x32_bf16 v[56:59], v[176:179], v[192:195], v[56:59]
	v_mfma_f32_16x16x32_bf16 v[48:51], v[184:187], v[192:195], v[48:51]
	v_mfma_f32_16x16x32_bf16 v[40:43], v[176:179], v[200:203], v[40:43]
	v_mfma_f32_16x16x32_bf16 v[32:35], v[184:187], v[200:203], v[32:35]
	v_mfma_f32_16x16x32_bf16 v[24:27], v[176:179], v[208:211], v[24:27]
	v_mfma_f32_16x16x32_bf16 v[16:19], v[184:187], v[208:211], v[16:19]
	v_mfma_f32_16x16x32_bf16 v[8:11], v[176:179], v[216:219], v[8:11]
	v_mfma_f32_16x16x32_bf16 v[0:3], v[184:187], v[216:219], v[0:3]
	s_setprio 0
	s_barrier
	s_add_i32 s51, s51, 2
	s_add_u32 s4, s4, 0x100
	s_addc_u32 s5, s5, 0
	s_add_u32 s45, s45, 0x100
	s_addc_u32 s50, s50, 0
	s_cmp_gt_u32 s51, 13
	s_cbranch_scc0 .LBB0_1487
	s_nop 0
	s_nop 0
	s_nop 0
	s_nop 0
	s_nop 0
	s_nop 0
	s_nop 0
	s_nop 0
	s_nop 0
	s_and_b64 vcc, exec, s[18:19]
	s_cbranch_vccz .LBB0_1490
	s_barrier

; #define PG8_STAGE(bufoff, gbase, voff) do { _Pragma("unroll") for (int _i = 0; _i < 2; ++_i) \
;         __builtin_amdgcn_global_load_lds((const unsigned*)((const char*)(gbase) + (voff)[_i]), (PG8_LAS unsigned*)(lds + (bufoff) + ldsw + _i * 8192), 16, 0, 0); } while (0)
; #define PG8_LDA(dst, b, h) do { _Pragma("unroll") for (int m = 0; m < 4; ++m) _Pragma("unroll") for (int k = 0; k < 2; ++k) dst[m][k] = *(const PG8_LAS bf16x8*)(lds + PG8_SA(b, h) + aoff + m * 2048 + k * 1024); } while (0)
; #define PG8_LDB(dst, b, h) do { _Pragma("unroll") for (int n = 0; n < 2; ++n) _Pragma("unroll") for (int k = 0; k < 2; ++k) dst[n][k] = *(const PG8_LAS bf16x8*)(lds + PG8_SB(b, h) + boff + n * 2048 + k * 1024); } while (0)
; #define PG8_MMA(ai, bj, At, Bt) do { __builtin_amdgcn_s_setprio(1); _Pragma("unroll") for (int m = 0; m < 4; ++m) _Pragma("unroll") for (int n = 0; n < 2; ++n) _Pragma("unroll") for (int k = 0; k < 2; ++k) \
;         acc[ai][bj][m][n] = __builtin_amdgcn_mfma_f32_16x16x32_bf16(Bt[n][k], At[m][k], acc[ai][bj][m][n], 0, 0, 0); __builtin_amdgcn_s_setprio(0); } while (0)
; #define PG8_WAIT_V(n) asm volatile("s_waitcnt vmcnt(" #n ")" ::: "memory")
; #define PG8_WAIT_L(n) asm volatile("s_waitcnt lgkmcnt(" #n ")" ::: "memory")
; template <class Epi, class Sched, bool ALIGN_EPI = false, bool SP2 = false>
; __device__ __forceinline__ void gemm_phase(PG8_LAS unsigned char* lds, const Gemm g, const Sched& S, const Epi& E) {
;     ...
;             const bool last = (t == nt - 2);
;             const char* a1 = cA + (size_t)(t + 1) * kstep;
;             const char* a2 = last ? nA : cA + (size_t)(t + 2) * kstep; const char* b2 = last ? nB : cB + (size_t)(t + 2) * kstep;
;             const char* a3 = a2 + kstep; const char* b3 = b2 + kstep;
;             if (last && has_next) S.a_ready(nxt);
;             if constexpr (SP2) {
;             PG8_LDB(B0, 0, 0); PG8_LDB(B1, 0, 1); PG8_SCHED; PG8_LDA(At, 0, 0); PG8_STAGE(PG8_SA(1, 1), a1 + hstep, voffA);
;             PG8_WAIT_V(8); PG8_WAIT_L(0); PG8_BAR; PG8_MMA(0, 0, At, B0); PG8_MMA(0, 1, At, B1); PG8_BAR; PG8_SCHED;
;             PG8_LDA(At, 0, 1); PG8_STAGE(PG8_SB(0, 0), b2, voffB); PG8_STAGE(PG8_SB(0, 1), b2 + hstep, voffB); PG8_STAGE(PG8_SA(0, 0), a2, voffA);
;             PG8_WAIT_V(8); PG8_WAIT_L(0); PG8_BAR; PG8_MMA(1, 0, At, B0); PG8_MMA(1, 1, At, B1); PG8_BAR; PG8_SCHED;
.LBB0_1572:
	v_lshl_add_u64 v[214:215], s[20:21], 0, v[132:133]
	s_add_i32 m0, s27, 0xc000
	ds_read_b128 v[140:143], v189
	global_load_lds_dwordx4 v[214:215], off
	v_lshl_add_u64 v[214:215], s[20:21], 0, v[134:135]
	s_add_i32 m0, s27, 0xe000
	ds_read_b128 v[144:147], v189 offset:1024
	global_load_lds_dwordx4 v[214:215], off
	s_add_u32 s22, s20, 0xfff50080
	s_addc_u32 s23, s21, -1
	s_cmp_eq_u32 s47, 40
	s_cselect_b32 s25, s1, s23
	s_cselect_b32 s24, s0, s22
	s_cselect_b32 s23, s19, s46
	s_cselect_b32 s22, s18, s45
	ds_read_b128 v[152:155], v189 offset:2048
	ds_read_b128 v[156:159], v189 offset:3072
	ds_read_b128 v[160:163], v190
	ds_read_b128 v[164:167], v190 offset:1024
	ds_read_b128 v[168:171], v190 offset:2048
	ds_read_b128 v[172:175], v190 offset:3072
	ds_read_b128 v[176:179], v191
	ds_read_b128 v[180:183], v191 offset:1024
	ds_read_b128 v[184:187], v191 offset:2048
	ds_read_b128 v[194:197], v191 offset:3072
	ds_read_b128 v[198:201], v191 offset:4096
	ds_read_b128 v[202:205], v191 offset:5120
	ds_read_b128 v[206:209], v191 offset:6144
	ds_read_b128 v[210:213], v191 offset:7168
	s_waitcnt vmcnt(8)
	s_waitcnt lgkmcnt(0)
	s_barrier
	s_setprio 1
	s_waitcnt lgkmcnt(0)
	v_mfma_f32_16x16x32_bf16 v[124:127], v[140:143], v[176:179], v[124:127]
	v_mfma_f32_16x16x32_bf16 v[120:123], v[152:155], v[176:179], v[120:123]
	v_mfma_f32_16x16x32_bf16 v[108:111], v[140:143], v[184:187], v[108:111]
	v_mfma_f32_16x16x32_bf16 v[104:107], v[152:155], v[184:187], v[104:107]
	v_mfma_f32_16x16x32_bf16 v[92:95], v[140:143], v[198:201], v[92:95]
	v_mfma_f32_16x16x32_bf16 v[88:91], v[152:155], v[198:201], v[88:91]
	v_mfma_f32_16x16x32_bf16 v[76:79], v[140:143], v[206:209], v[76:79]
	v_mfma_f32_16x16x32_bf16 v[72:75], v[152:155], v[206:209], v[72:75]
	v_mfma_f32_16x16x32_bf16 v[124:127], v[144:147], v[180:183], v[124:127]
	v_mfma_f32_16x16x32_bf16 v[120:123], v[156:159], v[180:183], v[120:123]
	v_mfma_f32_16x16x32_bf16 v[108:111], v[144:147], v[194:197], v[108:111]
	v_mfma_f32_16x16x32_bf16 v[104:107], v[156:159], v[194:197], v[104:107]
	v_mfma_f32_16x16x32_bf16 v[92:95], v[144:147], v[202:205], v[92:95]
	v_mfma_f32_16x16x32_bf16 v[88:91], v[156:159], v[202:205], v[88:91]
	v_mfma_f32_16x16x32_bf16 v[76:79], v[144:147], v[210:213], v[76:79]
	v_mfma_f32_16x16x32_bf16 v[72:75], v[156:159], v[210:213], v[72:75]
	s_setprio 0
	s_setprio 1
	v_mfma_f32_16x16x32_bf16 v[116:119], v[160:163], v[176:179], v[116:119]
	v_mfma_f32_16x16x32_bf16 v[112:115], v[168:171], v[176:179], v[112:115]
	v_mfma_f32_16x16x32_bf16 v[100:103], v[160:163], v[184:187], v[100:103]
	v_mfma_f32_16x16x32_bf16 v[96:99], v[168:171], v[184:187], v[96:99]
	v_mfma_f32_16x16x32_bf16 v[84:87], v[160:163], v[198:201], v[84:87]
	v_mfma_f32_16x16x32_bf16 v[80:83], v[168:171], v[198:201], v[80:83]
	v_mfma_f32_16x16x32_bf16 v[68:71], v[160:163], v[206:209], v[68:71]
	v_mfma_f32_16x16x32_bf16 v[64:67], v[168:171], v[206:209], v[64:67]
	v_mfma_f32_16x16x32_bf16 v[116:119], v[164:167], v[180:183], v[116:119]
	v_mfma_f32_16x16x32_bf16 v[112:115], v[172:175], v[180:183], v[112:115]
	v_mfma_f32_16x16x32_bf16 v[100:103], v[164:167], v[194:197], v[100:103]
	v_mfma_f32_16x16x32_bf16 v[96:99], v[172:175], v[194:197], v[96:99]
	v_mfma_f32_16x16x32_bf16 v[84:87], v[164:167], v[202:205], v[84:87]
	v_mfma_f32_16x16x32_bf16 v[80:83], v[172:175], v[202:205], v[80:83]
	v_mfma_f32_16x16x32_bf16 v[68:71], v[164:167], v[210:213], v[68:71]
	v_mfma_f32_16x16x32_bf16 v[64:67], v[172:175], v[210:213], v[64:67]
	s_setprio 0
	s_barrier
	s_add_i32 s50, s38, s26
	v_lshl_add_u64 v[214:215], s[22:23], 0, v[128:129]
	s_mov_b32 m0, s50
	v_lshl_add_u64 v[216:217], s[22:23], 0, v[130:131]
	global_load_lds_dwordx4 v[214:215], off
	s_add_i32 m0, s50, 0x2000
	s_add_u32 s50, s22, 0xb0000
	s_addc_u32 s51, s23, 0
	s_add_i32 s52, s39, s26
	global_load_lds_dwordx4 v[216:217], off
	v_lshl_add_u64 v[218:219], s[50:51], 0, v[128:129]
	s_mov_b32 m0, s52
	v_lshl_add_u64 v[220:221], s[24:25], 0, v[130:131]
	global_load_lds_dwordx4 v[218:219], off
	v_lshl_add_u64 v[218:219], s[50:51], 0, v[130:131]
	s_add_i32 m0, s52, 0x2000
	ds_read_b128 v[176:179], v191 offset:16384
	global_load_lds_dwordx4 v[218:219], off
	v_lshl_add_u64 v[218:219], s[24:25], 0, v[128:129]
	s_mov_b32 m0, s27
	ds_read_b128 v[180:183], v191 offset:17408
	global_load_lds_dwordx4 v[218:219], off
	s_mov_b32 m0, s28
	ds_read_b128 v[184:187], v191 offset:18432
	global_load_lds_dwordx4 v[220:221], off
	ds_read_b128 v[194:197], v191 offset:19456
	ds_read_b128 v[198:201], v191 offset:20480
	ds_read_b128 v[202:205], v191 offset:21504
	ds_read_b128 v[206:209], v191 offset:22528
	ds_read_b128 v[210:213], v191 offset:23552
	s_waitcnt vmcnt(8)
	s_waitcnt lgkmcnt(0)
	s_barrier
; #define PG8_STAGE(bufoff, gbase, voff) do { _Pragma("unroll") for (int _i = 0; _i < 2; ++_i) \
;         __builtin_amdgcn_global_load_lds((const unsigned*)((const char*)(gbase) + (voff)[_i]), (PG8_LAS unsigned*)(lds + (bufoff) + ldsw + _i * 8192), 16, 0, 0); } while (0)
; #define PG8_LDA(dst, b, h) do { _Pragma("unroll") for (int m = 0; m < 4; ++m) _Pragma("unroll") for (int k = 0; k < 2; ++k) dst[m][k] = *(const PG8_LAS bf16x8*)(lds + PG8_SA(b, h) + aoff + m * 2048 + k * 1024); } while (0)
; #define PG8_LDB(dst, b, h) do { _Pragma("unroll") for (int n = 0; n < 2; ++n) _Pragma("unroll") for (int k = 0; k < 2; ++k) dst[n][k] = *(const PG8_LAS bf16x8*)(lds + PG8_SB(b, h) + boff + n * 2048 + k * 1024); } while (0)
; #define PG8_MMA(ai, bj, At, Bt) do { __builtin_amdgcn_s_setprio(1); _Pragma("unroll") for (int m = 0; m < 4; ++m) _Pragma("unroll") for (int n = 0; n < 2; ++n) _Pragma("unroll") for (int k = 0; k < 2; ++k) \
;         acc[ai][bj][m][n] = __builtin_amdgcn_mfma_f32_16x16x32_bf16(Bt[n][k], At[m][k], acc[ai][bj][m][n], 0, 0, 0); __builtin_amdgcn_s_setprio(0); } while (0)
; #define PG8_WAIT_V(n) asm volatile("s_waitcnt vmcnt(" #n ")" ::: "memory")
; #define PG8_WAIT_L(n) asm volatile("s_waitcnt lgkmcnt(" #n ")" ::: "memory")
; #define PG8_BAR __builtin_amdgcn_s_barrier()
; #define PG8_SCHED __builtin_amdgcn_sched_barrier(0)
; template <class Epi, class Sched, bool ALIGN_EPI = false, bool SP2 = false>
; __device__ __forceinline__ void gemm_phase(PG8_LAS unsigned char* lds, const Gemm g, const Sched& S, const Epi& E) {
;     ...
;             PG8_WAIT_V(8); PG8_WAIT_L(0); PG8_BAR; PG8_MMA(1, 0, At, B0); PG8_MMA(1, 1, At, B1); PG8_BAR; PG8_SCHED;
;             PG8_LDB(B0, 1, 0); PG8_LDB(B1, 1, 1); PG8_SCHED; PG8_LDA(At, 1, 0); PG8_STAGE(PG8_SA(0, 1), a2 + hstep, voffA);
;             PG8_WAIT_V(8); PG8_WAIT_L(0); PG8_BAR; PG8_MMA(0, 0, At, B0); PG8_MMA(0, 1, At, B1); PG8_BAR; PG8_SCHED;
	s_setprio 1
	s_waitcnt lgkmcnt(0)
	v_mfma_f32_16x16x32_bf16 v[60:63], v[140:143], v[176:179], v[60:63]
	v_mfma_f32_16x16x32_bf16 v[56:59], v[152:155], v[176:179], v[56:59]
	v_mfma_f32_16x16x32_bf16 v[44:47], v[140:143], v[184:187], v[44:47]
	v_mfma_f32_16x16x32_bf16 v[40:43], v[152:155], v[184:187], v[40:43]
	v_mfma_f32_16x16x32_bf16 v[28:31], v[140:143], v[198:201], v[28:31]
	v_mfma_f32_16x16x32_bf16 v[24:27], v[152:155], v[198:201], v[24:27]
	v_mfma_f32_16x16x32_bf16 v[12:15], v[140:143], v[206:209], v[12:15]
	v_mfma_f32_16x16x32_bf16 v[8:11], v[152:155], v[206:209], v[8:11]
	v_mfma_f32_16x16x32_bf16 v[60:63], v[144:147], v[180:183], v[60:63]
	v_mfma_f32_16x16x32_bf16 v[56:59], v[156:159], v[180:183], v[56:59]
	v_mfma_f32_16x16x32_bf16 v[44:47], v[144:147], v[194:197], v[44:47]
	v_mfma_f32_16x16x32_bf16 v[40:43], v[156:159], v[194:197], v[40:43]
	v_mfma_f32_16x16x32_bf16 v[28:31], v[144:147], v[202:205], v[28:31]
	v_mfma_f32_16x16x32_bf16 v[24:27], v[156:159], v[202:205], v[24:27]
	v_mfma_f32_16x16x32_bf16 v[12:15], v[144:147], v[210:213], v[12:15]
	v_mfma_f32_16x16x32_bf16 v[8:11], v[156:159], v[210:213], v[8:11]
	s_setprio 0
	s_setprio 1
	v_mfma_f32_16x16x32_bf16 v[52:55], v[160:163], v[176:179], v[52:55]
	v_mfma_f32_16x16x32_bf16 v[48:51], v[168:171], v[176:179], v[48:51]
	v_mfma_f32_16x16x32_bf16 v[36:39], v[160:163], v[184:187], v[36:39]
	v_mfma_f32_16x16x32_bf16 v[32:35], v[168:171], v[184:187], v[32:35]
	v_mfma_f32_16x16x32_bf16 v[20:23], v[160:163], v[198:201], v[20:23]
	v_mfma_f32_16x16x32_bf16 v[16:19], v[168:171], v[198:201], v[16:19]
	v_mfma_f32_16x16x32_bf16 v[4:7], v[160:163], v[206:209], v[4:7]
	v_mfma_f32_16x16x32_bf16 v[0:3], v[168:171], v[206:209], v[0:3]
	v_mfma_f32_16x16x32_bf16 v[52:55], v[164:167], v[180:183], v[52:55]
	v_mfma_f32_16x16x32_bf16 v[48:51], v[172:175], v[180:183], v[48:51]
	v_mfma_f32_16x16x32_bf16 v[36:39], v[164:167], v[194:197], v[36:39]
	v_mfma_f32_16x16x32_bf16 v[32:35], v[172:175], v[194:197], v[32:35]
	v_mfma_f32_16x16x32_bf16 v[20:23], v[164:167], v[202:205], v[20:23]
	v_mfma_f32_16x16x32_bf16 v[16:19], v[172:175], v[202:205], v[16:19]
	v_mfma_f32_16x16x32_bf16 v[4:7], v[164:167], v[210:213], v[4:7]
	v_mfma_f32_16x16x32_bf16 v[0:3], v[172:175], v[210:213], v[0:3]
	s_setprio 0
	s_barrier
	s_add_i32 s50, 0, 0x18000
	s_add_i32 s51, 0, 0x1c000
	s_add_u32 s24, s24, 0xb0000
	s_addc_u32 s25, s25, 0
	s_mov_b32 m0, s29
	v_lshl_add_u64 v[222:223], s[24:25], 0, v[128:129]
	global_load_lds_dwordx4 v[222:223], off
	v_lshl_add_u64 v[222:223], s[24:25], 0, v[130:131]
	s_mov_b32 m0, s30
	v_add_u32_e32 v156, s50, v151
	global_load_lds_dwordx4 v[222:223], off
	v_add_u32_e32 v172, s51, v151
	ds_read_b128 v[140:143], v156
	ds_read_b128 v[144:147], v156 offset:1024
	ds_read_b128 v[152:155], v156 offset:2048
	ds_read_b128 v[156:159], v156 offset:3072
	ds_read_b128 v[160:163], v172
	ds_read_b128 v[164:167], v172 offset:1024
	ds_read_b128 v[168:171], v172 offset:2048
	ds_read_b128 v[172:175], v172 offset:3072
	ds_read_b128 v[176:179], v191 offset:32768
	ds_read_b128 v[180:183], v191 offset:33792
	ds_read_b128 v[184:187], v191 offset:34816
	ds_read_b128 v[194:197], v191 offset:35840
	ds_read_b128 v[198:201], v191 offset:36864
	ds_read_b128 v[202:205], v191 offset:37888
	ds_read_b128 v[206:209], v191 offset:38912
	ds_read_b128 v[210:213], v191 offset:39936
	s_waitcnt vmcnt(8)
	s_waitcnt lgkmcnt(0)
	s_barrier
	s_setprio 1
	s_waitcnt lgkmcnt(0)
	v_mfma_f32_16x16x32_bf16 v[124:127], v[140:143], v[176:179], v[124:127]
	v_mfma_f32_16x16x32_bf16 v[120:123], v[152:155], v[176:179], v[120:123]
	v_mfma_f32_16x16x32_bf16 v[108:111], v[140:143], v[184:187], v[108:111]
	v_mfma_f32_16x16x32_bf16 v[104:107], v[152:155], v[184:187], v[104:107]
	v_mfma_f32_16x16x32_bf16 v[92:95], v[140:143], v[198:201], v[92:95]
	v_mfma_f32_16x16x32_bf16 v[88:91], v[152:155], v[198:201], v[88:91]
	v_mfma_f32_16x16x32_bf16 v[76:79], v[140:143], v[206:209], v[76:79]
	v_mfma_f32_16x16x32_bf16 v[72:75], v[152:155], v[206:209], v[72:75]
	v_mfma_f32_16x16x32_bf16 v[124:127], v[144:147], v[180:183], v[124:127]
	v_mfma_f32_16x16x32_bf16 v[120:123], v[156:159], v[180:183], v[120:123]
	v_mfma_f32_16x16x32_bf16 v[108:111], v[144:147], v[194:197], v[108:111]
	v_mfma_f32_16x16x32_bf16 v[104:107], v[156:159], v[194:197], v[104:107]
	v_mfma_f32_16x16x32_bf16 v[92:95], v[144:147], v[202:205], v[92:95]
	v_mfma_f32_16x16x32_bf16 v[88:91], v[156:159], v[202:205], v[88:91]
	v_mfma_f32_16x16x32_bf16 v[76:79], v[144:147], v[210:213], v[76:79]
	v_mfma_f32_16x16x32_bf16 v[72:75], v[156:159], v[210:213], v[72:75]
	s_setprio 0
	s_setprio 1
	v_mfma_f32_16x16x32_bf16 v[116:119], v[160:163], v[176:179], v[116:119]
	v_mfma_f32_16x16x32_bf16 v[112:115], v[168:171], v[176:179], v[112:115]
	v_mfma_f32_16x16x32_bf16 v[100:103], v[160:163], v[184:187], v[100:103]
	v_mfma_f32_16x16x32_bf16 v[96:99], v[168:171], v[184:187], v[96:99]
	v_mfma_f32_16x16x32_bf16 v[84:87], v[160:163], v[198:201], v[84:87]
	v_mfma_f32_16x16x32_bf16 v[80:83], v[168:171], v[198:201], v[80:83]
	v_mfma_f32_16x16x32_bf16 v[68:71], v[160:163], v[206:209], v[68:71]
	v_mfma_f32_16x16x32_bf16 v[64:67], v[168:171], v[206:209], v[64:67]
	v_mfma_f32_16x16x32_bf16 v[116:119], v[164:167], v[180:183], v[116:119]
	v_mfma_f32_16x16x32_bf16 v[112:115], v[172:175], v[180:183], v[112:115]
	v_mfma_f32_16x16x32_bf16 v[100:103], v[164:167], v[194:197], v[100:103]
	v_mfma_f32_16x16x32_bf16 v[96:99], v[172:175], v[194:197], v[96:99]
	v_mfma_f32_16x16x32_bf16 v[84:87], v[164:167], v[202:205], v[84:87]
	v_mfma_f32_16x16x32_bf16 v[80:83], v[172:175], v[202:205], v[80:83]
	v_mfma_f32_16x16x32_bf16 v[68:71], v[164:167], v[210:213], v[68:71]
	v_mfma_f32_16x16x32_bf16 v[64:67], v[172:175], v[210:213], v[64:67]
	s_setprio 0
	s_barrier
; #define PG8_STAGE(bufoff, gbase, voff) do { _Pragma("unroll") for (int _i = 0; _i < 2; ++_i) \
;         __builtin_amdgcn_global_load_lds((const unsigned*)((const char*)(gbase) + (voff)[_i]), (PG8_LAS unsigned*)(lds + (bufoff) + ldsw + _i * 8192), 16, 0, 0); } while (0)
; #define PG8_LDA(dst, b, h) do { _Pragma("unroll") for (int m = 0; m < 4; ++m) _Pragma("unroll") for (int k = 0; k < 2; ++k) dst[m][k] = *(const PG8_LAS bf16x8*)(lds + PG8_SA(b, h) + aoff + m * 2048 + k * 1024); } while (0)
; #define PG8_MMA(ai, bj, At, Bt) do { __builtin_amdgcn_s_setprio(1); _Pragma("unroll") for (int m = 0; m < 4; ++m) _Pragma("unroll") for (int n = 0; n < 2; ++n) _Pragma("unroll") for (int k = 0; k < 2; ++k) \
;         acc[ai][bj][m][n] = __builtin_amdgcn_mfma_f32_16x16x32_bf16(Bt[n][k], At[m][k], acc[ai][bj][m][n], 0, 0, 0); __builtin_amdgcn_s_setprio(0); } while (0)
; #define PG8_WAIT_V(n) asm volatile("s_waitcnt vmcnt(" #n ")" ::: "memory")
; #define PG8_WAIT_L(n) asm volatile("s_waitcnt lgkmcnt(" #n ")" ::: "memory")
; #define PG8_BAR __builtin_amdgcn_s_barrier()
; #define PG8_SCHED __builtin_amdgcn_sched_barrier(0)
; template <class Epi, class Sched, bool ALIGN_EPI = false, bool SP2 = false>
; __device__ __forceinline__ void gemm_phase(PG8_LAS unsigned char* lds, const Gemm g, const Sched& S, const Epi& E) {
;     ...
;             PG8_LDA(At, 1, 1); PG8_STAGE(PG8_SB(1, 0), b3, voffB); PG8_STAGE(PG8_SB(1, 1), b3 + hstep, voffB); PG8_STAGE(PG8_SA(1, 0), a3, voffA);
;             PG8_WAIT_V(8); PG8_WAIT_L(0); PG8_BAR; PG8_MMA(1, 0, At, B0); PG8_MMA(1, 1, At, B1); PG8_BAR; PG8_SCHED;
;     ...
;         if constexpr (ALIGN_EPI) { if (wr == 0) PG8_BAR; }
	s_add_i32 s24, s50, s26
	v_lshl_add_u64 v[214:215], v[214:215], 0, s[14:15]
	s_mov_b32 m0, s24
	ds_read_b128 v[176:179], v191 offset:49152
	global_load_lds_dwordx4 v[214:215], off
	s_add_i32 m0, s24, 0x2000
	s_add_u32 s22, s22, 0xb0080
	v_lshl_add_u64 v[214:215], v[216:217], 0, s[14:15]
	s_addc_u32 s23, s23, 0
	s_add_i32 s24, s51, s26
	global_load_lds_dwordx4 v[214:215], off
	v_lshl_add_u64 v[214:215], s[22:23], 0, v[128:129]
	s_mov_b32 m0, s24
	ds_read_b128 v[180:183], v191 offset:50176
	global_load_lds_dwordx4 v[214:215], off
	v_lshl_add_u64 v[214:215], s[22:23], 0, v[130:131]
	s_add_i32 m0, s24, 0x2000
	ds_read_b128 v[184:187], v191 offset:51200
	global_load_lds_dwordx4 v[214:215], off
	v_lshl_add_u64 v[214:215], v[218:219], 0, s[14:15]
	s_mov_b32 m0, s34
	ds_read_b128 v[194:197], v191 offset:52224
	global_load_lds_dwordx4 v[214:215], off
	v_lshl_add_u64 v[214:215], v[220:221], 0, s[14:15]
	s_mov_b32 m0, s35
	ds_read_b128 v[198:201], v191 offset:53248
	global_load_lds_dwordx4 v[214:215], off
	ds_read_b128 v[202:205], v191 offset:54272
	ds_read_b128 v[206:209], v191 offset:55296
	ds_read_b128 v[210:213], v191 offset:56320
	s_waitcnt vmcnt(8)
	s_waitcnt lgkmcnt(0)
	s_barrier
	s_setprio 1
	s_waitcnt lgkmcnt(0)
	v_mfma_f32_16x16x32_bf16 v[60:63], v[140:143], v[176:179], v[60:63]
	v_mfma_f32_16x16x32_bf16 v[56:59], v[152:155], v[176:179], v[56:59]
	v_mfma_f32_16x16x32_bf16 v[44:47], v[140:143], v[184:187], v[44:47]
	v_mfma_f32_16x16x32_bf16 v[40:43], v[152:155], v[184:187], v[40:43]
	v_mfma_f32_16x16x32_bf16 v[28:31], v[140:143], v[198:201], v[28:31]
	v_mfma_f32_16x16x32_bf16 v[24:27], v[152:155], v[198:201], v[24:27]
	v_mfma_f32_16x16x32_bf16 v[12:15], v[140:143], v[206:209], v[12:15]
	v_mfma_f32_16x16x32_bf16 v[8:11], v[152:155], v[206:209], v[8:11]
	v_mfma_f32_16x16x32_bf16 v[60:63], v[144:147], v[180:183], v[60:63]
	v_mfma_f32_16x16x32_bf16 v[56:59], v[156:159], v[180:183], v[56:59]
	v_mfma_f32_16x16x32_bf16 v[44:47], v[144:147], v[194:197], v[44:47]
	v_mfma_f32_16x16x32_bf16 v[40:43], v[156:159], v[194:197], v[40:43]
	v_mfma_f32_16x16x32_bf16 v[28:31], v[144:147], v[202:205], v[28:31]
	v_mfma_f32_16x16x32_bf16 v[24:27], v[156:159], v[202:205], v[24:27]
	v_mfma_f32_16x16x32_bf16 v[12:15], v[144:147], v[210:213], v[12:15]
	v_mfma_f32_16x16x32_bf16 v[8:11], v[156:159], v[210:213], v[8:11]
	s_setprio 0
	s_setprio 1
	v_mfma_f32_16x16x32_bf16 v[52:55], v[160:163], v[176:179], v[52:55]
	v_mfma_f32_16x16x32_bf16 v[48:51], v[168:171], v[176:179], v[48:51]
	v_mfma_f32_16x16x32_bf16 v[36:39], v[160:163], v[184:187], v[36:39]
	v_mfma_f32_16x16x32_bf16 v[32:35], v[168:171], v[184:187], v[32:35]
	v_mfma_f32_16x16x32_bf16 v[20:23], v[160:163], v[198:201], v[20:23]
	v_mfma_f32_16x16x32_bf16 v[16:19], v[168:171], v[198:201], v[16:19]
	v_mfma_f32_16x16x32_bf16 v[4:7], v[160:163], v[206:209], v[4:7]
	v_mfma_f32_16x16x32_bf16 v[0:3], v[168:171], v[206:209], v[0:3]
	v_mfma_f32_16x16x32_bf16 v[52:55], v[164:167], v[180:183], v[52:55]
	v_mfma_f32_16x16x32_bf16 v[48:51], v[172:175], v[180:183], v[48:51]
	v_mfma_f32_16x16x32_bf16 v[36:39], v[164:167], v[194:197], v[36:39]
	v_mfma_f32_16x16x32_bf16 v[32:35], v[172:175], v[194:197], v[32:35]
	v_mfma_f32_16x16x32_bf16 v[20:23], v[164:167], v[202:205], v[20:23]
	v_mfma_f32_16x16x32_bf16 v[16:19], v[172:175], v[202:205], v[16:19]
	v_mfma_f32_16x16x32_bf16 v[4:7], v[164:167], v[210:213], v[4:7]
	v_mfma_f32_16x16x32_bf16 v[0:3], v[172:175], v[210:213], v[0:3]
	s_setprio 0
	s_barrier
	s_add_i32 s47, s47, 2
	s_add_u32 s20, s20, 0x100
	s_addc_u32 s21, s21, 0
	s_add_u32 s45, s45, 0x100
	s_addc_u32 s46, s46, 0
	s_cmp_gt_u32 s47, 41
	s_cbranch_scc0 .LBB0_1572
	s_nop 0
	s_nop 0
	s_nop 0
	s_nop 0
	s_nop 0
	s_nop 0
	s_nop 0
	s_nop 0
	s_nop 0
	s_and_b64 vcc, exec, s[16:17]
	s_cbranch_vccz .LBB0_1575
	s_barrier

; #define PG8_STAGE(bufoff, gbase, voff) do { _Pragma("unroll") for (int _i = 0; _i < 2; ++_i) \
;         __builtin_amdgcn_global_load_lds((const unsigned*)((const char*)(gbase) + (voff)[_i]), (PG8_LAS unsigned*)(lds + (bufoff) + ldsw + _i * 8192), 16, 0, 0); } while (0)
; #define PG8_LDA(dst, b, h) do { _Pragma("unroll") for (int m = 0; m < 4; ++m) _Pragma("unroll") for (int k = 0; k < 2; ++k) dst[m][k] = *(const PG8_LAS bf16x8*)(lds + PG8_SA(b, h) + aoff + m * 2048 + k * 1024); } while (0)
; #define PG8_LDB(dst, b, h) do { _Pragma("unroll") for (int n = 0; n < 2; ++n) _Pragma("unroll") for (int k = 0; k < 2; ++k) dst[n][k] = *(const PG8_LAS bf16x8*)(lds + PG8_SB(b, h) + boff + n * 2048 + k * 1024); } while (0)
; #define PG8_MMA(ai, bj, At, Bt) do { __builtin_amdgcn_s_setprio(1); _Pragma("unroll") for (int m = 0; m < 4; ++m) _Pragma("unroll") for (int n = 0; n < 2; ++n) _Pragma("unroll") for (int k = 0; k < 2; ++k) \
;         acc[ai][bj][m][n] = __builtin_amdgcn_mfma_f32_16x16x32_bf16(Bt[n][k], At[m][k], acc[ai][bj][m][n], 0, 0, 0); __builtin_amdgcn_s_setprio(0); } while (0)
; #define PG8_WAIT_V(n) asm volatile("s_waitcnt vmcnt(" #n ")" ::: "memory")
; #define PG8_WAIT_L(n) asm volatile("s_waitcnt lgkmcnt(" #n ")" ::: "memory")
; template <class Epi, class Sched, bool ALIGN_EPI = false, bool SP2 = false>
; __device__ __forceinline__ void gemm_phase(PG8_LAS unsigned char* lds, const Gemm g, const Sched& S, const Epi& E) {
;     ...
;             const bool last = (t == nt - 2);
;             const char* a1 = cA + (size_t)(t + 1) * kstep;
;             const char* a2 = last ? nA : cA + (size_t)(t + 2) * kstep; const char* b2 = last ? nB : cB + (size_t)(t + 2) * kstep;
;             const char* a3 = a2 + kstep; const char* b3 = b2 + kstep;
;             if (last && has_next) S.a_ready(nxt);
;             if constexpr (SP2) {
;             PG8_LDB(B0, 0, 0); PG8_LDB(B1, 0, 1); PG8_SCHED; PG8_LDA(At, 0, 0); PG8_STAGE(PG8_SA(1, 1), a1 + hstep, voffA);
;             PG8_WAIT_V(8); PG8_WAIT_L(0); PG8_BAR; PG8_MMA(0, 0, At, B0); PG8_MMA(0, 1, At, B1); PG8_BAR; PG8_SCHED;
;             PG8_LDA(At, 0, 1); PG8_STAGE(PG8_SB(0, 0), b2, voffB); PG8_STAGE(PG8_SB(0, 1), b2 + hstep, voffB); PG8_STAGE(PG8_SA(0, 0), a2, voffA);
;             PG8_WAIT_V(8); PG8_WAIT_L(0); PG8_BAR; PG8_MMA(1, 0, At, B0); PG8_MMA(1, 1, At, B1); PG8_BAR; PG8_SCHED;
.LBB0_1666:
	v_lshl_add_u64 v[152:153], s[4:5], 0, v[136:137]
	s_add_i32 m0, s39, 0xc000
	ds_read_b128 v[144:147], v155
	global_load_lds_dwordx4 v[152:153], off
	v_lshl_add_u64 v[152:153], s[4:5], 0, v[138:139]
	s_add_i32 m0, s39, 0xe000
	ds_read_b128 v[160:163], v155 offset:1024
	global_load_lds_dwordx4 v[152:153], off
	s_add_u32 s6, s4, 0xfffc0080
	s_addc_u32 s7, s5, -1
	s_cmp_eq_u32 s55, 12
	s_cselect_b32 s9, s10, s7
	s_cselect_b32 s8, s11, s6
	s_cselect_b32 s7, s25, s54
	s_cselect_b32 s6, s27, s53
	ds_read_b128 v[164:167], v155 offset:2048
	ds_read_b128 v[168:171], v155 offset:3072
	ds_read_b128 v[172:175], v156
	ds_read_b128 v[176:179], v156 offset:1024
	ds_read_b128 v[180:183], v156 offset:2048
	ds_read_b128 v[184:187], v156 offset:3072
	ds_read_b128 v[188:191], v157
	ds_read_b128 v[192:195], v157 offset:1024
	ds_read_b128 v[196:199], v157 offset:2048
	ds_read_b128 v[200:203], v157 offset:3072
	ds_read_b128 v[204:207], v157 offset:4096
	ds_read_b128 v[208:211], v157 offset:5120
	ds_read_b128 v[212:215], v157 offset:6144
	ds_read_b128 v[216:219], v157 offset:7168
	s_waitcnt vmcnt(8)
	s_waitcnt lgkmcnt(0)
	s_barrier
	s_setprio 1
	s_waitcnt lgkmcnt(0)
	v_mfma_f32_16x16x32_bf16 v[124:127], v[144:147], v[188:191], v[124:127]
	v_mfma_f32_16x16x32_bf16 v[116:119], v[164:167], v[188:191], v[116:119]
	v_mfma_f32_16x16x32_bf16 v[108:111], v[144:147], v[196:199], v[108:111]
	v_mfma_f32_16x16x32_bf16 v[100:103], v[164:167], v[196:199], v[100:103]
	v_mfma_f32_16x16x32_bf16 v[92:95], v[144:147], v[204:207], v[92:95]
	v_mfma_f32_16x16x32_bf16 v[84:87], v[164:167], v[204:207], v[84:87]
	v_mfma_f32_16x16x32_bf16 v[76:79], v[144:147], v[212:215], v[76:79]
	v_mfma_f32_16x16x32_bf16 v[68:71], v[164:167], v[212:215], v[68:71]
	v_mfma_f32_16x16x32_bf16 v[124:127], v[160:163], v[192:195], v[124:127]
	v_mfma_f32_16x16x32_bf16 v[116:119], v[168:171], v[192:195], v[116:119]
	v_mfma_f32_16x16x32_bf16 v[108:111], v[160:163], v[200:203], v[108:111]
	v_mfma_f32_16x16x32_bf16 v[100:103], v[168:171], v[200:203], v[100:103]
	v_mfma_f32_16x16x32_bf16 v[92:95], v[160:163], v[208:211], v[92:95]
	v_mfma_f32_16x16x32_bf16 v[84:87], v[168:171], v[208:211], v[84:87]
	v_mfma_f32_16x16x32_bf16 v[76:79], v[160:163], v[216:219], v[76:79]
	v_mfma_f32_16x16x32_bf16 v[68:71], v[168:171], v[216:219], v[68:71]
	s_setprio 0
	s_setprio 1
	v_mfma_f32_16x16x32_bf16 v[120:123], v[172:175], v[188:191], v[120:123]
	v_mfma_f32_16x16x32_bf16 v[112:115], v[180:183], v[188:191], v[112:115]
	v_mfma_f32_16x16x32_bf16 v[104:107], v[172:175], v[196:199], v[104:107]
	v_mfma_f32_16x16x32_bf16 v[96:99], v[180:183], v[196:199], v[96:99]
	v_mfma_f32_16x16x32_bf16 v[88:91], v[172:175], v[204:207], v[88:91]
	v_mfma_f32_16x16x32_bf16 v[80:83], v[180:183], v[204:207], v[80:83]
	v_mfma_f32_16x16x32_bf16 v[72:75], v[172:175], v[212:215], v[72:75]
	v_mfma_f32_16x16x32_bf16 v[64:67], v[180:183], v[212:215], v[64:67]
	v_mfma_f32_16x16x32_bf16 v[120:123], v[176:179], v[192:195], v[120:123]
	v_mfma_f32_16x16x32_bf16 v[112:115], v[184:187], v[192:195], v[112:115]
	v_mfma_f32_16x16x32_bf16 v[104:107], v[176:179], v[200:203], v[104:107]
	v_mfma_f32_16x16x32_bf16 v[96:99], v[184:187], v[200:203], v[96:99]
	v_mfma_f32_16x16x32_bf16 v[88:91], v[176:179], v[208:211], v[88:91]
	v_mfma_f32_16x16x32_bf16 v[80:83], v[184:187], v[208:211], v[80:83]
	v_mfma_f32_16x16x32_bf16 v[72:75], v[176:179], v[216:219], v[72:75]
	v_mfma_f32_16x16x32_bf16 v[64:67], v[184:187], v[216:219], v[64:67]
	s_setprio 0
	s_barrier
	s_add_i32 s56, s47, s36
	v_lshl_add_u64 v[152:153], s[6:7], 0, v[132:133]
	s_mov_b32 m0, s56
	v_lshl_add_u64 v[220:221], s[6:7], 0, v[128:129]
	global_load_lds_dwordx4 v[152:153], off
	s_add_i32 m0, s56, 0x2000
	s_add_u32 s56, s6, 0x40000
	s_addc_u32 s57, s7, 0
	s_add_i32 s58, s50, s36
	global_load_lds_dwordx4 v[220:221], off
	v_lshl_add_u64 v[222:223], s[56:57], 0, v[132:133]
	s_mov_b32 m0, s58
	v_lshl_add_u64 v[224:225], s[8:9], 0, v[130:131]
	global_load_lds_dwordx4 v[222:223], off
	v_lshl_add_u64 v[222:223], s[56:57], 0, v[128:129]
	s_add_i32 m0, s58, 0x2000
	ds_read_b128 v[188:191], v157 offset:16384
	global_load_lds_dwordx4 v[222:223], off
	v_lshl_add_u64 v[222:223], s[8:9], 0, v[134:135]
	s_mov_b32 m0, s39
	ds_read_b128 v[192:195], v157 offset:17408
	global_load_lds_dwordx4 v[222:223], off
	s_mov_b32 m0, s40
	ds_read_b128 v[196:199], v157 offset:18432
	global_load_lds_dwordx4 v[224:225], off
	ds_read_b128 v[200:203], v157 offset:19456
	ds_read_b128 v[204:207], v157 offset:20480
	ds_read_b128 v[208:211], v157 offset:21504
	ds_read_b128 v[212:215], v157 offset:22528
	ds_read_b128 v[216:219], v157 offset:23552
	s_waitcnt vmcnt(8)
	s_waitcnt lgkmcnt(0)
	s_barrier
; #define PG8_STAGE(bufoff, gbase, voff) do { _Pragma("unroll") for (int _i = 0; _i < 2; ++_i) \
;         __builtin_amdgcn_global_load_lds((const unsigned*)((const char*)(gbase) + (voff)[_i]), (PG8_LAS unsigned*)(lds + (bufoff) + ldsw + _i * 8192), 16, 0, 0); } while (0)
; #define PG8_LDA(dst, b, h) do { _Pragma("unroll") for (int m = 0; m < 4; ++m) _Pragma("unroll") for (int k = 0; k < 2; ++k) dst[m][k] = *(const PG8_LAS bf16x8*)(lds + PG8_SA(b, h) + aoff + m * 2048 + k * 1024); } while (0)
; #define PG8_LDB(dst, b, h) do { _Pragma("unroll") for (int n = 0; n < 2; ++n) _Pragma("unroll") for (int k = 0; k < 2; ++k) dst[n][k] = *(const PG8_LAS bf16x8*)(lds + PG8_SB(b, h) + boff + n * 2048 + k * 1024); } while (0)
; #define PG8_MMA(ai, bj, At, Bt) do { __builtin_amdgcn_s_setprio(1); _Pragma("unroll") for (int m = 0; m < 4; ++m) _Pragma("unroll") for (int n = 0; n < 2; ++n) _Pragma("unroll") for (int k = 0; k < 2; ++k) \
;         acc[ai][bj][m][n] = __builtin_amdgcn_mfma_f32_16x16x32_bf16(Bt[n][k], At[m][k], acc[ai][bj][m][n], 0, 0, 0); __builtin_amdgcn_s_setprio(0); } while (0)
; #define PG8_WAIT_V(n) asm volatile("s_waitcnt vmcnt(" #n ")" ::: "memory")
; #define PG8_WAIT_L(n) asm volatile("s_waitcnt lgkmcnt(" #n ")" ::: "memory")
; #define PG8_BAR __builtin_amdgcn_s_barrier()
; #define PG8_SCHED __builtin_amdgcn_sched_barrier(0)
; template <class Epi, class Sched, bool ALIGN_EPI = false, bool SP2 = false>
; __device__ __forceinline__ void gemm_phase(PG8_LAS unsigned char* lds, const Gemm g, const Sched& S, const Epi& E) {
;     ...
;             PG8_WAIT_V(8); PG8_WAIT_L(0); PG8_BAR; PG8_MMA(1, 0, At, B0); PG8_MMA(1, 1, At, B1); PG8_BAR; PG8_SCHED;
;             PG8_LDB(B0, 1, 0); PG8_LDB(B1, 1, 1); PG8_SCHED; PG8_LDA(At, 1, 0); PG8_STAGE(PG8_SA(0, 1), a2 + hstep, voffA);
;             PG8_WAIT_V(8); PG8_WAIT_L(0); PG8_BAR; PG8_MMA(0, 0, At, B0); PG8_MMA(0, 1, At, B1); PG8_BAR; PG8_SCHED;
	s_setprio 1
	s_waitcnt lgkmcnt(0)
	v_mfma_f32_16x16x32_bf16 v[60:63], v[144:147], v[188:191], v[60:63]
	v_mfma_f32_16x16x32_bf16 v[52:55], v[164:167], v[188:191], v[52:55]
	v_mfma_f32_16x16x32_bf16 v[44:47], v[144:147], v[196:199], v[44:47]
	v_mfma_f32_16x16x32_bf16 v[36:39], v[164:167], v[196:199], v[36:39]
	v_mfma_f32_16x16x32_bf16 v[28:31], v[144:147], v[204:207], v[28:31]
	v_mfma_f32_16x16x32_bf16 v[20:23], v[164:167], v[204:207], v[20:23]
	v_mfma_f32_16x16x32_bf16 v[12:15], v[144:147], v[212:215], v[12:15]
	v_mfma_f32_16x16x32_bf16 v[4:7], v[164:167], v[212:215], v[4:7]
	v_mfma_f32_16x16x32_bf16 v[60:63], v[160:163], v[192:195], v[60:63]
	v_mfma_f32_16x16x32_bf16 v[52:55], v[168:171], v[192:195], v[52:55]
	v_mfma_f32_16x16x32_bf16 v[44:47], v[160:163], v[200:203], v[44:47]
	v_mfma_f32_16x16x32_bf16 v[36:39], v[168:171], v[200:203], v[36:39]
	v_mfma_f32_16x16x32_bf16 v[28:31], v[160:163], v[208:211], v[28:31]
	v_mfma_f32_16x16x32_bf16 v[20:23], v[168:171], v[208:211], v[20:23]
	v_mfma_f32_16x16x32_bf16 v[12:15], v[160:163], v[216:219], v[12:15]
	v_mfma_f32_16x16x32_bf16 v[4:7], v[168:171], v[216:219], v[4:7]
	s_setprio 0
	s_setprio 1
	v_mfma_f32_16x16x32_bf16 v[56:59], v[172:175], v[188:191], v[56:59]
	v_mfma_f32_16x16x32_bf16 v[48:51], v[180:183], v[188:191], v[48:51]
	v_mfma_f32_16x16x32_bf16 v[40:43], v[172:175], v[196:199], v[40:43]
	v_mfma_f32_16x16x32_bf16 v[32:35], v[180:183], v[196:199], v[32:35]
	v_mfma_f32_16x16x32_bf16 v[24:27], v[172:175], v[204:207], v[24:27]
	v_mfma_f32_16x16x32_bf16 v[16:19], v[180:183], v[204:207], v[16:19]
	v_mfma_f32_16x16x32_bf16 v[8:11], v[172:175], v[212:215], v[8:11]
	v_mfma_f32_16x16x32_bf16 v[0:3], v[180:183], v[212:215], v[0:3]
	v_mfma_f32_16x16x32_bf16 v[56:59], v[176:179], v[192:195], v[56:59]
	v_mfma_f32_16x16x32_bf16 v[48:51], v[184:187], v[192:195], v[48:51]
	v_mfma_f32_16x16x32_bf16 v[40:43], v[176:179], v[200:203], v[40:43]
	v_mfma_f32_16x16x32_bf16 v[32:35], v[184:187], v[200:203], v[32:35]
	v_mfma_f32_16x16x32_bf16 v[24:27], v[176:179], v[208:211], v[24:27]
	v_mfma_f32_16x16x32_bf16 v[16:19], v[184:187], v[208:211], v[16:19]
	v_mfma_f32_16x16x32_bf16 v[8:11], v[176:179], v[216:219], v[8:11]
	v_mfma_f32_16x16x32_bf16 v[0:3], v[184:187], v[216:219], v[0:3]
	s_setprio 0
	s_barrier
	s_add_i32 s56, 0, 0x18000
	s_add_i32 s57, 0, 0x1c000
	s_add_u32 s8, s8, 0x40000
	s_addc_u32 s9, s9, 0
	s_mov_b32 m0, s41
	v_lshl_add_u64 v[226:227], s[8:9], 0, v[134:135]
	global_load_lds_dwordx4 v[226:227], off
	v_lshl_add_u64 v[226:227], s[8:9], 0, v[130:131]
	s_mov_b32 m0, s42
	v_add_u32_e32 v159, s56, v151
	global_load_lds_dwordx4 v[226:227], off
	ds_read_b128 v[144:147], v159
	ds_read_b128 v[160:163], v159 offset:1024
	ds_read_b128 v[164:167], v159 offset:2048
	ds_read_b128 v[168:171], v159 offset:3072
	v_add_u32_e32 v159, s57, v151
	ds_read_b128 v[172:175], v159
	ds_read_b128 v[176:179], v159 offset:1024
	ds_read_b128 v[180:183], v159 offset:2048
	ds_read_b128 v[184:187], v159 offset:3072
	ds_read_b128 v[188:191], v157 offset:32768
	ds_read_b128 v[192:195], v157 offset:33792
	ds_read_b128 v[196:199], v157 offset:34816
	ds_read_b128 v[200:203], v157 offset:35840
	ds_read_b128 v[204:207], v157 offset:36864
	ds_read_b128 v[208:211], v157 offset:37888
	ds_read_b128 v[212:215], v157 offset:38912
	ds_read_b128 v[216:219], v157 offset:39936
	s_waitcnt vmcnt(8)
	s_waitcnt lgkmcnt(0)
	s_barrier
	s_setprio 1
	s_waitcnt lgkmcnt(0)
	v_mfma_f32_16x16x32_bf16 v[124:127], v[144:147], v[188:191], v[124:127]
	v_mfma_f32_16x16x32_bf16 v[116:119], v[164:167], v[188:191], v[116:119]
	v_mfma_f32_16x16x32_bf16 v[108:111], v[144:147], v[196:199], v[108:111]
	v_mfma_f32_16x16x32_bf16 v[100:103], v[164:167], v[196:199], v[100:103]
	v_mfma_f32_16x16x32_bf16 v[92:95], v[144:147], v[204:207], v[92:95]
	v_mfma_f32_16x16x32_bf16 v[84:87], v[164:167], v[204:207], v[84:87]
	v_mfma_f32_16x16x32_bf16 v[76:79], v[144:147], v[212:215], v[76:79]
	v_mfma_f32_16x16x32_bf16 v[68:71], v[164:167], v[212:215], v[68:71]
	v_mfma_f32_16x16x32_bf16 v[124:127], v[160:163], v[192:195], v[124:127]
	v_mfma_f32_16x16x32_bf16 v[116:119], v[168:171], v[192:195], v[116:119]
	v_mfma_f32_16x16x32_bf16 v[108:111], v[160:163], v[200:203], v[108:111]
	v_mfma_f32_16x16x32_bf16 v[100:103], v[168:171], v[200:203], v[100:103]
	v_mfma_f32_16x16x32_bf16 v[92:95], v[160:163], v[208:211], v[92:95]
	v_mfma_f32_16x16x32_bf16 v[84:87], v[168:171], v[208:211], v[84:87]
	v_mfma_f32_16x16x32_bf16 v[76:79], v[160:163], v[216:219], v[76:79]
	v_mfma_f32_16x16x32_bf16 v[68:71], v[168:171], v[216:219], v[68:71]
	s_setprio 0
	s_setprio 1
	v_mfma_f32_16x16x32_bf16 v[120:123], v[172:175], v[188:191], v[120:123]
	v_mfma_f32_16x16x32_bf16 v[112:115], v[180:183], v[188:191], v[112:115]
	v_mfma_f32_16x16x32_bf16 v[104:107], v[172:175], v[196:199], v[104:107]
	v_mfma_f32_16x16x32_bf16 v[96:99], v[180:183], v[196:199], v[96:99]
	v_mfma_f32_16x16x32_bf16 v[88:91], v[172:175], v[204:207], v[88:91]
	v_mfma_f32_16x16x32_bf16 v[80:83], v[180:183], v[204:207], v[80:83]
	v_mfma_f32_16x16x32_bf16 v[72:75], v[172:175], v[212:215], v[72:75]
	v_mfma_f32_16x16x32_bf16 v[64:67], v[180:183], v[212:215], v[64:67]
	v_mfma_f32_16x16x32_bf16 v[120:123], v[176:179], v[192:195], v[120:123]
	v_mfma_f32_16x16x32_bf16 v[112:115], v[184:187], v[192:195], v[112:115]
	v_mfma_f32_16x16x32_bf16 v[104:107], v[176:179], v[200:203], v[104:107]
	v_mfma_f32_16x16x32_bf16 v[96:99], v[184:187], v[200:203], v[96:99]
	v_mfma_f32_16x16x32_bf16 v[88:91], v[176:179], v[208:211], v[88:91]
	v_mfma_f32_16x16x32_bf16 v[80:83], v[184:187], v[208:211], v[80:83]
	v_mfma_f32_16x16x32_bf16 v[72:75], v[176:179], v[216:219], v[72:75]
	v_mfma_f32_16x16x32_bf16 v[64:67], v[184:187], v[216:219], v[64:67]
	s_setprio 0
	s_barrier
; #define PG8_STAGE(bufoff, gbase, voff) do { _Pragma("unroll") for (int _i = 0; _i < 2; ++_i) \
;         __builtin_amdgcn_global_load_lds((const unsigned*)((const char*)(gbase) + (voff)[_i]), (PG8_LAS unsigned*)(lds + (bufoff) + ldsw + _i * 8192), 16, 0, 0); } while (0)
; #define PG8_LDA(dst, b, h) do { _Pragma("unroll") for (int m = 0; m < 4; ++m) _Pragma("unroll") for (int k = 0; k < 2; ++k) dst[m][k] = *(const PG8_LAS bf16x8*)(lds + PG8_SA(b, h) + aoff + m * 2048 + k * 1024); } while (0)
; #define PG8_MMA(ai, bj, At, Bt) do { __builtin_amdgcn_s_setprio(1); _Pragma("unroll") for (int m = 0; m < 4; ++m) _Pragma("unroll") for (int n = 0; n < 2; ++n) _Pragma("unroll") for (int k = 0; k < 2; ++k) \
;         acc[ai][bj][m][n] = __builtin_amdgcn_mfma_f32_16x16x32_bf16(Bt[n][k], At[m][k], acc[ai][bj][m][n], 0, 0, 0); __builtin_amdgcn_s_setprio(0); } while (0)
; #define PG8_WAIT_V(n) asm volatile("s_waitcnt vmcnt(" #n ")" ::: "memory")
; #define PG8_WAIT_L(n) asm volatile("s_waitcnt lgkmcnt(" #n ")" ::: "memory")
; #define PG8_BAR __builtin_amdgcn_s_barrier()
; #define PG8_SCHED __builtin_amdgcn_sched_barrier(0)
; template <class Epi, class Sched, bool ALIGN_EPI = false, bool SP2 = false>
; __device__ __forceinline__ void gemm_phase(PG8_LAS unsigned char* lds, const Gemm g, const Sched& S, const Epi& E) {
;     ...
;             PG8_LDA(At, 1, 1); PG8_STAGE(PG8_SB(1, 0), b3, voffB); PG8_STAGE(PG8_SB(1, 1), b3 + hstep, voffB); PG8_STAGE(PG8_SA(1, 0), a3, voffA);
;             PG8_WAIT_V(8); PG8_WAIT_L(0); PG8_BAR; PG8_MMA(1, 0, At, B0); PG8_MMA(1, 1, At, B1); PG8_BAR; PG8_SCHED;
;     ...
;         if constexpr (ALIGN_EPI) { if (wr == 0) PG8_BAR; }
	s_add_i32 s8, s56, s36
	v_lshl_add_u64 v[152:153], v[152:153], 0, s[20:21]
	s_mov_b32 m0, s8
	ds_read_b128 v[188:191], v157 offset:49152
	global_load_lds_dwordx4 v[152:153], off
	s_add_i32 m0, s8, 0x2000
	s_add_u32 s6, s6, 0x40080
	v_lshl_add_u64 v[152:153], v[220:221], 0, s[20:21]
	s_addc_u32 s7, s7, 0
	s_add_i32 s8, s57, s36
	global_load_lds_dwordx4 v[152:153], off
	v_lshl_add_u64 v[152:153], s[6:7], 0, v[132:133]
	s_mov_b32 m0, s8
	ds_read_b128 v[192:195], v157 offset:50176
	global_load_lds_dwordx4 v[152:153], off
	v_lshl_add_u64 v[152:153], s[6:7], 0, v[128:129]
	s_add_i32 m0, s8, 0x2000
	ds_read_b128 v[196:199], v157 offset:51200
	global_load_lds_dwordx4 v[152:153], off
	v_lshl_add_u64 v[152:153], v[222:223], 0, s[20:21]
	s_mov_b32 m0, s44
	ds_read_b128 v[200:203], v157 offset:52224
	global_load_lds_dwordx4 v[152:153], off
	v_lshl_add_u64 v[152:153], v[224:225], 0, s[20:21]
	s_mov_b32 m0, s45
	ds_read_b128 v[204:207], v157 offset:53248
	global_load_lds_dwordx4 v[152:153], off
	ds_read_b128 v[208:211], v157 offset:54272
	ds_read_b128 v[212:215], v157 offset:55296
	ds_read_b128 v[216:219], v157 offset:56320
	s_waitcnt vmcnt(8)
	s_waitcnt lgkmcnt(0)
	s_barrier
	s_setprio 1
	s_waitcnt lgkmcnt(0)
	v_mfma_f32_16x16x32_bf16 v[60:63], v[144:147], v[188:191], v[60:63]
	v_mfma_f32_16x16x32_bf16 v[52:55], v[164:167], v[188:191], v[52:55]
	v_mfma_f32_16x16x32_bf16 v[44:47], v[144:147], v[196:199], v[44:47]
	v_mfma_f32_16x16x32_bf16 v[36:39], v[164:167], v[196:199], v[36:39]
	v_mfma_f32_16x16x32_bf16 v[28:31], v[144:147], v[204:207], v[28:31]
	v_mfma_f32_16x16x32_bf16 v[20:23], v[164:167], v[204:207], v[20:23]
	v_mfma_f32_16x16x32_bf16 v[12:15], v[144:147], v[212:215], v[12:15]
	v_mfma_f32_16x16x32_bf16 v[4:7], v[164:167], v[212:215], v[4:7]
	v_mfma_f32_16x16x32_bf16 v[60:63], v[160:163], v[192:195], v[60:63]
	v_mfma_f32_16x16x32_bf16 v[52:55], v[168:171], v[192:195], v[52:55]
	v_mfma_f32_16x16x32_bf16 v[44:47], v[160:163], v[200:203], v[44:47]
	v_mfma_f32_16x16x32_bf16 v[36:39], v[168:171], v[200:203], v[36:39]
	v_mfma_f32_16x16x32_bf16 v[28:31], v[160:163], v[208:211], v[28:31]
	v_mfma_f32_16x16x32_bf16 v[20:23], v[168:171], v[208:211], v[20:23]
	v_mfma_f32_16x16x32_bf16 v[12:15], v[160:163], v[216:219], v[12:15]
	v_mfma_f32_16x16x32_bf16 v[4:7], v[168:171], v[216:219], v[4:7]
	s_setprio 0
	s_setprio 1
	v_mfma_f32_16x16x32_bf16 v[56:59], v[172:175], v[188:191], v[56:59]
	v_mfma_f32_16x16x32_bf16 v[48:51], v[180:183], v[188:191], v[48:51]
	v_mfma_f32_16x16x32_bf16 v[40:43], v[172:175], v[196:199], v[40:43]
	v_mfma_f32_16x16x32_bf16 v[32:35], v[180:183], v[196:199], v[32:35]
	v_mfma_f32_16x16x32_bf16 v[24:27], v[172:175], v[204:207], v[24:27]
	v_mfma_f32_16x16x32_bf16 v[16:19], v[180:183], v[204:207], v[16:19]
	v_mfma_f32_16x16x32_bf16 v[8:11], v[172:175], v[212:215], v[8:11]
	v_mfma_f32_16x16x32_bf16 v[0:3], v[180:183], v[212:215], v[0:3]
	v_mfma_f32_16x16x32_bf16 v[56:59], v[176:179], v[192:195], v[56:59]
	v_mfma_f32_16x16x32_bf16 v[48:51], v[184:187], v[192:195], v[48:51]
	v_mfma_f32_16x16x32_bf16 v[40:43], v[176:179], v[200:203], v[40:43]
	v_mfma_f32_16x16x32_bf16 v[32:35], v[184:187], v[200:203], v[32:35]
	v_mfma_f32_16x16x32_bf16 v[24:27], v[176:179], v[208:211], v[24:27]
	v_mfma_f32_16x16x32_bf16 v[16:19], v[184:187], v[208:211], v[16:19]
	v_mfma_f32_16x16x32_bf16 v[8:11], v[176:179], v[216:219], v[8:11]
	v_mfma_f32_16x16x32_bf16 v[0:3], v[184:187], v[216:219], v[0:3]
	s_setprio 0
	s_barrier
	s_add_i32 s55, s55, 2
	s_add_u32 s4, s4, 0x100
	s_addc_u32 s5, s5, 0
	s_add_u32 s53, s53, 0x100
	s_addc_u32 s54, s54, 0
	s_cmp_gt_u32 s55, 13
	s_cbranch_scc0 .LBB0_1666
	s_nop 0
	s_nop 0
	s_nop 0
	s_nop 0
	s_nop 0
	s_nop 0
	s_nop 0
	s_nop 0
	s_nop 0
	s_and_b64 vcc, exec, s[22:23]
	s_cbranch_vccz .LBB0_1669
	s_barrier

; #define PG8_STAGE(bufoff, gbase, voff) do { _Pragma("unroll") for (int _i = 0; _i < 2; ++_i) \
;         __builtin_amdgcn_global_load_lds((const unsigned*)((const char*)(gbase) + (voff)[_i]), (PG8_LAS unsigned*)(lds + (bufoff) + ldsw + _i * 8192), 16, 0, 0); } while (0)
; #define PG8_LDA(dst, b, h) do { _Pragma("unroll") for (int m = 0; m < 4; ++m) _Pragma("unroll") for (int k = 0; k < 2; ++k) dst[m][k] = *(const PG8_LAS bf16x8*)(lds + PG8_SA(b, h) + aoff + m * 2048 + k * 1024); } while (0)
; #define PG8_LDB(dst, b, h) do { _Pragma("unroll") for (int n = 0; n < 2; ++n) _Pragma("unroll") for (int k = 0; k < 2; ++k) dst[n][k] = *(const PG8_LAS bf16x8*)(lds + PG8_SB(b, h) + boff + n * 2048 + k * 1024); } while (0)
; #define PG8_MMA(ai, bj, At, Bt) do { __builtin_amdgcn_s_setprio(1); _Pragma("unroll") for (int m = 0; m < 4; ++m) _Pragma("unroll") for (int n = 0; n < 2; ++n) _Pragma("unroll") for (int k = 0; k < 2; ++k) \
;         acc[ai][bj][m][n] = __builtin_amdgcn_mfma_f32_16x16x32_bf16(Bt[n][k], At[m][k], acc[ai][bj][m][n], 0, 0, 0); __builtin_amdgcn_s_setprio(0); } while (0)
; #define PG8_WAIT_V(n) asm volatile("s_waitcnt vmcnt(" #n ")" ::: "memory")
; #define PG8_WAIT_L(n) asm volatile("s_waitcnt lgkmcnt(" #n ")" ::: "memory")
; template <class Epi, class Sched, bool ALIGN_EPI = false, bool SP2 = false>
; __device__ __forceinline__ void gemm_phase(PG8_LAS unsigned char* lds, const Gemm g, const Sched& S, const Epi& E) {
;     ...
;             const bool last = (t == nt - 2);
;             const char* a1 = cA + (size_t)(t + 1) * kstep;
;             const char* a2 = last ? nA : cA + (size_t)(t + 2) * kstep; const char* b2 = last ? nB : cB + (size_t)(t + 2) * kstep;
;             const char* a3 = a2 + kstep; const char* b3 = b2 + kstep;
;             if (last && has_next) S.a_ready(nxt);
;             if constexpr (SP2) {
;             PG8_LDB(B0, 0, 0); PG8_LDB(B1, 0, 1); PG8_SCHED; PG8_LDA(At, 0, 0); PG8_STAGE(PG8_SA(1, 1), a1 + hstep, voffA);
;             PG8_WAIT_V(8); PG8_WAIT_L(0); PG8_BAR; PG8_MMA(0, 0, At, B0); PG8_MMA(0, 1, At, B1); PG8_BAR; PG8_SCHED;
;             PG8_LDA(At, 0, 1); PG8_STAGE(PG8_SB(0, 0), b2, voffB); PG8_STAGE(PG8_SB(0, 1), b2 + hstep, voffB); PG8_STAGE(PG8_SA(0, 0), a2, voffA);
;             PG8_WAIT_V(8); PG8_WAIT_L(0); PG8_BAR; PG8_MMA(1, 0, At, B0); PG8_MMA(1, 1, At, B1); PG8_BAR; PG8_SCHED;
.LBB0_1751:
	v_lshl_add_u64 v[190:191], s[20:21], 0, v[132:133]
	s_add_i32 m0, s27, 0xc000
	ds_read_b128 v[140:143], v194
	global_load_lds_dwordx4 v[190:191], off
	v_lshl_add_u64 v[190:191], s[20:21], 0, v[134:135]
	s_add_i32 m0, s27, 0xe000
	ds_read_b128 v[144:147], v194 offset:1024
	global_load_lds_dwordx4 v[190:191], off
	s_add_u32 s22, s20, 0xfff50080
	s_addc_u32 s23, s21, -1
	s_cmp_eq_u32 s47, 40
	s_cselect_b32 s25, s1, s23
	s_cselect_b32 s24, s0, s22
	s_cselect_b32 s23, s19, s46
	s_cselect_b32 s22, s18, s45
	ds_read_b128 v[150:153], v194 offset:2048
	ds_read_b128 v[154:157], v194 offset:3072
	ds_read_b128 v[158:161], v195
	ds_read_b128 v[162:165], v195 offset:1024
	ds_read_b128 v[166:169], v195 offset:2048
	ds_read_b128 v[170:173], v195 offset:3072
	ds_read_b128 v[174:177], v196
	ds_read_b128 v[178:181], v196 offset:1024
	ds_read_b128 v[182:185], v196 offset:2048
	ds_read_b128 v[186:189], v196 offset:3072
	ds_read_b128 v[200:203], v196 offset:4096
	ds_read_b128 v[204:207], v196 offset:5120
	ds_read_b128 v[208:211], v196 offset:6144
	ds_read_b128 v[212:215], v196 offset:7168
	s_waitcnt vmcnt(8)
	s_waitcnt lgkmcnt(0)
	s_barrier
	s_setprio 1
	s_waitcnt lgkmcnt(0)
	v_mfma_f32_16x16x32_bf16 v[124:127], v[140:143], v[174:177], v[124:127]
	v_mfma_f32_16x16x32_bf16 v[120:123], v[150:153], v[174:177], v[120:123]
	v_mfma_f32_16x16x32_bf16 v[108:111], v[140:143], v[182:185], v[108:111]
	v_mfma_f32_16x16x32_bf16 v[104:107], v[150:153], v[182:185], v[104:107]
	v_mfma_f32_16x16x32_bf16 v[92:95], v[140:143], v[200:203], v[92:95]
	v_mfma_f32_16x16x32_bf16 v[88:91], v[150:153], v[200:203], v[88:91]
	v_mfma_f32_16x16x32_bf16 v[76:79], v[140:143], v[208:211], v[76:79]
	v_mfma_f32_16x16x32_bf16 v[72:75], v[150:153], v[208:211], v[72:75]
	v_mfma_f32_16x16x32_bf16 v[124:127], v[144:147], v[178:181], v[124:127]
	v_mfma_f32_16x16x32_bf16 v[120:123], v[154:157], v[178:181], v[120:123]
	v_mfma_f32_16x16x32_bf16 v[108:111], v[144:147], v[186:189], v[108:111]
	v_mfma_f32_16x16x32_bf16 v[104:107], v[154:157], v[186:189], v[104:107]
	v_mfma_f32_16x16x32_bf16 v[92:95], v[144:147], v[204:207], v[92:95]
	v_mfma_f32_16x16x32_bf16 v[88:91], v[154:157], v[204:207], v[88:91]
	v_mfma_f32_16x16x32_bf16 v[76:79], v[144:147], v[212:215], v[76:79]
	v_mfma_f32_16x16x32_bf16 v[72:75], v[154:157], v[212:215], v[72:75]
	s_setprio 0
	s_setprio 1
	v_mfma_f32_16x16x32_bf16 v[116:119], v[158:161], v[174:177], v[116:119]
	v_mfma_f32_16x16x32_bf16 v[112:115], v[166:169], v[174:177], v[112:115]
	v_mfma_f32_16x16x32_bf16 v[100:103], v[158:161], v[182:185], v[100:103]
	v_mfma_f32_16x16x32_bf16 v[96:99], v[166:169], v[182:185], v[96:99]
	v_mfma_f32_16x16x32_bf16 v[84:87], v[158:161], v[200:203], v[84:87]
	v_mfma_f32_16x16x32_bf16 v[80:83], v[166:169], v[200:203], v[80:83]
	v_mfma_f32_16x16x32_bf16 v[68:71], v[158:161], v[208:211], v[68:71]
	v_mfma_f32_16x16x32_bf16 v[64:67], v[166:169], v[208:211], v[64:67]
	v_mfma_f32_16x16x32_bf16 v[116:119], v[162:165], v[178:181], v[116:119]
	v_mfma_f32_16x16x32_bf16 v[112:115], v[170:173], v[178:181], v[112:115]
	v_mfma_f32_16x16x32_bf16 v[100:103], v[162:165], v[186:189], v[100:103]
	v_mfma_f32_16x16x32_bf16 v[96:99], v[170:173], v[186:189], v[96:99]
	v_mfma_f32_16x16x32_bf16 v[84:87], v[162:165], v[204:207], v[84:87]
	v_mfma_f32_16x16x32_bf16 v[80:83], v[170:173], v[204:207], v[80:83]
	v_mfma_f32_16x16x32_bf16 v[68:71], v[162:165], v[212:215], v[68:71]
	v_mfma_f32_16x16x32_bf16 v[64:67], v[170:173], v[212:215], v[64:67]
	s_setprio 0
	s_barrier
	s_add_i32 s50, s38, s26
	v_lshl_add_u64 v[190:191], s[22:23], 0, v[128:129]
	s_mov_b32 m0, s50
	v_lshl_add_u64 v[216:217], s[22:23], 0, v[130:131]
	global_load_lds_dwordx4 v[190:191], off
	s_add_i32 m0, s50, 0x2000
	s_add_u32 s50, s22, 0xb0000
	s_addc_u32 s51, s23, 0
	s_add_i32 s52, s39, s26
	global_load_lds_dwordx4 v[216:217], off
	v_lshl_add_u64 v[218:219], s[50:51], 0, v[128:129]
	s_mov_b32 m0, s52
	v_lshl_add_u64 v[220:221], s[24:25], 0, v[130:131]
	global_load_lds_dwordx4 v[218:219], off
	v_lshl_add_u64 v[218:219], s[50:51], 0, v[130:131]
	s_add_i32 m0, s52, 0x2000
	ds_read_b128 v[174:177], v196 offset:16384
	global_load_lds_dwordx4 v[218:219], off
	v_lshl_add_u64 v[218:219], s[24:25], 0, v[128:129]
	s_mov_b32 m0, s27
	ds_read_b128 v[178:181], v196 offset:17408
	global_load_lds_dwordx4 v[218:219], off
	s_mov_b32 m0, s28
	ds_read_b128 v[182:185], v196 offset:18432
	global_load_lds_dwordx4 v[220:221], off
	ds_read_b128 v[186:189], v196 offset:19456
	ds_read_b128 v[200:203], v196 offset:20480
	ds_read_b128 v[204:207], v196 offset:21504
	ds_read_b128 v[208:211], v196 offset:22528
	ds_read_b128 v[212:215], v196 offset:23552
	s_waitcnt vmcnt(8)
	s_waitcnt lgkmcnt(0)
	s_barrier
; #define PG8_STAGE(bufoff, gbase, voff) do { _Pragma("unroll") for (int _i = 0; _i < 2; ++_i) \
;         __builtin_amdgcn_global_load_lds((const unsigned*)((const char*)(gbase) + (voff)[_i]), (PG8_LAS unsigned*)(lds + (bufoff) + ldsw + _i * 8192), 16, 0, 0); } while (0)
; #define PG8_LDA(dst, b, h) do { _Pragma("unroll") for (int m = 0; m < 4; ++m) _Pragma("unroll") for (int k = 0; k < 2; ++k) dst[m][k] = *(const PG8_LAS bf16x8*)(lds + PG8_SA(b, h) + aoff + m * 2048 + k * 1024); } while (0)
; #define PG8_LDB(dst, b, h) do { _Pragma("unroll") for (int n = 0; n < 2; ++n) _Pragma("unroll") for (int k = 0; k < 2; ++k) dst[n][k] = *(const PG8_LAS bf16x8*)(lds + PG8_SB(b, h) + boff + n * 2048 + k * 1024); } while (0)
; #define PG8_MMA(ai, bj, At, Bt) do { __builtin_amdgcn_s_setprio(1); _Pragma("unroll") for (int m = 0; m < 4; ++m) _Pragma("unroll") for (int n = 0; n < 2; ++n) _Pragma("unroll") for (int k = 0; k < 2; ++k) \
;         acc[ai][bj][m][n] = __builtin_amdgcn_mfma_f32_16x16x32_bf16(Bt[n][k], At[m][k], acc[ai][bj][m][n], 0, 0, 0); __builtin_amdgcn_s_setprio(0); } while (0)
; #define PG8_WAIT_V(n) asm volatile("s_waitcnt vmcnt(" #n ")" ::: "memory")
; #define PG8_WAIT_L(n) asm volatile("s_waitcnt lgkmcnt(" #n ")" ::: "memory")
; #define PG8_BAR __builtin_amdgcn_s_barrier()
; #define PG8_SCHED __builtin_amdgcn_sched_barrier(0)
; template <class Epi, class Sched, bool ALIGN_EPI = false, bool SP2 = false>
; __device__ __forceinline__ void gemm_phase(PG8_LAS unsigned char* lds, const Gemm g, const Sched& S, const Epi& E) {
;     ...
;             PG8_WAIT_V(8); PG8_WAIT_L(0); PG8_BAR; PG8_MMA(1, 0, At, B0); PG8_MMA(1, 1, At, B1); PG8_BAR; PG8_SCHED;
;             PG8_LDB(B0, 1, 0); PG8_LDB(B1, 1, 1); PG8_SCHED; PG8_LDA(At, 1, 0); PG8_STAGE(PG8_SA(0, 1), a2 + hstep, voffA);
;             PG8_WAIT_V(8); PG8_WAIT_L(0); PG8_BAR; PG8_MMA(0, 0, At, B0); PG8_MMA(0, 1, At, B1); PG8_BAR; PG8_SCHED;
	s_setprio 1
	s_waitcnt lgkmcnt(0)
	v_mfma_f32_16x16x32_bf16 v[60:63], v[140:143], v[174:177], v[60:63]
	v_mfma_f32_16x16x32_bf16 v[56:59], v[150:153], v[174:177], v[56:59]
	v_mfma_f32_16x16x32_bf16 v[44:47], v[140:143], v[182:185], v[44:47]
	v_mfma_f32_16x16x32_bf16 v[40:43], v[150:153], v[182:185], v[40:43]
	v_mfma_f32_16x16x32_bf16 v[28:31], v[140:143], v[200:203], v[28:31]
	v_mfma_f32_16x16x32_bf16 v[24:27], v[150:153], v[200:203], v[24:27]
	v_mfma_f32_16x16x32_bf16 v[12:15], v[140:143], v[208:211], v[12:15]
	v_mfma_f32_16x16x32_bf16 v[8:11], v[150:153], v[208:211], v[8:11]
	v_mfma_f32_16x16x32_bf16 v[60:63], v[144:147], v[178:181], v[60:63]
	v_mfma_f32_16x16x32_bf16 v[56:59], v[154:157], v[178:181], v[56:59]
	v_mfma_f32_16x16x32_bf16 v[44:47], v[144:147], v[186:189], v[44:47]
	v_mfma_f32_16x16x32_bf16 v[40:43], v[154:157], v[186:189], v[40:43]
	v_mfma_f32_16x16x32_bf16 v[28:31], v[144:147], v[204:207], v[28:31]
	v_mfma_f32_16x16x32_bf16 v[24:27], v[154:157], v[204:207], v[24:27]
	v_mfma_f32_16x16x32_bf16 v[12:15], v[144:147], v[212:215], v[12:15]
	v_mfma_f32_16x16x32_bf16 v[8:11], v[154:157], v[212:215], v[8:11]
	s_setprio 0
	s_setprio 1
	v_mfma_f32_16x16x32_bf16 v[52:55], v[158:161], v[174:177], v[52:55]
	v_mfma_f32_16x16x32_bf16 v[48:51], v[166:169], v[174:177], v[48:51]
	v_mfma_f32_16x16x32_bf16 v[36:39], v[158:161], v[182:185], v[36:39]
	v_mfma_f32_16x16x32_bf16 v[32:35], v[166:169], v[182:185], v[32:35]
	v_mfma_f32_16x16x32_bf16 v[20:23], v[158:161], v[200:203], v[20:23]
	v_mfma_f32_16x16x32_bf16 v[16:19], v[166:169], v[200:203], v[16:19]
	v_mfma_f32_16x16x32_bf16 v[4:7], v[158:161], v[208:211], v[4:7]
	v_mfma_f32_16x16x32_bf16 v[0:3], v[166:169], v[208:211], v[0:3]
	v_mfma_f32_16x16x32_bf16 v[52:55], v[162:165], v[178:181], v[52:55]
	v_mfma_f32_16x16x32_bf16 v[48:51], v[170:173], v[178:181], v[48:51]
	v_mfma_f32_16x16x32_bf16 v[36:39], v[162:165], v[186:189], v[36:39]
	v_mfma_f32_16x16x32_bf16 v[32:35], v[170:173], v[186:189], v[32:35]
	v_mfma_f32_16x16x32_bf16 v[20:23], v[162:165], v[204:207], v[20:23]
	v_mfma_f32_16x16x32_bf16 v[16:19], v[170:173], v[204:207], v[16:19]
	v_mfma_f32_16x16x32_bf16 v[4:7], v[162:165], v[212:215], v[4:7]
	v_mfma_f32_16x16x32_bf16 v[0:3], v[170:173], v[212:215], v[0:3]
	s_setprio 0
	s_barrier
	s_add_i32 s50, 0, 0x18000
	s_add_i32 s51, 0, 0x1c000
	s_add_u32 s24, s24, 0xb0000
	s_addc_u32 s25, s25, 0
	s_mov_b32 m0, s29
	v_lshl_add_u64 v[222:223], s[24:25], 0, v[128:129]
	global_load_lds_dwordx4 v[222:223], off
	v_lshl_add_u64 v[222:223], s[24:25], 0, v[130:131]
	s_mov_b32 m0, s30
	v_add_u32_e32 v154, s50, v192
	global_load_lds_dwordx4 v[222:223], off
	v_add_u32_e32 v170, s51, v192
	ds_read_b128 v[140:143], v154
	ds_read_b128 v[144:147], v154 offset:1024
	ds_read_b128 v[150:153], v154 offset:2048
	ds_read_b128 v[154:157], v154 offset:3072
	ds_read_b128 v[158:161], v170
	ds_read_b128 v[162:165], v170 offset:1024
	ds_read_b128 v[166:169], v170 offset:2048
	ds_read_b128 v[170:173], v170 offset:3072
	ds_read_b128 v[174:177], v196 offset:32768
	ds_read_b128 v[178:181], v196 offset:33792
	ds_read_b128 v[182:185], v196 offset:34816
	ds_read_b128 v[186:189], v196 offset:35840
	ds_read_b128 v[200:203], v196 offset:36864
	ds_read_b128 v[204:207], v196 offset:37888
	ds_read_b128 v[208:211], v196 offset:38912
	ds_read_b128 v[212:215], v196 offset:39936
	s_waitcnt vmcnt(8)
	s_waitcnt lgkmcnt(0)
	s_barrier
	s_setprio 1
	s_waitcnt lgkmcnt(0)
	v_mfma_f32_16x16x32_bf16 v[124:127], v[140:143], v[174:177], v[124:127]
	v_mfma_f32_16x16x32_bf16 v[120:123], v[150:153], v[174:177], v[120:123]
	v_mfma_f32_16x16x32_bf16 v[108:111], v[140:143], v[182:185], v[108:111]
	v_mfma_f32_16x16x32_bf16 v[104:107], v[150:153], v[182:185], v[104:107]
	v_mfma_f32_16x16x32_bf16 v[92:95], v[140:143], v[200:203], v[92:95]
	v_mfma_f32_16x16x32_bf16 v[88:91], v[150:153], v[200:203], v[88:91]
	v_mfma_f32_16x16x32_bf16 v[76:79], v[140:143], v[208:211], v[76:79]
	v_mfma_f32_16x16x32_bf16 v[72:75], v[150:153], v[208:211], v[72:75]
	v_mfma_f32_16x16x32_bf16 v[124:127], v[144:147], v[178:181], v[124:127]
	v_mfma_f32_16x16x32_bf16 v[120:123], v[154:157], v[178:181], v[120:123]
	v_mfma_f32_16x16x32_bf16 v[108:111], v[144:147], v[186:189], v[108:111]
	v_mfma_f32_16x16x32_bf16 v[104:107], v[154:157], v[186:189], v[104:107]
	v_mfma_f32_16x16x32_bf16 v[92:95], v[144:147], v[204:207], v[92:95]
	v_mfma_f32_16x16x32_bf16 v[88:91], v[154:157], v[204:207], v[88:91]
	v_mfma_f32_16x16x32_bf16 v[76:79], v[144:147], v[212:215], v[76:79]
	v_mfma_f32_16x16x32_bf16 v[72:75], v[154:157], v[212:215], v[72:75]
	s_setprio 0
	s_setprio 1
	v_mfma_f32_16x16x32_bf16 v[116:119], v[158:161], v[174:177], v[116:119]
	v_mfma_f32_16x16x32_bf16 v[112:115], v[166:169], v[174:177], v[112:115]
	v_mfma_f32_16x16x32_bf16 v[100:103], v[158:161], v[182:185], v[100:103]
	v_mfma_f32_16x16x32_bf16 v[96:99], v[166:169], v[182:185], v[96:99]
	v_mfma_f32_16x16x32_bf16 v[84:87], v[158:161], v[200:203], v[84:87]
	v_mfma_f32_16x16x32_bf16 v[80:83], v[166:169], v[200:203], v[80:83]
	v_mfma_f32_16x16x32_bf16 v[68:71], v[158:161], v[208:211], v[68:71]
	v_mfma_f32_16x16x32_bf16 v[64:67], v[166:169], v[208:211], v[64:67]
	v_mfma_f32_16x16x32_bf16 v[116:119], v[162:165], v[178:181], v[116:119]
	v_mfma_f32_16x16x32_bf16 v[112:115], v[170:173], v[178:181], v[112:115]
	v_mfma_f32_16x16x32_bf16 v[100:103], v[162:165], v[186:189], v[100:103]
	v_mfma_f32_16x16x32_bf16 v[96:99], v[170:173], v[186:189], v[96:99]
	v_mfma_f32_16x16x32_bf16 v[84:87], v[162:165], v[204:207], v[84:87]
	v_mfma_f32_16x16x32_bf16 v[80:83], v[170:173], v[204:207], v[80:83]
	v_mfma_f32_16x16x32_bf16 v[68:71], v[162:165], v[212:215], v[68:71]
	v_mfma_f32_16x16x32_bf16 v[64:67], v[170:173], v[212:215], v[64:67]
	s_setprio 0
	s_barrier
; #define PG8_STAGE(bufoff, gbase, voff) do { _Pragma("unroll") for (int _i = 0; _i < 2; ++_i) \
;         __builtin_amdgcn_global_load_lds((const unsigned*)((const char*)(gbase) + (voff)[_i]), (PG8_LAS unsigned*)(lds + (bufoff) + ldsw + _i * 8192), 16, 0, 0); } while (0)
; #define PG8_LDA(dst, b, h) do { _Pragma("unroll") for (int m = 0; m < 4; ++m) _Pragma("unroll") for (int k = 0; k < 2; ++k) dst[m][k] = *(const PG8_LAS bf16x8*)(lds + PG8_SA(b, h) + aoff + m * 2048 + k * 1024); } while (0)
; #define PG8_MMA(ai, bj, At, Bt) do { __builtin_amdgcn_s_setprio(1); _Pragma("unroll") for (int m = 0; m < 4; ++m) _Pragma("unroll") for (int n = 0; n < 2; ++n) _Pragma("unroll") for (int k = 0; k < 2; ++k) \
;         acc[ai][bj][m][n] = __builtin_amdgcn_mfma_f32_16x16x32_bf16(Bt[n][k], At[m][k], acc[ai][bj][m][n], 0, 0, 0); __builtin_amdgcn_s_setprio(0); } while (0)
; #define PG8_WAIT_V(n) asm volatile("s_waitcnt vmcnt(" #n ")" ::: "memory")
; #define PG8_WAIT_L(n) asm volatile("s_waitcnt lgkmcnt(" #n ")" ::: "memory")
; #define PG8_BAR __builtin_amdgcn_s_barrier()
; #define PG8_SCHED __builtin_amdgcn_sched_barrier(0)
; template <class Epi, class Sched, bool ALIGN_EPI = false, bool SP2 = false>
; __device__ __forceinline__ void gemm_phase(PG8_LAS unsigned char* lds, const Gemm g, const Sched& S, const Epi& E) {
;     ...
;             PG8_LDA(At, 1, 1); PG8_STAGE(PG8_SB(1, 0), b3, voffB); PG8_STAGE(PG8_SB(1, 1), b3 + hstep, voffB); PG8_STAGE(PG8_SA(1, 0), a3, voffA);
;             PG8_WAIT_V(8); PG8_WAIT_L(0); PG8_BAR; PG8_MMA(1, 0, At, B0); PG8_MMA(1, 1, At, B1); PG8_BAR; PG8_SCHED;
;     ...
;         if constexpr (ALIGN_EPI) { if (wr == 0) PG8_BAR; }
;         if constexpr (!Epi::AFTER_DRAIN) { E(acc, cur, wr, wc, fr, fq); S.done(cur); }
;         if (!has_next) break;
	s_add_i32 s24, s50, s26
	v_lshl_add_u64 v[190:191], v[190:191], 0, s[14:15]
	s_mov_b32 m0, s24
	ds_read_b128 v[174:177], v196 offset:49152
	global_load_lds_dwordx4 v[190:191], off
	s_add_i32 m0, s24, 0x2000
	s_add_u32 s22, s22, 0xb0080
	v_lshl_add_u64 v[190:191], v[216:217], 0, s[14:15]
	s_addc_u32 s23, s23, 0
	s_add_i32 s24, s51, s26
	global_load_lds_dwordx4 v[190:191], off
	v_lshl_add_u64 v[190:191], s[22:23], 0, v[128:129]
	s_mov_b32 m0, s24
	ds_read_b128 v[178:181], v196 offset:50176
	global_load_lds_dwordx4 v[190:191], off
	v_lshl_add_u64 v[190:191], s[22:23], 0, v[130:131]
	s_add_i32 m0, s24, 0x2000
	ds_read_b128 v[182:185], v196 offset:51200
	global_load_lds_dwordx4 v[190:191], off
	v_lshl_add_u64 v[190:191], v[218:219], 0, s[14:15]
	s_mov_b32 m0, s34
	ds_read_b128 v[186:189], v196 offset:52224
	global_load_lds_dwordx4 v[190:191], off
	v_lshl_add_u64 v[190:191], v[220:221], 0, s[14:15]
	s_mov_b32 m0, s35
	ds_read_b128 v[200:203], v196 offset:53248
	global_load_lds_dwordx4 v[190:191], off
	ds_read_b128 v[204:207], v196 offset:54272
	ds_read_b128 v[208:211], v196 offset:55296
	ds_read_b128 v[212:215], v196 offset:56320
	s_waitcnt vmcnt(8)
	s_waitcnt lgkmcnt(0)
	s_barrier
	s_setprio 1
	s_waitcnt lgkmcnt(0)
	v_mfma_f32_16x16x32_bf16 v[60:63], v[140:143], v[174:177], v[60:63]
	v_mfma_f32_16x16x32_bf16 v[56:59], v[150:153], v[174:177], v[56:59]
	v_mfma_f32_16x16x32_bf16 v[44:47], v[140:143], v[182:185], v[44:47]
	v_mfma_f32_16x16x32_bf16 v[40:43], v[150:153], v[182:185], v[40:43]
	v_mfma_f32_16x16x32_bf16 v[28:31], v[140:143], v[200:203], v[28:31]
	v_mfma_f32_16x16x32_bf16 v[24:27], v[150:153], v[200:203], v[24:27]
	v_mfma_f32_16x16x32_bf16 v[12:15], v[140:143], v[208:211], v[12:15]
	v_mfma_f32_16x16x32_bf16 v[8:11], v[150:153], v[208:211], v[8:11]
	v_mfma_f32_16x16x32_bf16 v[60:63], v[144:147], v[178:181], v[60:63]
	v_mfma_f32_16x16x32_bf16 v[56:59], v[154:157], v[178:181], v[56:59]
	v_mfma_f32_16x16x32_bf16 v[44:47], v[144:147], v[186:189], v[44:47]
	v_mfma_f32_16x16x32_bf16 v[40:43], v[154:157], v[186:189], v[40:43]
	v_mfma_f32_16x16x32_bf16 v[28:31], v[144:147], v[204:207], v[28:31]
	v_mfma_f32_16x16x32_bf16 v[24:27], v[154:157], v[204:207], v[24:27]
	v_mfma_f32_16x16x32_bf16 v[12:15], v[144:147], v[212:215], v[12:15]
	v_mfma_f32_16x16x32_bf16 v[8:11], v[154:157], v[212:215], v[8:11]
	s_setprio 0
	s_setprio 1
	v_mfma_f32_16x16x32_bf16 v[52:55], v[158:161], v[174:177], v[52:55]
	v_mfma_f32_16x16x32_bf16 v[48:51], v[166:169], v[174:177], v[48:51]
	v_mfma_f32_16x16x32_bf16 v[36:39], v[158:161], v[182:185], v[36:39]
	v_mfma_f32_16x16x32_bf16 v[32:35], v[166:169], v[182:185], v[32:35]
	v_mfma_f32_16x16x32_bf16 v[20:23], v[158:161], v[200:203], v[20:23]
	v_mfma_f32_16x16x32_bf16 v[16:19], v[166:169], v[200:203], v[16:19]
	v_mfma_f32_16x16x32_bf16 v[4:7], v[158:161], v[208:211], v[4:7]
	v_mfma_f32_16x16x32_bf16 v[0:3], v[166:169], v[208:211], v[0:3]
	v_mfma_f32_16x16x32_bf16 v[52:55], v[162:165], v[178:181], v[52:55]
	v_mfma_f32_16x16x32_bf16 v[48:51], v[170:173], v[178:181], v[48:51]
	v_mfma_f32_16x16x32_bf16 v[36:39], v[162:165], v[186:189], v[36:39]
	v_mfma_f32_16x16x32_bf16 v[32:35], v[170:173], v[186:189], v[32:35]
	v_mfma_f32_16x16x32_bf16 v[20:23], v[162:165], v[204:207], v[20:23]
	v_mfma_f32_16x16x32_bf16 v[16:19], v[170:173], v[204:207], v[16:19]
	v_mfma_f32_16x16x32_bf16 v[4:7], v[162:165], v[212:215], v[4:7]
	v_mfma_f32_16x16x32_bf16 v[0:3], v[170:173], v[212:215], v[0:3]
	s_setprio 0
	s_barrier
	s_add_i32 s47, s47, 2
	s_add_u32 s20, s20, 0x100
	s_addc_u32 s21, s21, 0
	s_add_u32 s45, s45, 0x100
	s_addc_u32 s46, s46, 0
	s_cmp_gt_u32 s47, 41
	s_cbranch_scc0 .LBB0_1751
	s_nop 0
	s_nop 0
	s_nop 0
	s_nop 0
	s_nop 0
	s_nop 0
	s_nop 0
	s_nop 0
	s_nop 0
	s_and_b64 vcc, exec, s[16:17]
	s_cbranch_vccz .LBB0_1754
	s_barrier
